# leftover hazard s_nops of removed division sequences deleted; acc zeroing via v_mov_b64; fewer lgkmcnt waits in phase A k-loop; attention mask via bfe+bfi
# speedup vs baseline: 1.0645x; 1.0150x over previous
; DI void gemm_tile(const bf16_t* __restrict__ A, int lda, const bf16_t* __restrict__ Bt, int ldb, int bvalid, int K, f32x4 (&acc)[4][4], char* lds, bool preloaded = false) {
;   const int tid = tidx(), lane = tid & 63, wave = __builtin_amdgcn_readfirstlane(tid >> 6);
;   const int wm = wave >> 1, wn = wave & 1;
;   const int lr = tid >> 3, lc = tid & 7;
;   const int fr = lane & 15, fq = lane >> 4;
;   const int fx = (fr >> 1) & 7;
;   const bf16_t* ap = A + (size_t)lr * lda + ((lc ^ ((lr >> 1) & 7)) << 3);
;   const bf16_t* bp = Bt + ((lc ^ ((lr >> 1) & 7)) << 3);
;   typedef __attribute__((address_space(1))) const unsigned gptr_t;
;   typedef __attribute__((address_space(3))) unsigned lptr_t;
;   const unsigned lbase = (unsigned)(size_t)lds + (unsigned)tid * 16u;
;     ...
;   auto compute = [&](int st) {
;     const char* base = lds + st * 32768;
;     bf16x8 af[2][4], bfr[2][4];
; #pragma unroll
;     for (int s = 0; s < 2; ++s) {
;       const int ch = ((4 * s + fq) ^ fx) << 4;
; #pragma unroll
;       for (int mi = 0; mi < 4; ++mi) af[s][mi] = *(const bf16x8*)(base + (wm * 64 + mi * 16 + fr) * 128 + ch);
; #pragma unroll
;       for (int ni = 0; ni < 4; ++ni) bfr[s][ni] = *(const bf16x8*)(base + 16384 + (wn * 64 + ni * 16 + fr) * 128 + ch);
;     }
;     __builtin_amdgcn_s_setprio(1);
; #pragma unroll
;     for (int s = 0; s < 2; ++s)
; #pragma unroll
;       for (int mi = 0; mi < 4; ++mi)
; #pragma unroll
; DI void phaseD_tile(const P& p, int layer, int mt, int nt, char* lds) {
;   const int lane = tidx() & 63, wave = __builtin_amdgcn_readfirstlane(tidx() >> 6);
;   const int row0 = mt * 128, col0 = nt * 128;
;   const int wm = wave >> 1, wn = wave & 1, fr = lane & 15, fq = lane >> 4;
;   f32x4 acc[4][4];
;   zero_acc(acc);
;   const size_t goff = ((size_t)((mt * 2 + wm) * 16 + nt * 2 + wn) * 64 + lane) * 16;
;   const unsigned* GP = (const unsigned*)(p.ws + W_GP) + goff;
;   const unsigned* GA = (const unsigned*)(p.ws + W_GA) + goff;
;   u32x4 gpv[4], gav[4];
; #pragma unroll
;   for (int mi = 0; mi < 4; ++mi) { gpv[mi] = __builtin_nontemporal_load((const u32x4*)(GP + mi * 4)); gav[mi] = __builtin_nontemporal_load((const u32x4*)(GA + mi * 4)); }
;   gemm_tile((const bf16_t*)(p.ws + W_POOLED) + (size_t)row0 * 512, 512, (const bf16_t*)(p.ws + W_WPO) + ((size_t)layer * 1024 + col0) * 512, 512, 128, 512, acc, lds);
.LBB0_277:
	v_mov_b32_e32 v99, v158
	v_mov_b32_e32 v2, v158
	s_lshl_b32 s8, s6, 1
	v_readfirstlane_b32 s5, v2
	s_ashr_i32 s19, s5, 7
	s_bfe_u32 s20, s5, 0x10006
	s_lshl_b32 s5, s7, 5
	s_lshl_b32 s4, s7, 7
	s_lshl_b32 s7, s19, 4
	s_add_i32 s5, s8, s5
	s_add_i32 s5, s5, s7
	s_or_b32 s8, s5, s20
	s_ashr_i32 s9, s8, 31
	v_and_b32_e32 v0, 63, v99
	s_lshl_b64 s[8:9], s[8:9], 12
	v_lshl_or_b32 v2, v0, 6, s8
	v_mov_b32_e32 v3, s9
	v_readlane_b32 s8, v240, 41
	v_readlane_b32 s9, v240, 42
	s_ashr_i32 s5, s4, 31
	s_lshl_b32 s6, s6, 7
	v_lshl_add_u64 v[6:7], s[8:9], 0, v[2:3]
	v_readlane_b32 s8, v240, 43
	v_readlane_b32 s9, v240, 44
	v_mov_b32_e32 v30, v158
	v_readlane_b32 s22, v240, 35
	v_lshl_add_u64 v[10:11], s[8:9], 0, v[2:3]
	s_lshl_b64 s[8:9], s[4:5], 10
	s_add_u32 s10, s74, s8
	s_addc_u32 s11, s75, s9
	s_ashr_i32 s7, s6, 31
	s_lshl_b64 s[12:13], s[6:7], 9
	s_add_u32 s12, s12, s94
	global_load_dwordx4 v[2:5], v[6:7], off offset:48 nt
	global_load_dwordx4 v[14:17], v[6:7], off offset:32 nt
	global_load_dwordx4 v[54:57], v[6:7], off offset:16 nt
	global_load_dwordx4 v[38:41], v[6:7], off nt
	s_nop 0
	global_load_dwordx4 v[6:9], v[10:11], off offset:48 nt
	global_load_dwordx4 v[18:21], v[10:11], off offset:32 nt
	global_load_dwordx4 v[58:61], v[10:11], off offset:16 nt
	global_load_dwordx4 v[46:49], v[10:11], off nt
	s_addc_u32 s13, s13, s95
	s_lshl_b64 s[12:13], s[12:13], 1
	v_ashrrev_i32_e32 v12, 3, v30
	v_lshrrev_b32_e32 v0, 4, v30
	v_ashrrev_i32_e32 v13, 31, v12
	v_xor_b32_e32 v0, v0, v30
	v_readlane_b32 s23, v240, 36
	s_add_u32 s22, s22, s12
	v_lshlrev_b64 v[10:11], 10, v[12:13]
	v_lshlrev_b32_e32 v0, 4, v0
	s_addc_u32 s23, s23, s13
	v_lshl_add_u64 v[10:11], s[10:11], 0, v[10:11]
	v_and_b32_e32 v0, 0x70, v0
	v_lshlrev_b32_e32 v35, 9, v12
	v_lshl_add_u64 v[10:11], v[10:11], 0, v[0:1]
	v_lshl_add_u64 v[26:27], s[22:23], 0, v[0:1]
	v_and_b32_e32 v0, 0xfe00, v35
	v_lshlrev_b32_e32 v34, 4, v30
	v_lshlrev_b32_e32 v0, 1, v0
	v_add_u32_e32 v22, 0x4000, v34
	v_readfirstlane_b32 s5, v34
	v_lshl_add_u64 v[12:13], v[26:27], 0, v[0:1]
	v_add_u32_e32 v0, 0x1000, v34
	s_mov_b32 m0, s5
	v_readfirstlane_b32 s10, v22
	v_readfirstlane_b32 s11, v0
	v_add_u32_e32 v0, 0x4000, v35
	global_load_lds_dwordx4 v[10:11], off
	s_mov_b32 m0, s10
	s_mov_b64 s[40:41], 0x8000
	v_and_b32_e32 v0, 0xfe00, v0
	global_load_lds_dwordx4 v[12:13], off
	v_lshl_add_u64 v[22:23], v[10:11], 0, s[40:41]
	s_mov_b32 m0, s11
	v_lshlrev_b32_e32 v0, 1, v0
	global_load_lds_dwordx4 v[22:23], off
	v_lshl_add_u64 v[22:23], v[26:27], 0, v[0:1]
	v_add_u32_e32 v0, 0x5000, v34
	s_mov_b32 s33, 0x8000
	v_readfirstlane_b32 s21, v0
	v_add_u32_e32 v0, 0x2000, v34
	s_mov_b32 m0, s21
	s_mov_b64 s[42:43], 0x10000
	v_readfirstlane_b32 s22, v0
	v_bitop3_b32 v0, v35, s33, v167 bitop3:0x6c
	global_load_lds_dwordx4 v[22:23], off
	v_lshl_add_u64 v[24:25], v[10:11], 0, s[42:43]
	s_mov_b32 m0, s22
	v_lshlrev_b32_e32 v0, 1, v0
	global_load_lds_dwordx4 v[24:25], off
	v_lshl_add_u64 v[24:25], v[26:27], 0, v[0:1]
	v_add_u32_e32 v0, 0x6000, v34
	v_readfirstlane_b32 s26, v30
	v_readfirstlane_b32 s23, v0
	v_add_u32_e32 v0, 0x3000, v34
	s_lshl_b32 s27, s26, 7
	v_readfirstlane_b32 s24, v0
	v_add_u32_e32 v0, 0xc000, v35
	v_and_b32_e32 v0, 0xfe00, v0
	v_lshlrev_b32_e32 v0, 1, v0
	v_lshl_add_u64 v[26:27], v[26:27], 0, v[0:1]
	v_add_u32_e32 v0, 0x7000, v34
	s_lshl_b32 s26, s26, 6
	v_readfirstlane_b32 s25, v0
	v_lshlrev_b32_e32 v0, 7, v30
	v_bfe_u32 v31, v30, 4, 2
	v_bfe_u32 v33, v30, 1, 3
	s_mov_b32 m0, s23
	s_mov_b64 s[50:51], 0x18000
	s_and_b32 s27, s27, 0x2000
	v_and_b32_e32 v0, 0x780, v0
	s_and_b32 s26, s26, 0xffffe000
	v_lshrrev_b32_e32 v32, 1, v30
	global_load_lds_dwordx4 v[24:25], off
	v_lshl_add_u64 v[28:29], v[10:11], 0, s[50:51]
	s_mov_b32 m0, s24
	v_or_b32_e32 v30, s27, v0
	v_or_b32_e32 v37, s26, v0
	v_bitop3_b32 v0, v31, v33, 4 bitop3:0x36
	global_load_lds_dwordx4 v[28:29], off
	v_bitop3_b32 v28, v32, v31, 7 bitop3:0x6c
	v_lshlrev_b32_e32 v31, 4, v0
	v_add_u32_e32 v0, 0x8000, v34
	s_mov_b32 m0, s25
	s_mov_b64 s[38:39], 0x80
	v_add_u32_e32 v32, 0xc000, v34
	v_readfirstlane_b32 s29, v0
	global_load_lds_dwordx4 v[26:27], off
	v_lshlrev_b32_e32 v36, 4, v28
	v_lshl_add_u64 v[28:29], v[10:11], 0, s[38:39]
	s_mov_b32 m0, s29
	v_readfirstlane_b32 s26, v32
	v_add_u32_e32 v0, 0x9000, v34
	s_waitcnt vmcnt(0) lgkmcnt(0)
	s_barrier
; #define MFMA16(a, b, c) __builtin_amdgcn_mfma_f32_16x16x32_bf16((a), (b), (c), 0, 0, 0)
; DI void gemm_tile(const bf16_t* __restrict__ A, int lda, const bf16_t* __restrict__ Bt, int ldb, int bvalid, int K, f32x4 (&acc)[4][4], char* lds, bool preloaded = false) {
;     ...
;   auto compute = [&](int st) {
;     const char* base = lds + st * 32768;
;     bf16x8 af[2][4], bfr[2][4];
; #pragma unroll
;     for (int s = 0; s < 2; ++s) {
;       const int ch = ((4 * s + fq) ^ fx) << 4;
; #pragma unroll
;       for (int mi = 0; mi < 4; ++mi) af[s][mi] = *(const bf16x8*)(base + (wm * 64 + mi * 16 + fr) * 128 + ch);
; #pragma unroll
;       for (int ni = 0; ni < 4; ++ni) bfr[s][ni] = *(const bf16x8*)(base + 16384 + (wn * 64 + ni * 16 + fr) * 128 + ch);
;     }
;     __builtin_amdgcn_s_setprio(1);
; #pragma unroll
;     for (int s = 0; s < 2; ++s)
; #pragma unroll
;       for (int mi = 0; mi < 4; ++mi)
; #pragma unroll
;         for (int ni = 0; ni < 4; ++ni) acc[mi][ni] = MFMA16(af[s][mi], bfr[s][ni], acc[mi][ni]);
;     __builtin_amdgcn_s_setprio(0);
;   };
;   const int nk = K >> 6;
;   if (!preloaded) { GLDS(0, 0) }
;   __syncthreads();
;   for (int kt = 0; kt < nk; ++kt) {
;     if (kt + 1 < nk) { GLDS((kt + 1) & 1, (kt + 1) << 6) }
;     compute(kt & 1);
;     __syncthreads();
;   }
	global_load_lds_dwordx4 v[28:29], off
	v_lshl_add_u64 v[28:29], v[12:13], 0, s[38:39]
	s_mov_b32 m0, s26
	s_mov_b64 s[58:59], 0x8080
	v_readfirstlane_b32 s27, v0
	v_add_u32_e32 v0, 0xd000, v34
	global_load_lds_dwordx4 v[28:29], off
	v_lshl_add_u64 v[28:29], v[10:11], 0, s[58:59]
	s_mov_b32 m0, s27
	v_readfirstlane_b32 s28, v0
	v_add_u32_e32 v0, 0xa000, v34
	global_load_lds_dwordx4 v[28:29], off
	v_lshl_add_u64 v[28:29], v[22:23], 0, s[38:39]
	s_mov_b32 m0, s28
	s_mov_b64 s[62:63], 0x10080
	v_readfirstlane_b32 s30, v0
	v_add_u32_e32 v0, 0xe000, v34
	global_load_lds_dwordx4 v[28:29], off
	v_lshl_add_u64 v[28:29], v[10:11], 0, s[62:63]
	s_mov_b32 m0, s30
	v_readfirstlane_b32 s31, v0
	v_add_u32_e32 v0, 0xb000, v34
	global_load_lds_dwordx4 v[28:29], off
	v_lshl_add_u64 v[28:29], v[24:25], 0, s[38:39]
	s_mov_b32 m0, s31
	s_mov_b64 s[68:69], 0x18080
	v_readfirstlane_b32 s34, v0
	v_add_u32_e32 v0, 0xf000, v34
	global_load_lds_dwordx4 v[28:29], off
	v_lshl_add_u64 v[28:29], v[10:11], 0, s[68:69]
	s_mov_b32 m0, s34
	v_readfirstlane_b32 s35, v0
	global_load_lds_dwordx4 v[28:29], off
	v_lshl_add_u64 v[28:29], v[26:27], 0, s[38:39]
	s_mov_b32 m0, s35
	v_or_b32_e32 v0, v36, v37
	global_load_lds_dwordx4 v[28:29], off
	v_or_b32_e32 v28, v36, v30
	v_or_b32_e32 v29, v31, v37
	v_or_b32_e32 v30, v31, v30
	ds_read_b128 v[32:35], v0
	ds_read_b128 v[42:45], v0 offset:2048
	ds_read_b128 v[50:53], v0 offset:4096
	ds_read_b128 v[62:65], v0 offset:6144
	ds_read_b128 v[66:69], v28 offset:16384
	ds_read_b128 v[70:73], v28 offset:18432
	ds_read_b128 v[74:77], v28 offset:20480
	ds_read_b128 v[78:81], v28 offset:22528
	ds_read_b128 v[82:85], v29
	ds_read_b128 v[86:89], v29 offset:2048
	ds_read_b128 v[90:93], v29 offset:4096
	ds_read_b128 v[94:97], v29 offset:6144
	ds_read_b128 v[100:103], v30 offset:16384
	ds_read_b128 v[104:107], v30 offset:18432
	ds_read_b128 v[108:111], v30 offset:20480
	ds_read_b128 v[112:115], v30 offset:22528
	v_and_b32_e32 v98, 15, v99
	s_setprio 1
	s_waitcnt lgkmcnt(0)
	v_mfma_f32_16x16x32_bf16 v[116:119], v[32:35], v[66:69], 0
	v_mfma_f32_16x16x32_bf16 v[120:123], v[32:35], v[70:73], 0
	v_mfma_f32_16x16x32_bf16 v[124:127], v[32:35], v[74:77], 0
	v_mfma_f32_16x16x32_bf16 v[32:35], v[32:35], v[78:81], 0
	v_mfma_f32_16x16x32_bf16 v[128:131], v[42:45], v[66:69], 0
	v_mfma_f32_16x16x32_bf16 v[132:135], v[42:45], v[70:73], 0
	v_mfma_f32_16x16x32_bf16 v[136:139], v[42:45], v[74:77], 0
	v_mfma_f32_16x16x32_bf16 v[42:45], v[42:45], v[78:81], 0
	v_mfma_f32_16x16x32_bf16 v[140:143], v[50:53], v[66:69], 0
	v_mfma_f32_16x16x32_bf16 v[144:147], v[50:53], v[70:73], 0
	v_mfma_f32_16x16x32_bf16 v[148:151], v[50:53], v[74:77], 0
	v_mfma_f32_16x16x32_bf16 v[50:53], v[50:53], v[78:81], 0
	v_mfma_f32_16x16x32_bf16 v[66:69], v[62:65], v[66:69], 0
	v_mfma_f32_16x16x32_bf16 v[70:73], v[62:65], v[70:73], 0
	v_mfma_f32_16x16x32_bf16 v[74:77], v[62:65], v[74:77], 0
	v_mfma_f32_16x16x32_bf16 v[62:65], v[62:65], v[78:81], 0
	v_mfma_f32_16x16x32_bf16 v[78:81], v[82:85], v[100:103], v[116:119]
	v_mfma_f32_16x16x32_bf16 v[116:119], v[82:85], v[104:107], v[120:123]
	v_mfma_f32_16x16x32_bf16 v[120:123], v[82:85], v[108:111], v[124:127]
	v_mfma_f32_16x16x32_bf16 v[32:35], v[82:85], v[112:115], v[32:35]
	v_mfma_f32_16x16x32_bf16 v[82:85], v[86:89], v[100:103], v[128:131]
	v_mfma_f32_16x16x32_bf16 v[124:127], v[86:89], v[104:107], v[132:135]
	v_mfma_f32_16x16x32_bf16 v[128:131], v[86:89], v[108:111], v[136:139]
	v_mfma_f32_16x16x32_bf16 v[42:45], v[86:89], v[112:115], v[42:45]
	v_mfma_f32_16x16x32_bf16 v[86:89], v[90:93], v[100:103], v[140:143]
	v_mfma_f32_16x16x32_bf16 v[132:135], v[90:93], v[104:107], v[144:147]
	v_mfma_f32_16x16x32_bf16 v[136:139], v[90:93], v[108:111], v[148:151]
	v_mfma_f32_16x16x32_bf16 v[50:53], v[90:93], v[112:115], v[50:53]
	v_mfma_f32_16x16x32_bf16 v[66:69], v[94:97], v[100:103], v[66:69]
	v_mfma_f32_16x16x32_bf16 v[70:73], v[94:97], v[104:107], v[70:73]
	v_mfma_f32_16x16x32_bf16 v[74:77], v[94:97], v[108:111], v[74:77]
	v_mfma_f32_16x16x32_bf16 v[62:65], v[94:97], v[112:115], v[62:65]
	s_setprio 0
	s_mov_b64 s[36:37], 0x100
	s_mov_b32 m0, s5
	v_lshl_add_u64 v[36:37], v[10:11], 0, s[36:37]
	s_waitcnt vmcnt(0)
	s_barrier
	global_load_lds_dwordx4 v[36:37], off
	v_lshl_add_u64 v[36:37], v[12:13], 0, s[36:37]
	s_mov_b32 m0, s10
	s_mov_b64 s[70:71], 0x8100
	global_load_lds_dwordx4 v[36:37], off
	v_lshl_add_u64 v[36:37], v[10:11], 0, s[70:71]
	s_mov_b32 m0, s11
	s_mov_b64 s[92:93], 0x10100
	global_load_lds_dwordx4 v[36:37], off
	v_lshl_add_u64 v[36:37], v[22:23], 0, s[36:37]
	s_mov_b32 m0, s21
	s_mov_b64 s[0:1], 0x18100
	global_load_lds_dwordx4 v[36:37], off
	v_lshl_add_u64 v[36:37], v[10:11], 0, s[92:93]
	s_mov_b32 m0, s22
	s_nop 0
	global_load_lds_dwordx4 v[36:37], off
	v_lshl_add_u64 v[36:37], v[24:25], 0, s[36:37]
	s_mov_b32 m0, s23
	s_nop 0
	global_load_lds_dwordx4 v[36:37], off
	v_lshl_add_u64 v[36:37], v[10:11], 0, s[0:1]
	s_mov_b32 m0, s24
	s_nop 0
	global_load_lds_dwordx4 v[36:37], off
	v_lshl_add_u64 v[36:37], v[26:27], 0, s[36:37]
	s_mov_b32 m0, s25
	s_nop 0
	global_load_lds_dwordx4 v[36:37], off
	ds_read_b128 v[90:93], v0 offset:32768
	ds_read_b128 v[94:97], v0 offset:34816
	ds_read_b128 v[100:103], v0 offset:36864
	ds_read_b128 v[104:107], v0 offset:38912
	ds_read_b128 v[108:111], v28 offset:49152
	ds_read_b128 v[112:115], v28 offset:51200
	ds_read_b128 v[140:143], v28 offset:53248
	ds_read_b128 v[144:147], v28 offset:55296
	ds_read_b128 v[148:151], v29 offset:32768
	ds_read_b128 v[152:155], v29 offset:34816
	ds_read_b128 v[180:183], v29 offset:36864
	ds_read_b128 v[184:187], v29 offset:38912
	ds_read_b128 v[188:191], v30 offset:49152
	ds_read_b128 v[192:195], v30 offset:51200
	ds_read_b128 v[196:199], v30 offset:53248
	ds_read_b128 v[200:203], v30 offset:55296
	s_setprio 1
	s_waitcnt lgkmcnt(0)
; #define MFMA16(a, b, c) __builtin_amdgcn_mfma_f32_16x16x32_bf16((a), (b), (c), 0, 0, 0)
; DI void gemm_tile(const bf16_t* __restrict__ A, int lda, const bf16_t* __restrict__ Bt, int ldb, int bvalid, int K, f32x4 (&acc)[4][4], char* lds, bool preloaded = false) {
;     ...
;   auto compute = [&](int st) {
;     const char* base = lds + st * 32768;
;     bf16x8 af[2][4], bfr[2][4];
; #pragma unroll
;     for (int s = 0; s < 2; ++s) {
;       const int ch = ((4 * s + fq) ^ fx) << 4;
; #pragma unroll
;       for (int mi = 0; mi < 4; ++mi) af[s][mi] = *(const bf16x8*)(base + (wm * 64 + mi * 16 + fr) * 128 + ch);
; #pragma unroll
;       for (int ni = 0; ni < 4; ++ni) bfr[s][ni] = *(const bf16x8*)(base + 16384 + (wn * 64 + ni * 16 + fr) * 128 + ch);
;     }
;     __builtin_amdgcn_s_setprio(1);
; #pragma unroll
;     for (int s = 0; s < 2; ++s)
; #pragma unroll
;       for (int mi = 0; mi < 4; ++mi)
; #pragma unroll
;         for (int ni = 0; ni < 4; ++ni) acc[mi][ni] = MFMA16(af[s][mi], bfr[s][ni], acc[mi][ni]);
;     __builtin_amdgcn_s_setprio(0);
;   };
;   const int nk = K >> 6;
;   if (!preloaded) { GLDS(0, 0) }
;   __syncthreads();
;   for (int kt = 0; kt < nk; ++kt) {
;     if (kt + 1 < nk) { GLDS((kt + 1) & 1, (kt + 1) << 6) }
;     compute(kt & 1);
;     __syncthreads();
	v_mfma_f32_16x16x32_bf16 v[78:81], v[90:93], v[108:111], v[78:81]
	v_mfma_f32_16x16x32_bf16 v[116:119], v[90:93], v[112:115], v[116:119]
	v_mfma_f32_16x16x32_bf16 v[120:123], v[90:93], v[140:143], v[120:123]
	v_mfma_f32_16x16x32_bf16 v[32:35], v[90:93], v[144:147], v[32:35]
	v_mfma_f32_16x16x32_bf16 v[82:85], v[94:97], v[108:111], v[82:85]
	v_mfma_f32_16x16x32_bf16 v[90:93], v[94:97], v[112:115], v[124:127]
	v_mfma_f32_16x16x32_bf16 v[124:127], v[94:97], v[140:143], v[128:131]
	v_mfma_f32_16x16x32_bf16 v[42:45], v[94:97], v[144:147], v[42:45]
	v_mfma_f32_16x16x32_bf16 v[86:89], v[100:103], v[108:111], v[86:89]
	v_mfma_f32_16x16x32_bf16 v[94:97], v[100:103], v[112:115], v[132:135]
	v_mfma_f32_16x16x32_bf16 v[128:131], v[100:103], v[140:143], v[136:139]
	v_mfma_f32_16x16x32_bf16 v[50:53], v[100:103], v[144:147], v[50:53]
	v_mfma_f32_16x16x32_bf16 v[66:69], v[104:107], v[108:111], v[66:69]
	v_mfma_f32_16x16x32_bf16 v[70:73], v[104:107], v[112:115], v[70:73]
	v_mfma_f32_16x16x32_bf16 v[74:77], v[104:107], v[140:143], v[74:77]
	v_mfma_f32_16x16x32_bf16 v[62:65], v[104:107], v[144:147], v[62:65]
	v_mfma_f32_16x16x32_bf16 v[78:81], v[148:151], v[188:191], v[78:81]
	v_mfma_f32_16x16x32_bf16 v[100:103], v[148:151], v[192:195], v[116:119]
	v_mfma_f32_16x16x32_bf16 v[104:107], v[148:151], v[196:199], v[120:123]
	v_mfma_f32_16x16x32_bf16 v[32:35], v[148:151], v[200:203], v[32:35]
	v_mfma_f32_16x16x32_bf16 v[82:85], v[152:155], v[188:191], v[82:85]
	v_mfma_f32_16x16x32_bf16 v[90:93], v[152:155], v[192:195], v[90:93]
	v_mfma_f32_16x16x32_bf16 v[108:111], v[152:155], v[196:199], v[124:127]
	v_mfma_f32_16x16x32_bf16 v[42:45], v[152:155], v[200:203], v[42:45]
	v_mfma_f32_16x16x32_bf16 v[86:89], v[180:183], v[188:191], v[86:89]
	v_mfma_f32_16x16x32_bf16 v[94:97], v[180:183], v[192:195], v[94:97]
	v_mfma_f32_16x16x32_bf16 v[112:115], v[180:183], v[196:199], v[128:131]
	v_mfma_f32_16x16x32_bf16 v[50:53], v[180:183], v[200:203], v[50:53]
	v_mfma_f32_16x16x32_bf16 v[66:69], v[184:187], v[188:191], v[66:69]
	v_mfma_f32_16x16x32_bf16 v[70:73], v[184:187], v[192:195], v[70:73]
	v_mfma_f32_16x16x32_bf16 v[74:77], v[184:187], v[196:199], v[74:77]
	v_mfma_f32_16x16x32_bf16 v[62:65], v[184:187], v[200:203], v[62:65]
	s_setprio 0
	s_mov_b64 s[0:1], 0x180
	s_mov_b32 m0, s29
	v_lshl_add_u64 v[36:37], v[10:11], 0, s[0:1]
	s_waitcnt vmcnt(0)
	s_barrier
	global_load_lds_dwordx4 v[36:37], off
	v_lshl_add_u64 v[36:37], v[12:13], 0, s[0:1]
	s_mov_b32 m0, s26
	s_mov_b64 s[2:3], 0x8180
	global_load_lds_dwordx4 v[36:37], off
	v_lshl_add_u64 v[36:37], v[10:11], 0, s[2:3]
	s_mov_b32 m0, s27
	s_mov_b64 s[2:3], 0x10180
	global_load_lds_dwordx4 v[36:37], off
	v_lshl_add_u64 v[36:37], v[22:23], 0, s[0:1]
	s_mov_b32 m0, s28
	s_nop 0
	global_load_lds_dwordx4 v[36:37], off
	v_lshl_add_u64 v[36:37], v[10:11], 0, s[2:3]
	s_mov_b32 m0, s30
	s_mov_b64 s[2:3], 0x18180
	global_load_lds_dwordx4 v[36:37], off
	v_lshl_add_u64 v[36:37], v[24:25], 0, s[0:1]
	s_mov_b32 m0, s31
	s_nop 0
	global_load_lds_dwordx4 v[36:37], off
	v_lshl_add_u64 v[36:37], v[10:11], 0, s[2:3]
	s_mov_b32 m0, s34
	s_nop 0
	global_load_lds_dwordx4 v[36:37], off
	v_lshl_add_u64 v[36:37], v[26:27], 0, s[0:1]
	s_mov_b32 m0, s35
	s_nop 0
	global_load_lds_dwordx4 v[36:37], off
	ds_read_b128 v[116:119], v0
	ds_read_b128 v[120:123], v0 offset:2048
	ds_read_b128 v[124:127], v0 offset:4096
	ds_read_b128 v[128:131], v0 offset:6144
	ds_read_b128 v[132:135], v28 offset:16384
	ds_read_b128 v[136:139], v28 offset:18432
	ds_read_b128 v[140:143], v28 offset:20480
	ds_read_b128 v[144:147], v28 offset:22528
	ds_read_b128 v[148:151], v29
	ds_read_b128 v[152:155], v29 offset:2048
	ds_read_b128 v[180:183], v29 offset:4096
	ds_read_b128 v[184:187], v29 offset:6144
	ds_read_b128 v[188:191], v30 offset:16384
	ds_read_b128 v[192:195], v30 offset:18432
	ds_read_b128 v[196:199], v30 offset:20480
	ds_read_b128 v[200:203], v30 offset:22528
	s_setprio 1
	s_waitcnt lgkmcnt(0)
	v_mfma_f32_16x16x32_bf16 v[78:81], v[116:119], v[132:135], v[78:81]
	v_mfma_f32_16x16x32_bf16 v[100:103], v[116:119], v[136:139], v[100:103]
	v_mfma_f32_16x16x32_bf16 v[104:107], v[116:119], v[140:143], v[104:107]
	v_mfma_f32_16x16x32_bf16 v[32:35], v[116:119], v[144:147], v[32:35]
	v_mfma_f32_16x16x32_bf16 v[82:85], v[120:123], v[132:135], v[82:85]
	v_mfma_f32_16x16x32_bf16 v[90:93], v[120:123], v[136:139], v[90:93]
	v_mfma_f32_16x16x32_bf16 v[108:111], v[120:123], v[140:143], v[108:111]
	v_mfma_f32_16x16x32_bf16 v[42:45], v[120:123], v[144:147], v[42:45]
	v_mfma_f32_16x16x32_bf16 v[86:89], v[124:127], v[132:135], v[86:89]
	v_mfma_f32_16x16x32_bf16 v[94:97], v[124:127], v[136:139], v[94:97]
	v_mfma_f32_16x16x32_bf16 v[112:115], v[124:127], v[140:143], v[112:115]
	v_mfma_f32_16x16x32_bf16 v[50:53], v[124:127], v[144:147], v[50:53]
	v_mfma_f32_16x16x32_bf16 v[66:69], v[128:131], v[132:135], v[66:69]
	v_mfma_f32_16x16x32_bf16 v[70:73], v[128:131], v[136:139], v[70:73]
	v_mfma_f32_16x16x32_bf16 v[74:77], v[128:131], v[140:143], v[74:77]
	v_mfma_f32_16x16x32_bf16 v[62:65], v[128:131], v[144:147], v[62:65]
	v_mfma_f32_16x16x32_bf16 v[78:81], v[148:151], v[188:191], v[78:81]
	v_mfma_f32_16x16x32_bf16 v[100:103], v[148:151], v[192:195], v[100:103]
	v_mfma_f32_16x16x32_bf16 v[104:107], v[148:151], v[196:199], v[104:107]
	v_mfma_f32_16x16x32_bf16 v[32:35], v[148:151], v[200:203], v[32:35]
	v_mfma_f32_16x16x32_bf16 v[82:85], v[152:155], v[188:191], v[82:85]
	v_mfma_f32_16x16x32_bf16 v[90:93], v[152:155], v[192:195], v[90:93]
	v_mfma_f32_16x16x32_bf16 v[108:111], v[152:155], v[196:199], v[108:111]
	v_mfma_f32_16x16x32_bf16 v[42:45], v[152:155], v[200:203], v[42:45]
	v_mfma_f32_16x16x32_bf16 v[86:89], v[180:183], v[188:191], v[86:89]
	v_mfma_f32_16x16x32_bf16 v[94:97], v[180:183], v[192:195], v[94:97]
	v_mfma_f32_16x16x32_bf16 v[112:115], v[180:183], v[196:199], v[112:115]
	v_mfma_f32_16x16x32_bf16 v[50:53], v[180:183], v[200:203], v[50:53]
	v_mfma_f32_16x16x32_bf16 v[66:69], v[184:187], v[188:191], v[66:69]
	v_mfma_f32_16x16x32_bf16 v[70:73], v[184:187], v[192:195], v[70:73]
	v_mfma_f32_16x16x32_bf16 v[74:77], v[184:187], v[196:199], v[74:77]
	v_mfma_f32_16x16x32_bf16 v[62:65], v[184:187], v[200:203], v[62:65]
	s_setprio 0
	s_mov_b64 s[36:37], 0x200
	s_mov_b32 m0, s5
	v_lshl_add_u64 v[36:37], v[10:11], 0, s[36:37]
	s_waitcnt vmcnt(0)
	s_barrier
; #define MFMA16(a, b, c) __builtin_amdgcn_mfma_f32_16x16x32_bf16((a), (b), (c), 0, 0, 0)
; DI void gemm_tile(const bf16_t* __restrict__ A, int lda, const bf16_t* __restrict__ Bt, int ldb, int bvalid, int K, f32x4 (&acc)[4][4], char* lds, bool preloaded = false) {
;     ...
;   auto compute = [&](int st) {
;     const char* base = lds + st * 32768;
;     bf16x8 af[2][4], bfr[2][4];
; #pragma unroll
;     for (int s = 0; s < 2; ++s) {
;       const int ch = ((4 * s + fq) ^ fx) << 4;
; #pragma unroll
;       for (int mi = 0; mi < 4; ++mi) af[s][mi] = *(const bf16x8*)(base + (wm * 64 + mi * 16 + fr) * 128 + ch);
; #pragma unroll
;       for (int ni = 0; ni < 4; ++ni) bfr[s][ni] = *(const bf16x8*)(base + 16384 + (wn * 64 + ni * 16 + fr) * 128 + ch);
;     }
;     __builtin_amdgcn_s_setprio(1);
; #pragma unroll
;     for (int s = 0; s < 2; ++s)
; #pragma unroll
;       for (int mi = 0; mi < 4; ++mi)
; #pragma unroll
;         for (int ni = 0; ni < 4; ++ni) acc[mi][ni] = MFMA16(af[s][mi], bfr[s][ni], acc[mi][ni]);
;     __builtin_amdgcn_s_setprio(0);
;   };
;   const int nk = K >> 6;
;   if (!preloaded) { GLDS(0, 0) }
;   __syncthreads();
;   for (int kt = 0; kt < nk; ++kt) {
;     if (kt + 1 < nk) { GLDS((kt + 1) & 1, (kt + 1) << 6) }
;     compute(kt & 1);
;     __syncthreads();
	global_load_lds_dwordx4 v[36:37], off
	v_lshl_add_u64 v[36:37], v[12:13], 0, s[36:37]
	s_mov_b32 m0, s10
	s_mov_b64 s[2:3], 0x8200
	global_load_lds_dwordx4 v[36:37], off
	v_lshl_add_u64 v[36:37], v[10:11], 0, s[2:3]
	s_mov_b32 m0, s11
	s_mov_b64 s[2:3], 0x10200
	global_load_lds_dwordx4 v[36:37], off
	v_lshl_add_u64 v[36:37], v[22:23], 0, s[36:37]
	s_mov_b32 m0, s21
	s_nop 0
	global_load_lds_dwordx4 v[36:37], off
	v_lshl_add_u64 v[36:37], v[10:11], 0, s[2:3]
	s_mov_b32 m0, s22
	s_mov_b64 s[2:3], 0x18200
	global_load_lds_dwordx4 v[36:37], off
	v_lshl_add_u64 v[36:37], v[24:25], 0, s[36:37]
	s_mov_b32 m0, s23
	s_nop 0
	global_load_lds_dwordx4 v[36:37], off
	v_lshl_add_u64 v[36:37], v[10:11], 0, s[2:3]
	s_mov_b32 m0, s24
	s_nop 0
	global_load_lds_dwordx4 v[36:37], off
	v_lshl_add_u64 v[36:37], v[26:27], 0, s[36:37]
	s_mov_b32 m0, s25
	s_nop 0
	global_load_lds_dwordx4 v[36:37], off
	ds_read_b128 v[116:119], v0 offset:32768
	ds_read_b128 v[120:123], v0 offset:34816
	ds_read_b128 v[124:127], v0 offset:36864
	ds_read_b128 v[128:131], v0 offset:38912
	ds_read_b128 v[132:135], v28 offset:49152
	ds_read_b128 v[136:139], v28 offset:51200
	ds_read_b128 v[140:143], v28 offset:53248
	ds_read_b128 v[144:147], v28 offset:55296
	ds_read_b128 v[148:151], v29 offset:32768
	ds_read_b128 v[152:155], v29 offset:34816
	ds_read_b128 v[180:183], v29 offset:36864
	ds_read_b128 v[184:187], v29 offset:38912
	ds_read_b128 v[188:191], v30 offset:49152
	ds_read_b128 v[192:195], v30 offset:51200
	ds_read_b128 v[196:199], v30 offset:53248
	ds_read_b128 v[200:203], v30 offset:55296
	s_setprio 1
	s_waitcnt lgkmcnt(0)
	v_mfma_f32_16x16x32_bf16 v[78:81], v[116:119], v[132:135], v[78:81]
	v_mfma_f32_16x16x32_bf16 v[100:103], v[116:119], v[136:139], v[100:103]
	v_mfma_f32_16x16x32_bf16 v[104:107], v[116:119], v[140:143], v[104:107]
	v_mfma_f32_16x16x32_bf16 v[32:35], v[116:119], v[144:147], v[32:35]
	v_mfma_f32_16x16x32_bf16 v[82:85], v[120:123], v[132:135], v[82:85]
	v_mfma_f32_16x16x32_bf16 v[90:93], v[120:123], v[136:139], v[90:93]
	v_mfma_f32_16x16x32_bf16 v[108:111], v[120:123], v[140:143], v[108:111]
	v_mfma_f32_16x16x32_bf16 v[42:45], v[120:123], v[144:147], v[42:45]
	v_mfma_f32_16x16x32_bf16 v[86:89], v[124:127], v[132:135], v[86:89]
	v_mfma_f32_16x16x32_bf16 v[94:97], v[124:127], v[136:139], v[94:97]
	v_mfma_f32_16x16x32_bf16 v[112:115], v[124:127], v[140:143], v[112:115]
	v_mfma_f32_16x16x32_bf16 v[50:53], v[124:127], v[144:147], v[50:53]
	v_mfma_f32_16x16x32_bf16 v[66:69], v[128:131], v[132:135], v[66:69]
	v_mfma_f32_16x16x32_bf16 v[70:73], v[128:131], v[136:139], v[70:73]
	v_mfma_f32_16x16x32_bf16 v[74:77], v[128:131], v[140:143], v[74:77]
	v_mfma_f32_16x16x32_bf16 v[62:65], v[128:131], v[144:147], v[62:65]
	v_mfma_f32_16x16x32_bf16 v[78:81], v[148:151], v[188:191], v[78:81]
	v_mfma_f32_16x16x32_bf16 v[100:103], v[148:151], v[192:195], v[100:103]
	v_mfma_f32_16x16x32_bf16 v[104:107], v[148:151], v[196:199], v[104:107]
	v_mfma_f32_16x16x32_bf16 v[32:35], v[148:151], v[200:203], v[32:35]
	v_mfma_f32_16x16x32_bf16 v[82:85], v[152:155], v[188:191], v[82:85]
	v_mfma_f32_16x16x32_bf16 v[90:93], v[152:155], v[192:195], v[90:93]
	v_mfma_f32_16x16x32_bf16 v[108:111], v[152:155], v[196:199], v[108:111]
	v_mfma_f32_16x16x32_bf16 v[42:45], v[152:155], v[200:203], v[42:45]
	v_mfma_f32_16x16x32_bf16 v[86:89], v[180:183], v[188:191], v[86:89]
	v_mfma_f32_16x16x32_bf16 v[94:97], v[180:183], v[192:195], v[94:97]
	v_mfma_f32_16x16x32_bf16 v[112:115], v[180:183], v[196:199], v[112:115]
	v_mfma_f32_16x16x32_bf16 v[50:53], v[180:183], v[200:203], v[50:53]
	v_mfma_f32_16x16x32_bf16 v[66:69], v[184:187], v[188:191], v[66:69]
	v_mfma_f32_16x16x32_bf16 v[70:73], v[184:187], v[192:195], v[70:73]
	v_mfma_f32_16x16x32_bf16 v[74:77], v[184:187], v[196:199], v[74:77]
	v_mfma_f32_16x16x32_bf16 v[62:65], v[184:187], v[200:203], v[62:65]
	s_setprio 0
	s_mov_b64 s[2:3], 0x280
	s_mov_b32 m0, s29
	v_lshl_add_u64 v[36:37], v[10:11], 0, s[2:3]
	s_waitcnt vmcnt(0)
	s_barrier
	global_load_lds_dwordx4 v[36:37], off
	v_lshl_add_u64 v[36:37], v[12:13], 0, s[2:3]
	s_mov_b32 m0, s26
	s_mov_b64 s[14:15], 0x8280
	global_load_lds_dwordx4 v[36:37], off
	v_lshl_add_u64 v[36:37], v[10:11], 0, s[14:15]
	s_mov_b32 m0, s27
	s_mov_b64 s[14:15], 0x10280
	global_load_lds_dwordx4 v[36:37], off
	v_lshl_add_u64 v[36:37], v[22:23], 0, s[2:3]
	s_mov_b32 m0, s28
	s_nop 0
	global_load_lds_dwordx4 v[36:37], off
	v_lshl_add_u64 v[36:37], v[10:11], 0, s[14:15]
	s_mov_b32 m0, s30
	s_mov_b64 s[14:15], 0x18280
	global_load_lds_dwordx4 v[36:37], off
	v_lshl_add_u64 v[36:37], v[24:25], 0, s[2:3]
	s_mov_b32 m0, s31
	s_nop 0
	global_load_lds_dwordx4 v[36:37], off
	v_lshl_add_u64 v[36:37], v[10:11], 0, s[14:15]
	s_mov_b32 m0, s34
	s_nop 0
	global_load_lds_dwordx4 v[36:37], off
	v_lshl_add_u64 v[36:37], v[26:27], 0, s[2:3]
	s_mov_b32 m0, s35
	s_nop 0
	global_load_lds_dwordx4 v[36:37], off
	ds_read_b128 v[116:119], v0
	ds_read_b128 v[120:123], v0 offset:2048
	ds_read_b128 v[124:127], v0 offset:4096
	ds_read_b128 v[128:131], v0 offset:6144
	ds_read_b128 v[132:135], v28 offset:16384
	ds_read_b128 v[136:139], v28 offset:18432
	ds_read_b128 v[140:143], v28 offset:20480
	ds_read_b128 v[144:147], v28 offset:22528
	ds_read_b128 v[148:151], v29
	ds_read_b128 v[152:155], v29 offset:2048
	ds_read_b128 v[180:183], v29 offset:4096
	ds_read_b128 v[184:187], v29 offset:6144
	ds_read_b128 v[188:191], v30 offset:16384
	ds_read_b128 v[192:195], v30 offset:18432
	ds_read_b128 v[196:199], v30 offset:20480
	ds_read_b128 v[200:203], v30 offset:22528
	s_setprio 1
	s_waitcnt lgkmcnt(0)
; #define MFMA16(a, b, c) __builtin_amdgcn_mfma_f32_16x16x32_bf16((a), (b), (c), 0, 0, 0)
; DI void gemm_tile(const bf16_t* __restrict__ A, int lda, const bf16_t* __restrict__ Bt, int ldb, int bvalid, int K, f32x4 (&acc)[4][4], char* lds, bool preloaded = false) {
;     ...
;   auto compute = [&](int st) {
;     const char* base = lds + st * 32768;
;     bf16x8 af[2][4], bfr[2][4];
; #pragma unroll
;     for (int s = 0; s < 2; ++s) {
;       const int ch = ((4 * s + fq) ^ fx) << 4;
; #pragma unroll
;       for (int mi = 0; mi < 4; ++mi) af[s][mi] = *(const bf16x8*)(base + (wm * 64 + mi * 16 + fr) * 128 + ch);
; #pragma unroll
;       for (int ni = 0; ni < 4; ++ni) bfr[s][ni] = *(const bf16x8*)(base + 16384 + (wn * 64 + ni * 16 + fr) * 128 + ch);
;     }
;     __builtin_amdgcn_s_setprio(1);
; #pragma unroll
;     for (int s = 0; s < 2; ++s)
; #pragma unroll
;       for (int mi = 0; mi < 4; ++mi)
; #pragma unroll
;         for (int ni = 0; ni < 4; ++ni) acc[mi][ni] = MFMA16(af[s][mi], bfr[s][ni], acc[mi][ni]);
;     __builtin_amdgcn_s_setprio(0);
;   };
;   const int nk = K >> 6;
;   if (!preloaded) { GLDS(0, 0) }
;   __syncthreads();
;   for (int kt = 0; kt < nk; ++kt) {
;     if (kt + 1 < nk) { GLDS((kt + 1) & 1, (kt + 1) << 6) }
;     compute(kt & 1);
;     __syncthreads();
	v_mfma_f32_16x16x32_bf16 v[78:81], v[116:119], v[132:135], v[78:81]
	v_mfma_f32_16x16x32_bf16 v[100:103], v[116:119], v[136:139], v[100:103]
	v_mfma_f32_16x16x32_bf16 v[104:107], v[116:119], v[140:143], v[104:107]
	v_mfma_f32_16x16x32_bf16 v[32:35], v[116:119], v[144:147], v[32:35]
	v_mfma_f32_16x16x32_bf16 v[82:85], v[120:123], v[132:135], v[82:85]
	v_mfma_f32_16x16x32_bf16 v[90:93], v[120:123], v[136:139], v[90:93]
	v_mfma_f32_16x16x32_bf16 v[108:111], v[120:123], v[140:143], v[108:111]
	v_mfma_f32_16x16x32_bf16 v[42:45], v[120:123], v[144:147], v[42:45]
	v_mfma_f32_16x16x32_bf16 v[86:89], v[124:127], v[132:135], v[86:89]
	v_mfma_f32_16x16x32_bf16 v[94:97], v[124:127], v[136:139], v[94:97]
	v_mfma_f32_16x16x32_bf16 v[112:115], v[124:127], v[140:143], v[112:115]
	v_mfma_f32_16x16x32_bf16 v[50:53], v[124:127], v[144:147], v[50:53]
	v_mfma_f32_16x16x32_bf16 v[66:69], v[128:131], v[132:135], v[66:69]
	v_mfma_f32_16x16x32_bf16 v[70:73], v[128:131], v[136:139], v[70:73]
	v_mfma_f32_16x16x32_bf16 v[74:77], v[128:131], v[140:143], v[74:77]
	v_mfma_f32_16x16x32_bf16 v[62:65], v[128:131], v[144:147], v[62:65]
	v_mfma_f32_16x16x32_bf16 v[78:81], v[148:151], v[188:191], v[78:81]
	v_mfma_f32_16x16x32_bf16 v[100:103], v[148:151], v[192:195], v[100:103]
	v_mfma_f32_16x16x32_bf16 v[104:107], v[148:151], v[196:199], v[104:107]
	v_mfma_f32_16x16x32_bf16 v[32:35], v[148:151], v[200:203], v[32:35]
	v_mfma_f32_16x16x32_bf16 v[82:85], v[152:155], v[188:191], v[82:85]
	v_mfma_f32_16x16x32_bf16 v[90:93], v[152:155], v[192:195], v[90:93]
	v_mfma_f32_16x16x32_bf16 v[108:111], v[152:155], v[196:199], v[108:111]
	v_mfma_f32_16x16x32_bf16 v[42:45], v[152:155], v[200:203], v[42:45]
	v_mfma_f32_16x16x32_bf16 v[86:89], v[180:183], v[188:191], v[86:89]
	v_mfma_f32_16x16x32_bf16 v[94:97], v[180:183], v[192:195], v[94:97]
	v_mfma_f32_16x16x32_bf16 v[112:115], v[180:183], v[196:199], v[112:115]
	v_mfma_f32_16x16x32_bf16 v[50:53], v[180:183], v[200:203], v[50:53]
	v_mfma_f32_16x16x32_bf16 v[66:69], v[184:187], v[188:191], v[66:69]
	v_mfma_f32_16x16x32_bf16 v[70:73], v[184:187], v[192:195], v[70:73]
	v_mfma_f32_16x16x32_bf16 v[74:77], v[184:187], v[196:199], v[74:77]
	v_mfma_f32_16x16x32_bf16 v[62:65], v[184:187], v[200:203], v[62:65]
	s_setprio 0
	s_mov_b64 s[14:15], 0x300
	s_mov_b32 m0, s5
	v_lshl_add_u64 v[36:37], v[10:11], 0, s[14:15]
	s_waitcnt vmcnt(0)
	s_barrier
	global_load_lds_dwordx4 v[36:37], off
	v_lshl_add_u64 v[36:37], v[12:13], 0, s[14:15]
	s_mov_b32 m0, s10
	s_mov_b64 s[64:65], 0x8300
	global_load_lds_dwordx4 v[36:37], off
	v_lshl_add_u64 v[36:37], v[10:11], 0, s[64:65]
	s_mov_b32 m0, s11
	s_mov_b64 s[10:11], 0x10300
	global_load_lds_dwordx4 v[36:37], off
	v_lshl_add_u64 v[36:37], v[22:23], 0, s[14:15]
	s_mov_b32 m0, s21
	s_nop 0
	global_load_lds_dwordx4 v[36:37], off
	v_lshl_add_u64 v[36:37], v[10:11], 0, s[10:11]
	s_mov_b32 m0, s22
	s_mov_b64 s[10:11], 0x18300
	global_load_lds_dwordx4 v[36:37], off
	v_lshl_add_u64 v[36:37], v[24:25], 0, s[14:15]
	s_mov_b32 m0, s23
	s_nop 0
	global_load_lds_dwordx4 v[36:37], off
	v_lshl_add_u64 v[36:37], v[10:11], 0, s[10:11]
	s_mov_b32 m0, s24
	s_nop 0
	global_load_lds_dwordx4 v[36:37], off
	v_lshl_add_u64 v[36:37], v[26:27], 0, s[14:15]
	s_mov_b32 m0, s25
	s_nop 0
	global_load_lds_dwordx4 v[36:37], off
	ds_read_b128 v[116:119], v0 offset:32768
	ds_read_b128 v[120:123], v0 offset:34816
	ds_read_b128 v[124:127], v0 offset:36864
	ds_read_b128 v[128:131], v0 offset:38912
	ds_read_b128 v[132:135], v28 offset:49152
	ds_read_b128 v[136:139], v28 offset:51200
	ds_read_b128 v[140:143], v28 offset:53248
	ds_read_b128 v[144:147], v28 offset:55296
	ds_read_b128 v[148:151], v29 offset:32768
	ds_read_b128 v[152:155], v29 offset:34816
	ds_read_b128 v[180:183], v29 offset:36864
	ds_read_b128 v[184:187], v29 offset:38912
	ds_read_b128 v[188:191], v30 offset:49152
	ds_read_b128 v[192:195], v30 offset:51200
	ds_read_b128 v[196:199], v30 offset:53248
	ds_read_b128 v[200:203], v30 offset:55296
	s_setprio 1
	s_waitcnt lgkmcnt(0)
	v_mfma_f32_16x16x32_bf16 v[78:81], v[116:119], v[132:135], v[78:81]
	v_mfma_f32_16x16x32_bf16 v[100:103], v[116:119], v[136:139], v[100:103]
	v_mfma_f32_16x16x32_bf16 v[104:107], v[116:119], v[140:143], v[104:107]
	v_mfma_f32_16x16x32_bf16 v[32:35], v[116:119], v[144:147], v[32:35]
	v_mfma_f32_16x16x32_bf16 v[82:85], v[120:123], v[132:135], v[82:85]
	v_mfma_f32_16x16x32_bf16 v[90:93], v[120:123], v[136:139], v[90:93]
	v_mfma_f32_16x16x32_bf16 v[108:111], v[120:123], v[140:143], v[108:111]
	v_mfma_f32_16x16x32_bf16 v[42:45], v[120:123], v[144:147], v[42:45]
	v_mfma_f32_16x16x32_bf16 v[86:89], v[124:127], v[132:135], v[86:89]
	v_mfma_f32_16x16x32_bf16 v[94:97], v[124:127], v[136:139], v[94:97]
	v_mfma_f32_16x16x32_bf16 v[112:115], v[124:127], v[140:143], v[112:115]
	v_mfma_f32_16x16x32_bf16 v[50:53], v[124:127], v[144:147], v[50:53]
	v_mfma_f32_16x16x32_bf16 v[66:69], v[128:131], v[132:135], v[66:69]
	v_mfma_f32_16x16x32_bf16 v[70:73], v[128:131], v[136:139], v[70:73]
	v_mfma_f32_16x16x32_bf16 v[74:77], v[128:131], v[140:143], v[74:77]
	v_mfma_f32_16x16x32_bf16 v[62:65], v[128:131], v[144:147], v[62:65]
	v_mfma_f32_16x16x32_bf16 v[78:81], v[148:151], v[188:191], v[78:81]
	v_mfma_f32_16x16x32_bf16 v[100:103], v[148:151], v[192:195], v[100:103]
	v_mfma_f32_16x16x32_bf16 v[104:107], v[148:151], v[196:199], v[104:107]
	v_mfma_f32_16x16x32_bf16 v[32:35], v[148:151], v[200:203], v[32:35]
	v_mfma_f32_16x16x32_bf16 v[82:85], v[152:155], v[188:191], v[82:85]
	v_mfma_f32_16x16x32_bf16 v[90:93], v[152:155], v[192:195], v[90:93]
	v_mfma_f32_16x16x32_bf16 v[108:111], v[152:155], v[196:199], v[108:111]
	v_mfma_f32_16x16x32_bf16 v[42:45], v[152:155], v[200:203], v[42:45]
	v_mfma_f32_16x16x32_bf16 v[86:89], v[180:183], v[188:191], v[86:89]
	v_mfma_f32_16x16x32_bf16 v[94:97], v[180:183], v[192:195], v[94:97]
	v_mfma_f32_16x16x32_bf16 v[112:115], v[180:183], v[196:199], v[112:115]
	v_mfma_f32_16x16x32_bf16 v[50:53], v[180:183], v[200:203], v[50:53]
	v_mfma_f32_16x16x32_bf16 v[66:69], v[184:187], v[188:191], v[66:69]
	v_mfma_f32_16x16x32_bf16 v[70:73], v[184:187], v[192:195], v[70:73]
	v_mfma_f32_16x16x32_bf16 v[74:77], v[184:187], v[196:199], v[74:77]
	v_mfma_f32_16x16x32_bf16 v[62:65], v[184:187], v[200:203], v[62:65]
	s_setprio 0
	s_mov_b64 s[64:65], 0x380
	s_mov_b32 m0, s29
	v_lshl_add_u64 v[36:37], v[10:11], 0, s[64:65]
	s_waitcnt vmcnt(0)
	s_barrier
; #define MFMA16(a, b, c) __builtin_amdgcn_mfma_f32_16x16x32_bf16((a), (b), (c), 0, 0, 0)
; DI void gemm_tile(const bf16_t* __restrict__ A, int lda, const bf16_t* __restrict__ Bt, int ldb, int bvalid, int K, f32x4 (&acc)[4][4], char* lds, bool preloaded = false) {
;     ...
;   auto compute = [&](int st) {
;     const char* base = lds + st * 32768;
;     bf16x8 af[2][4], bfr[2][4];
; #pragma unroll
;     for (int s = 0; s < 2; ++s) {
;       const int ch = ((4 * s + fq) ^ fx) << 4;
; #pragma unroll
;       for (int mi = 0; mi < 4; ++mi) af[s][mi] = *(const bf16x8*)(base + (wm * 64 + mi * 16 + fr) * 128 + ch);
; #pragma unroll
;       for (int ni = 0; ni < 4; ++ni) bfr[s][ni] = *(const bf16x8*)(base + 16384 + (wn * 64 + ni * 16 + fr) * 128 + ch);
;     }
;     __builtin_amdgcn_s_setprio(1);
; #pragma unroll
;     for (int s = 0; s < 2; ++s)
; #pragma unroll
;       for (int mi = 0; mi < 4; ++mi)
; #pragma unroll
;         for (int ni = 0; ni < 4; ++ni) acc[mi][ni] = MFMA16(af[s][mi], bfr[s][ni], acc[mi][ni]);
;     __builtin_amdgcn_s_setprio(0);
;   };
;   const int nk = K >> 6;
;   if (!preloaded) { GLDS(0, 0) }
;   __syncthreads();
;   for (int kt = 0; kt < nk; ++kt) {
;     if (kt + 1 < nk) { GLDS((kt + 1) & 1, (kt + 1) << 6) }
;     compute(kt & 1);
;     __syncthreads();
;   }
	global_load_lds_dwordx4 v[36:37], off
	v_lshl_add_u64 v[12:13], v[12:13], 0, s[64:65]
	s_mov_b32 m0, s26
	s_mov_b64 s[10:11], 0x8380
	global_load_lds_dwordx4 v[12:13], off
	v_lshl_add_u64 v[12:13], v[10:11], 0, s[10:11]
	s_mov_b32 m0, s27
	s_mov_b64 s[10:11], 0x10380
	global_load_lds_dwordx4 v[12:13], off
	v_lshl_add_u64 v[12:13], v[22:23], 0, s[64:65]
	s_mov_b32 m0, s28
	s_nop 0
	global_load_lds_dwordx4 v[12:13], off
	v_lshl_add_u64 v[12:13], v[10:11], 0, s[10:11]
	s_mov_b32 m0, s30
	s_mov_b64 s[10:11], 0x18380
	global_load_lds_dwordx4 v[12:13], off
	v_lshl_add_u64 v[12:13], v[24:25], 0, s[64:65]
	s_mov_b32 m0, s31
	v_lshl_add_u64 v[10:11], v[10:11], 0, s[10:11]
	global_load_lds_dwordx4 v[12:13], off
	s_mov_b32 m0, s34
	s_nop 0
	global_load_lds_dwordx4 v[10:11], off
	v_lshl_add_u64 v[10:11], v[26:27], 0, s[64:65]
	s_mov_b32 m0, s35
	s_nop 0
	global_load_lds_dwordx4 v[10:11], off
	ds_read_b128 v[10:13], v0
	ds_read_b128 v[22:25], v0 offset:2048
	ds_read_b128 v[116:119], v0 offset:4096
	ds_read_b128 v[120:123], v0 offset:6144
	ds_read_b128 v[124:127], v28 offset:16384
	ds_read_b128 v[128:131], v28 offset:18432
	ds_read_b128 v[132:135], v28 offset:20480
	ds_read_b128 v[136:139], v28 offset:22528
	ds_read_b128 v[140:143], v29
	ds_read_b128 v[144:147], v29 offset:2048
	ds_read_b128 v[148:151], v29 offset:4096
	ds_read_b128 v[152:155], v29 offset:6144
	ds_read_b128 v[180:183], v30 offset:16384
	ds_read_b128 v[184:187], v30 offset:18432
	ds_read_b128 v[188:191], v30 offset:20480
	ds_read_b128 v[192:195], v30 offset:22528
	s_setprio 1
	s_waitcnt lgkmcnt(0)
	v_mfma_f32_16x16x32_bf16 v[78:81], v[10:13], v[124:127], v[78:81]
	v_mfma_f32_16x16x32_bf16 v[100:103], v[10:13], v[128:131], v[100:103]
	v_mfma_f32_16x16x32_bf16 v[104:107], v[10:13], v[132:135], v[104:107]
	v_mfma_f32_16x16x32_bf16 v[10:13], v[10:13], v[136:139], v[32:35]
	v_mfma_f32_16x16x32_bf16 v[32:35], v[22:25], v[124:127], v[82:85]
	v_mfma_f32_16x16x32_bf16 v[82:85], v[22:25], v[128:131], v[90:93]
	v_mfma_f32_16x16x32_bf16 v[90:93], v[22:25], v[132:135], v[108:111]
	v_mfma_f32_16x16x32_bf16 v[22:25], v[22:25], v[136:139], v[42:45]
	v_mfma_f32_16x16x32_bf16 v[42:45], v[116:119], v[124:127], v[86:89]
	v_mfma_f32_16x16x32_bf16 v[86:89], v[116:119], v[128:131], v[94:97]
	v_mfma_f32_16x16x32_bf16 v[94:97], v[116:119], v[132:135], v[112:115]
	v_mfma_f32_16x16x32_bf16 v[50:53], v[116:119], v[136:139], v[50:53]
	v_mfma_f32_16x16x32_bf16 v[66:69], v[120:123], v[124:127], v[66:69]
	v_mfma_f32_16x16x32_bf16 v[70:73], v[120:123], v[128:131], v[70:73]
	v_mfma_f32_16x16x32_bf16 v[74:77], v[120:123], v[132:135], v[74:77]
	v_mfma_f32_16x16x32_bf16 v[62:65], v[120:123], v[136:139], v[62:65]
	v_mfma_f32_16x16x32_bf16 v[78:81], v[140:143], v[180:183], v[78:81]
	v_mfma_f32_16x16x32_bf16 v[100:103], v[140:143], v[184:187], v[100:103]
	v_mfma_f32_16x16x32_bf16 v[104:107], v[140:143], v[188:191], v[104:107]
	v_mfma_f32_16x16x32_bf16 v[10:13], v[140:143], v[192:195], v[10:13]
	v_mfma_f32_16x16x32_bf16 v[32:35], v[144:147], v[180:183], v[32:35]
	v_mfma_f32_16x16x32_bf16 v[82:85], v[144:147], v[184:187], v[82:85]
	v_mfma_f32_16x16x32_bf16 v[90:93], v[144:147], v[188:191], v[90:93]
	v_mfma_f32_16x16x32_bf16 v[22:25], v[144:147], v[192:195], v[22:25]
	v_mfma_f32_16x16x32_bf16 v[42:45], v[148:151], v[180:183], v[42:45]
	v_mfma_f32_16x16x32_bf16 v[86:89], v[148:151], v[184:187], v[86:89]
	v_mfma_f32_16x16x32_bf16 v[94:97], v[148:151], v[188:191], v[94:97]
	v_mfma_f32_16x16x32_bf16 v[50:53], v[148:151], v[192:195], v[50:53]
	v_mfma_f32_16x16x32_bf16 v[66:69], v[152:155], v[180:183], v[66:69]
	v_mfma_f32_16x16x32_bf16 v[70:73], v[152:155], v[184:187], v[70:73]
	v_mfma_f32_16x16x32_bf16 v[74:77], v[152:155], v[188:191], v[74:77]
	v_mfma_f32_16x16x32_bf16 v[62:65], v[152:155], v[192:195], v[62:65]
	s_setprio 0
	s_waitcnt vmcnt(0)
	s_barrier
	ds_read_b128 v[108:111], v0 offset:32768
	ds_read_b128 v[112:115], v0 offset:34816
	ds_read_b128 v[116:119], v0 offset:36864
	ds_read_b128 v[120:123], v0 offset:38912
	ds_read_b128 v[124:127], v28 offset:49152
	ds_read_b128 v[128:131], v28 offset:51200
	ds_read_b128 v[132:135], v28 offset:53248
	ds_read_b128 v[136:139], v28 offset:55296
	ds_read_b128 v[140:143], v29 offset:32768
	ds_read_b128 v[144:147], v29 offset:34816
	ds_read_b128 v[148:151], v29 offset:36864
	ds_read_b128 v[26:29], v29 offset:38912
	ds_read_b128 v[152:155], v30 offset:49152
	ds_read_b128 v[180:183], v30 offset:51200
	ds_read_b128 v[184:187], v30 offset:53248
	ds_read_b128 v[188:191], v30 offset:55296
	s_setprio 1
	s_waitcnt lgkmcnt(11)
	v_mfma_f32_16x16x32_bf16 v[78:81], v[108:111], v[124:127], v[78:81]
	s_waitcnt lgkmcnt(10)
	v_mfma_f32_16x16x32_bf16 v[100:103], v[108:111], v[128:131], v[100:103]
	s_waitcnt lgkmcnt(9)
	v_mfma_f32_16x16x32_bf16 v[104:107], v[108:111], v[132:135], v[104:107]
	s_waitcnt lgkmcnt(8)
	v_mfma_f32_16x16x32_bf16 v[108:111], v[108:111], v[136:139], v[10:13]
	v_mfma_f32_16x16x32_bf16 v[34:37], v[112:115], v[124:127], v[32:35]
	v_mfma_f32_16x16x32_bf16 v[82:85], v[112:115], v[128:131], v[82:85]
	v_mfma_f32_16x16x32_bf16 v[192:195], v[112:115], v[132:135], v[90:93]
	v_mfma_f32_16x16x32_bf16 v[112:115], v[112:115], v[136:139], v[22:25]
	v_mfma_f32_16x16x32_bf16 v[42:45], v[116:119], v[124:127], v[42:45]
	v_mfma_f32_16x16x32_bf16 v[196:199], v[116:119], v[128:131], v[86:89]
	v_mfma_f32_16x16x32_bf16 v[200:203], v[116:119], v[132:135], v[94:97]
	v_mfma_f32_16x16x32_bf16 v[50:53], v[116:119], v[136:139], v[50:53]
	v_mfma_f32_16x16x32_bf16 v[116:119], v[120:123], v[124:127], v[66:69]
	v_mfma_f32_16x16x32_bf16 v[124:127], v[120:123], v[128:131], v[70:73]
	v_mfma_f32_16x16x32_bf16 v[128:131], v[120:123], v[132:135], v[74:77]
	v_mfma_f32_16x16x32_bf16 v[120:123], v[120:123], v[136:139], v[62:65]
	s_waitcnt lgkmcnt(3)
	v_mfma_f32_16x16x32_bf16 v[10:13], v[140:143], v[152:155], v[78:81]
	s_waitcnt lgkmcnt(2)
	v_mfma_f32_16x16x32_bf16 v[22:25], v[140:143], v[180:183], v[100:103]
	s_waitcnt lgkmcnt(1)
	v_mfma_f32_16x16x32_bf16 v[30:33], v[140:143], v[184:187], v[104:107]
	s_waitcnt lgkmcnt(0)
	v_mfma_f32_16x16x32_bf16 v[94:97], v[140:143], v[188:191], v[108:111]
	v_mfma_f32_16x16x32_bf16 v[90:93], v[144:147], v[152:155], v[34:37]
	v_mfma_f32_16x16x32_bf16 v[62:65], v[144:147], v[180:183], v[82:85]
	v_mfma_f32_16x16x32_bf16 v[70:73], v[144:147], v[184:187], v[192:195]
	v_mfma_f32_16x16x32_bf16 v[86:89], v[144:147], v[188:191], v[112:115]
	v_mfma_f32_16x16x32_bf16 v[82:85], v[148:151], v[152:155], v[42:45]
	v_mfma_f32_16x16x32_bf16 v[78:81], v[148:151], v[180:183], v[196:199]
	v_mfma_f32_16x16x32_bf16 v[74:77], v[148:151], v[184:187], v[200:203]
	v_mfma_f32_16x16x32_bf16 v[66:69], v[148:151], v[188:191], v[50:53]
	v_mfma_f32_16x16x32_bf16 v[50:53], v[26:29], v[152:155], v[116:119]
	v_mfma_f32_16x16x32_bf16 v[42:45], v[26:29], v[180:183], v[124:127]
	v_mfma_f32_16x16x32_bf16 v[34:37], v[26:29], v[184:187], v[128:131]
	v_mfma_f32_16x16x32_bf16 v[26:29], v[26:29], v[188:191], v[120:123]
	s_setprio 0
	v_mov_b32_e32 v106, v158
	s_barrier
; DI int tidx() { int t = __builtin_amdgcn_workitem_id_x(); asm volatile("" : "+v"(t)); return t; }
; DI void gemm_prefetch0(const bf16_t* __restrict__ A, int lda, const bf16_t* __restrict__ Bt, int ldb, int bvalid, char* lds) {
;   const int tid = tidx();
;   const int lr = tid >> 3, lc = tid & 7;
;   const bf16_t* ap = A + (size_t)lr * lda + ((lc ^ ((lr >> 1) & 7)) << 3);
;   const bf16_t* bp = Bt + ((lc ^ ((lr >> 1) & 7)) << 3);
;   typedef __attribute__((address_space(1))) const unsigned gptr_t;
;   typedef __attribute__((address_space(3))) unsigned lptr_t;
;   const unsigned lbase = (unsigned)(size_t)lds + (unsigned)tid * 16u;
; #pragma unroll
;   for (int i = 0; i < 4; ++i) {
;     __builtin_amdgcn_global_load_lds((gptr_t*)(ap + (size_t)(32 * i) * lda), (lptr_t*)(lbase + i * 4096), 16, 0, 0);
;     __builtin_amdgcn_global_load_lds((gptr_t*)(bp + (size_t)((lr + 32 * i) & (bvalid - 1)) * ldb), (lptr_t*)(lbase + 16384 + i * 4096), 16, 0, 0);
;   }
; DI void phaseD_tile(const P& p, int layer, int mt, int nt, char* lds) {
;     ...
; #pragma unroll
;   for (int mi = 0; mi < 4; ++mi)
; #pragma unroll
;     for (int ni = 0; ni < 4; ++ni)
; #pragma unroll
;       for (int j = 0; j < 4; ++j) acc[mi][ni][j] *= (float)((gpv[mi][ni] >> (8 * j)) & 255u) / fmaxf((float)((gav[mi][ni] >> (8 * j)) & 255u), 1.f);
	s_add_u32 s10, s97, s8
	v_readlane_b32 s5, v240, 45
	s_addc_u32 s11, s5, s9
	v_ashrrev_i32_e32 v100, 3, v106
	v_lshrrev_b32_e32 v0, 4, v106
	v_readlane_b32 s8, v240, 33
	v_ashrrev_i32_e32 v101, 31, v100
	v_xor_b32_e32 v0, v0, v106
	v_readlane_b32 s9, v240, 34
	s_add_u32 s8, s8, s12
	v_lshlrev_b64 v[102:103], 10, v[100:101]
	v_lshlrev_b32_e32 v0, 4, v0
	s_addc_u32 s9, s9, s13
	v_lshl_add_u64 v[102:103], s[10:11], 0, v[102:103]
	v_and_b32_e32 v0, 0x70, v0
	v_lshlrev_b32_e32 v107, 9, v100
	v_lshl_add_u64 v[102:103], v[102:103], 0, v[0:1]
	v_lshl_add_u64 v[104:105], s[8:9], 0, v[0:1]
	v_lshlrev_b32_e32 v106, 4, v106
	v_and_b32_e32 v0, 0xfe00, v107
	v_add_u32_e32 v108, 0x4000, v106
	v_readfirstlane_b32 s5, v106
	v_lshlrev_b32_e32 v0, 1, v0
	s_mov_b32 m0, s5
	v_lshl_add_u64 v[100:101], v[104:105], 0, v[0:1]
	v_readfirstlane_b32 s5, v108
	v_add_u32_e32 v0, 0x1000, v106
	global_load_lds_dwordx4 v[102:103], off
	s_mov_b32 m0, s5
	v_readfirstlane_b32 s5, v0
	v_add_u32_e32 v0, 0x4000, v107
	v_and_b32_e32 v0, 0xfe00, v0
	global_load_lds_dwordx4 v[100:101], off
	v_lshl_add_u64 v[100:101], v[102:103], 0, s[40:41]
	s_mov_b32 m0, s5
	v_lshlrev_b32_e32 v0, 1, v0
	global_load_lds_dwordx4 v[100:101], off
	v_lshl_add_u64 v[100:101], v[104:105], 0, v[0:1]
	v_add_u32_e32 v0, 0x5000, v106
	s_mov_b64 s[30:31], 0x100
	v_readfirstlane_b32 s5, v0
	v_add_u32_e32 v0, 0x2000, v106
	s_mov_b32 m0, s5
	v_readfirstlane_b32 s5, v0
	v_bitop3_b32 v0, v107, s33, v167 bitop3:0x6c
	global_load_lds_dwordx4 v[100:101], off
	v_lshl_add_u64 v[100:101], v[102:103], 0, s[42:43]
	s_mov_b32 m0, s5
	v_lshlrev_b32_e32 v0, 1, v0
	global_load_lds_dwordx4 v[100:101], off
	v_lshl_add_u64 v[100:101], v[104:105], 0, v[0:1]
	v_add_u32_e32 v0, 0x6000, v106
	s_nop 0
	v_readfirstlane_b32 s5, v0
	v_add_u32_e32 v0, 0x3000, v106
	s_mov_b32 m0, s5
	v_readfirstlane_b32 s5, v0
	v_add_u32_e32 v0, 0xc000, v107
	v_and_b32_e32 v0, 0xfe00, v0
	global_load_lds_dwordx4 v[100:101], off
	v_lshl_add_u64 v[100:101], v[102:103], 0, s[50:51]
	s_mov_b32 m0, s5
	v_lshlrev_b32_e32 v0, 1, v0
	global_load_lds_dwordx4 v[100:101], off
	v_lshl_add_u64 v[100:101], v[104:105], 0, v[0:1]
	v_add_u32_e32 v0, 0x7000, v106
	v_cvt_f32_ubyte2_e32 v104, v38
	v_readfirstlane_b32 s5, v0
	s_mov_b32 m0, s5
	v_cvt_f32_ubyte0_e32 v0, v46
	global_load_lds_dwordx4 v[100:101], off
	v_max_f32_e32 v100, 1.0, v0
	v_cvt_f32_ubyte1_e32 v0, v46
	v_max_f32_e32 v101, 1.0, v0
	v_cvt_f32_ubyte2_e32 v0, v46
	v_max_f32_e32 v102, 1.0, v0
	v_cvt_f32_ubyte3_e32 v0, v46
	v_max_f32_e32 v103, 1.0, v0
	v_cvt_f32_ubyte0_e32 v0, v38
	v_cvt_f32_ubyte1_e32 v46, v38
	v_cvt_f32_ubyte3_e32 v38, v38
	v_rcp_f32_e32 v105, v103
	s_nop 0
	v_mul_f32_e32 v105, v38, v105
	v_rcp_f32_e32 v38, v102
	s_nop 0
	v_mul_f32_e32 v104, v104, v38
	v_pk_mul_f32 v[12:13], v[104:105], v[12:13]
	v_rcp_f32_e32 v38, v101
	s_nop 0
	v_mul_f32_e32 v107, v46, v38
	v_rcp_f32_e32 v38, v100
	s_nop 0
	v_mul_f32_e32 v106, v0, v38
	v_cvt_f32_ubyte0_e32 v0, v47
	v_max_f32_e32 v104, 1.0, v0
	v_cvt_f32_ubyte1_e32 v0, v47
	v_max_f32_e32 v105, 1.0, v0
	v_cvt_f32_ubyte2_e32 v0, v47
	v_pk_mul_f32 v[10:11], v[106:107], v[10:11]
	v_max_f32_e32 v106, 1.0, v0
	v_cvt_f32_ubyte3_e32 v0, v47
	v_max_f32_e32 v107, 1.0, v0
	v_cvt_f32_ubyte0_e32 v0, v39
	v_cvt_f32_ubyte1_e32 v46, v39
	v_cvt_f32_ubyte2_e32 v38, v39
	v_cvt_f32_ubyte3_e32 v39, v39
	v_rcp_f32_e32 v47, v107
	s_nop 0
	v_mul_f32_e32 v39, v39, v47
	v_rcp_f32_e32 v47, v106
	s_nop 0
	v_mul_f32_e32 v38, v38, v47
	v_pk_mul_f32 v[24:25], v[38:39], v[24:25]
	v_cvt_f32_ubyte3_e32 v39, v40
	v_cvt_f32_ubyte2_e32 v38, v40
	v_rcp_f32_e32 v47, v105
	s_nop 0
	v_mul_f32_e32 v47, v46, v47
	v_rcp_f32_e32 v46, v104
	s_nop 0
	v_mul_f32_e32 v46, v0, v46
	v_cvt_f32_ubyte0_e32 v0, v48
	v_max_f32_e32 v108, 1.0, v0
	v_cvt_f32_ubyte1_e32 v0, v48
	v_max_f32_e32 v109, 1.0, v0
	v_cvt_f32_ubyte2_e32 v0, v48
	v_max_f32_e32 v110, 1.0, v0
	v_cvt_f32_ubyte3_e32 v0, v48
	v_max_f32_e32 v111, 1.0, v0
	v_pk_mul_f32 v[22:23], v[46:47], v[22:23]
	v_cvt_f32_ubyte0_e32 v0, v40
	v_cvt_f32_ubyte1_e32 v46, v40
	v_rcp_f32_e32 v40, v111
	s_nop 0
	v_mul_f32_e32 v39, v39, v40
	v_rcp_f32_e32 v40, v110
	s_nop 0
	v_mul_f32_e32 v38, v38, v40
	v_pk_mul_f32 v[32:33], v[38:39], v[32:33]
	v_cvt_f32_ubyte1_e32 v38, v41
	v_cvt_f32_ubyte2_e32 v39, v41
	v_rcp_f32_e32 v40, v109
	s_nop 0
	v_mul_f32_e32 v47, v46, v40
	v_rcp_f32_e32 v40, v108
	s_nop 0
	v_mul_f32_e32 v46, v0, v40
	v_cvt_f32_ubyte0_e32 v0, v49
	v_max_f32_e32 v112, 1.0, v0
	v_cvt_f32_ubyte1_e32 v0, v49
	v_max_f32_e32 v113, 1.0, v0
	v_cvt_f32_ubyte2_e32 v0, v49
	v_max_f32_e32 v114, 1.0, v0
	v_cvt_f32_ubyte3_e32 v0, v49
	v_max_f32_e32 v115, 1.0, v0
	v_cvt_f32_ubyte3_e32 v40, v41
	v_cvt_f32_ubyte0_e32 v0, v41
	v_pk_mul_f32 v[30:31], v[46:47], v[30:31]
	v_rcp_f32_e32 v41, v115
	s_nop 0
	v_mul_f32_e32 v41, v40, v41
	v_rcp_f32_e32 v40, v114
	s_nop 0
	v_mul_f32_e32 v40, v39, v40
	v_pk_mul_f32 v[40:41], v[40:41], v[96:97]
	v_rcp_f32_e32 v39, v113
	s_nop 0
	v_mul_f32_e32 v39, v38, v39
	v_rcp_f32_e32 v38, v112
	s_nop 0
	v_mul_f32_e32 v38, v0, v38
	v_cvt_f32_ubyte0_e32 v0, v58
	v_pk_mul_f32 v[38:39], v[38:39], v[94:95]
	v_max_f32_e32 v94, 1.0, v0
	v_cvt_f32_ubyte1_e32 v0, v58
	v_max_f32_e32 v95, 1.0, v0
	v_cvt_f32_ubyte2_e32 v0, v58
	v_max_f32_e32 v96, 1.0, v0
	v_cvt_f32_ubyte3_e32 v0, v58
	v_max_f32_e32 v97, 1.0, v0
	v_cvt_f32_ubyte3_e32 v48, v54
	v_cvt_f32_ubyte0_e32 v0, v54
	v_cvt_f32_ubyte1_e32 v46, v54
	v_cvt_f32_ubyte2_e32 v47, v54
	v_rcp_f32_e32 v49, v97
	s_nop 0
	v_mul_f32_e32 v49, v48, v49
	v_rcp_f32_e32 v48, v96
	s_nop 0
	v_mul_f32_e32 v48, v47, v48
	v_pk_mul_f32 v[48:49], v[48:49], v[92:93]
	v_rcp_f32_e32 v47, v95
	s_nop 0
	v_mul_f32_e32 v47, v46, v47
; DI void phaseD_tile(const P& p, int layer, int mt, int nt, char* lds) {
;     ...
; #pragma unroll
;   for (int mi = 0; mi < 4; ++mi)
; #pragma unroll
;     for (int ni = 0; ni < 4; ++ni)
; #pragma unroll
;       for (int j = 0; j < 4; ++j) acc[mi][ni][j] *= (float)((gpv[mi][ni] >> (8 * j)) & 255u) / fmaxf((float)((gav[mi][ni] >> (8 * j)) & 255u), 1.f);
	v_rcp_f32_e32 v46, v94
	s_nop 0
	v_mul_f32_e32 v46, v0, v46
	v_cvt_f32_ubyte0_e32 v0, v59
	v_pk_mul_f32 v[46:47], v[46:47], v[90:91]
	v_max_f32_e32 v90, 1.0, v0
	v_cvt_f32_ubyte1_e32 v0, v59
	v_max_f32_e32 v91, 1.0, v0
	v_cvt_f32_ubyte2_e32 v0, v59
	v_max_f32_e32 v92, 1.0, v0
	v_cvt_f32_ubyte3_e32 v0, v59
	v_max_f32_e32 v93, 1.0, v0
	v_cvt_f32_ubyte0_e32 v0, v55
	v_cvt_f32_ubyte1_e32 v58, v55
	v_cvt_f32_ubyte2_e32 v54, v55
	v_cvt_f32_ubyte3_e32 v55, v55
	v_rcp_f32_e32 v59, v93
	s_nop 0
	v_mul_f32_e32 v55, v55, v59
	v_rcp_f32_e32 v59, v92
	s_nop 0
	v_mul_f32_e32 v54, v54, v59
	v_pk_mul_f32 v[64:65], v[54:55], v[64:65]
	v_cvt_f32_ubyte3_e32 v55, v56
	v_cvt_f32_ubyte2_e32 v54, v56
	v_rcp_f32_e32 v59, v91
	s_nop 0
	v_mul_f32_e32 v59, v58, v59
	v_rcp_f32_e32 v58, v90
	s_nop 0
	v_mul_f32_e32 v58, v0, v58
	v_cvt_f32_ubyte0_e32 v0, v60
	v_max_f32_e32 v116, 1.0, v0
	v_cvt_f32_ubyte1_e32 v0, v60
	v_max_f32_e32 v117, 1.0, v0
	v_cvt_f32_ubyte2_e32 v0, v60
	v_max_f32_e32 v118, 1.0, v0
	v_cvt_f32_ubyte3_e32 v0, v60
	v_max_f32_e32 v119, 1.0, v0
	v_pk_mul_f32 v[62:63], v[58:59], v[62:63]
	v_cvt_f32_ubyte0_e32 v0, v56
	v_cvt_f32_ubyte1_e32 v58, v56
	v_rcp_f32_e32 v56, v119
	s_nop 0
	v_mul_f32_e32 v55, v55, v56
	v_rcp_f32_e32 v56, v118
	s_nop 0
	v_mul_f32_e32 v54, v54, v56
	v_pk_mul_f32 v[72:73], v[54:55], v[72:73]
	v_cvt_f32_ubyte1_e32 v54, v57
	v_cvt_f32_ubyte2_e32 v55, v57
	v_rcp_f32_e32 v56, v117
	s_nop 0
	v_mul_f32_e32 v59, v58, v56
	v_rcp_f32_e32 v56, v116
	s_nop 0
	v_mul_f32_e32 v58, v0, v56
	v_cvt_f32_ubyte0_e32 v0, v61
	v_max_f32_e32 v120, 1.0, v0
	v_cvt_f32_ubyte1_e32 v0, v61
	v_max_f32_e32 v121, 1.0, v0
	v_cvt_f32_ubyte2_e32 v0, v61
	v_max_f32_e32 v122, 1.0, v0
	v_cvt_f32_ubyte3_e32 v0, v61
	v_max_f32_e32 v123, 1.0, v0
	v_cvt_f32_ubyte3_e32 v56, v57
	v_cvt_f32_ubyte0_e32 v0, v57
	v_pk_mul_f32 v[70:71], v[58:59], v[70:71]
	v_rcp_f32_e32 v57, v123
	s_nop 0
	v_mul_f32_e32 v57, v56, v57
	v_rcp_f32_e32 v56, v122
	s_nop 0
	v_mul_f32_e32 v56, v55, v56
	v_pk_mul_f32 v[56:57], v[56:57], v[88:89]
	v_rcp_f32_e32 v55, v121
	s_nop 0
	v_mul_f32_e32 v55, v54, v55
	v_rcp_f32_e32 v54, v120
	s_nop 0
	v_mul_f32_e32 v54, v0, v54
	v_cvt_f32_ubyte0_e32 v0, v18
	v_pk_mul_f32 v[54:55], v[54:55], v[86:87]
	v_max_f32_e32 v86, 1.0, v0
	v_cvt_f32_ubyte1_e32 v0, v18
	v_max_f32_e32 v87, 1.0, v0
	v_cvt_f32_ubyte2_e32 v0, v18
	v_max_f32_e32 v88, 1.0, v0
	v_cvt_f32_ubyte3_e32 v0, v18
	v_max_f32_e32 v89, 1.0, v0
	v_cvt_f32_ubyte0_e32 v0, v14
	v_cvt_f32_ubyte1_e32 v18, v14
	v_cvt_f32_ubyte2_e32 v58, v14
	v_cvt_f32_ubyte3_e32 v14, v14
	v_rcp_f32_e32 v59, v89
	s_nop 0
	v_mul_f32_e32 v61, v14, v59
	v_rcp_f32_e32 v14, v88
	s_nop 0
	v_mul_f32_e32 v60, v58, v14
	v_pk_mul_f32 v[60:61], v[60:61], v[84:85]
	v_rcp_f32_e32 v14, v87
	s_nop 0
	v_mul_f32_e32 v59, v18, v14
	v_rcp_f32_e32 v14, v86
	s_nop 0
	v_mul_f32_e32 v58, v0, v14
	v_cvt_f32_ubyte0_e32 v0, v19
	v_pk_mul_f32 v[58:59], v[58:59], v[82:83]
	v_max_f32_e32 v82, 1.0, v0
	v_cvt_f32_ubyte1_e32 v0, v19
	v_max_f32_e32 v83, 1.0, v0
	v_cvt_f32_ubyte2_e32 v0, v19
	v_max_f32_e32 v84, 1.0, v0
	v_cvt_f32_ubyte3_e32 v0, v19
	v_max_f32_e32 v85, 1.0, v0
	v_cvt_f32_ubyte0_e32 v0, v15
	v_cvt_f32_ubyte1_e32 v18, v15
	v_cvt_f32_ubyte2_e32 v14, v15
	v_cvt_f32_ubyte3_e32 v15, v15
	v_rcp_f32_e32 v19, v85
	s_nop 0
	v_mul_f32_e32 v15, v15, v19
	v_rcp_f32_e32 v19, v84
	s_nop 0
	v_mul_f32_e32 v14, v14, v19
	v_pk_mul_f32 v[80:81], v[14:15], v[80:81]
	v_cvt_f32_ubyte3_e32 v15, v16
	v_cvt_f32_ubyte2_e32 v14, v16
	v_rcp_f32_e32 v19, v83
	s_nop 0
	v_mul_f32_e32 v19, v18, v19
	v_rcp_f32_e32 v18, v82
	s_nop 0
	v_mul_f32_e32 v18, v0, v18
	v_cvt_f32_ubyte0_e32 v0, v20
	v_max_f32_e32 v124, 1.0, v0
	v_cvt_f32_ubyte1_e32 v0, v20
	v_max_f32_e32 v125, 1.0, v0
	v_cvt_f32_ubyte2_e32 v0, v20
	v_max_f32_e32 v126, 1.0, v0
	v_cvt_f32_ubyte3_e32 v0, v20
	v_max_f32_e32 v127, 1.0, v0
	v_pk_mul_f32 v[78:79], v[18:19], v[78:79]
	v_cvt_f32_ubyte0_e32 v0, v16
	v_cvt_f32_ubyte1_e32 v18, v16
	v_rcp_f32_e32 v16, v127
	s_nop 0
	v_mul_f32_e32 v15, v15, v16
	v_rcp_f32_e32 v16, v126
	s_nop 0
	v_mul_f32_e32 v14, v14, v16
	v_pk_mul_f32 v[76:77], v[14:15], v[76:77]
	v_cvt_f32_ubyte1_e32 v14, v17
	v_cvt_f32_ubyte2_e32 v15, v17
	v_rcp_f32_e32 v16, v125
	s_nop 0
	v_mul_f32_e32 v19, v18, v16
	v_rcp_f32_e32 v16, v124
	s_nop 0
	v_mul_f32_e32 v18, v0, v16
	v_cvt_f32_ubyte0_e32 v0, v21
	v_max_f32_e32 v128, 1.0, v0
	v_cvt_f32_ubyte1_e32 v0, v21
	v_max_f32_e32 v129, 1.0, v0
	v_cvt_f32_ubyte2_e32 v0, v21
	v_max_f32_e32 v130, 1.0, v0
	v_cvt_f32_ubyte3_e32 v0, v21
	v_max_f32_e32 v131, 1.0, v0
	v_cvt_f32_ubyte3_e32 v16, v17
	v_cvt_f32_ubyte0_e32 v0, v17
	v_pk_mul_f32 v[74:75], v[18:19], v[74:75]
	v_rcp_f32_e32 v17, v131
	s_nop 0
	v_mul_f32_e32 v17, v16, v17
	v_rcp_f32_e32 v16, v130
	s_nop 0
	v_mul_f32_e32 v16, v15, v16
	v_pk_mul_f32 v[16:17], v[16:17], v[68:69]
	v_rcp_f32_e32 v15, v129
	s_nop 0
	v_mul_f32_e32 v15, v14, v15
	v_rcp_f32_e32 v14, v128
	s_nop 0
	v_mul_f32_e32 v14, v0, v14
	v_cvt_f32_ubyte0_e32 v0, v6
	v_pk_mul_f32 v[14:15], v[14:15], v[66:67]
	v_max_f32_e32 v66, 1.0, v0
	v_cvt_f32_ubyte1_e32 v0, v6
	v_max_f32_e32 v67, 1.0, v0
	v_cvt_f32_ubyte2_e32 v0, v6
	v_max_f32_e32 v68, 1.0, v0
	v_cvt_f32_ubyte3_e32 v0, v6
	v_max_f32_e32 v69, 1.0, v0
	v_cvt_f32_ubyte0_e32 v0, v2
	v_cvt_f32_ubyte1_e32 v6, v2
	v_cvt_f32_ubyte2_e32 v18, v2
	v_cvt_f32_ubyte3_e32 v2, v2
	v_rcp_f32_e32 v19, v69
	s_nop 0
	v_mul_f32_e32 v21, v2, v19
	v_rcp_f32_e32 v2, v68
	s_nop 0
	v_mul_f32_e32 v20, v18, v2
	v_pk_mul_f32 v[20:21], v[20:21], v[52:53]
	v_rcp_f32_e32 v2, v67
	s_nop 0
	v_mul_f32_e32 v19, v6, v2
	v_rcp_f32_e32 v2, v66
	s_nop 0
	v_mul_f32_e32 v18, v0, v2
	v_cvt_f32_ubyte0_e32 v0, v7
	v_max_f32_e32 v52, 1.0, v0
; DI int tidx() { int t = __builtin_amdgcn_workitem_id_x(); asm volatile("" : "+v"(t)); return t; }
; DI void gemm_tile(const bf16_t* __restrict__ A, int lda, const bf16_t* __restrict__ Bt, int ldb, int bvalid, int K, f32x4 (&acc)[4][4], char* lds, bool preloaded = false) {
;   const int tid = tidx(), lane = tid & 63, wave = __builtin_amdgcn_readfirstlane(tid >> 6);
;   const int wm = wave >> 1, wn = wave & 1;
;   const int lr = tid >> 3, lc = tid & 7;
;   const int fr = lane & 15, fq = lane >> 4;
;   const int fx = (fr >> 1) & 7;
;   const bf16_t* ap = A + (size_t)lr * lda + ((lc ^ ((lr >> 1) & 7)) << 3);
;   const bf16_t* bp = Bt + ((lc ^ ((lr >> 1) & 7)) << 3);
;   typedef __attribute__((address_space(1))) const unsigned gptr_t;
;   typedef __attribute__((address_space(3))) unsigned lptr_t;
;   const unsigned lbase = (unsigned)(size_t)lds + (unsigned)tid * 16u;
;     ...
;   auto compute = [&](int st) {
;     const char* base = lds + st * 32768;
;     bf16x8 af[2][4], bfr[2][4];
; #pragma unroll
;     for (int s = 0; s < 2; ++s) {
;       const int ch = ((4 * s + fq) ^ fx) << 4;
; #pragma unroll
;       for (int mi = 0; mi < 4; ++mi) af[s][mi] = *(const bf16x8*)(base + (wm * 64 + mi * 16 + fr) * 128 + ch);
; #pragma unroll
;       for (int ni = 0; ni < 4; ++ni) bfr[s][ni] = *(const bf16x8*)(base + 16384 + (wn * 64 + ni * 16 + fr) * 128 + ch);
;     }
;     __builtin_amdgcn_s_setprio(1);
; #pragma unroll
;     for (int s = 0; s < 2; ++s)
; #pragma unroll
;       for (int mi = 0; mi < 4; ++mi)
; #pragma unroll
;         for (int ni = 0; ni < 4; ++ni) acc[mi][ni] = MFMA16(af[s][mi], bfr[s][ni], acc[mi][ni]);
;     __builtin_amdgcn_s_setprio(0);
;   };
;   const int nk = K >> 6;
;   if (!preloaded) { GLDS(0, 0) }
;   __syncthreads();
;   for (int kt = 0; kt < nk; ++kt) {
;     if (kt + 1 < nk) { GLDS((kt + 1) & 1, (kt + 1) << 6) }
; DI void phaseD_tile(const P& p, int layer, int mt, int nt, char* lds) {
;     ...
; #pragma unroll
;   for (int mi = 0; mi < 4; ++mi)
; #pragma unroll
;     for (int ni = 0; ni < 4; ++ni)
; #pragma unroll
;       for (int j = 0; j < 4; ++j) acc[mi][ni][j] *= (float)((gpv[mi][ni] >> (8 * j)) & 255u) / fmaxf((float)((gav[mi][ni] >> (8 * j)) & 255u), 1.f);
;   gemm_tile((const bf16_t*)(p.ws + W_ZA) + (size_t)row0 * 512, 512, (const bf16_t*)(p.ws + W_WAO) + ((size_t)layer * 1024 + col0) * 512, 512, 128, 512, acc, lds, true);
	v_cvt_f32_ubyte1_e32 v0, v7
	v_max_f32_e32 v53, 1.0, v0
	v_cvt_f32_ubyte2_e32 v0, v7
	v_max_f32_e32 v132, 1.0, v0
	v_cvt_f32_ubyte3_e32 v0, v7
	v_max_f32_e32 v133, 1.0, v0
	v_cvt_f32_ubyte0_e32 v0, v3
	v_cvt_f32_ubyte1_e32 v6, v3
	v_cvt_f32_ubyte2_e32 v2, v3
	v_cvt_f32_ubyte3_e32 v3, v3
	v_pk_mul_f32 v[18:19], v[18:19], v[50:51]
	v_rcp_f32_e32 v7, v133
	s_nop 0
	v_mul_f32_e32 v3, v3, v7
	v_rcp_f32_e32 v7, v132
	s_nop 0
	v_mul_f32_e32 v2, v2, v7
	v_pk_mul_f32 v[44:45], v[2:3], v[44:45]
	v_cvt_f32_ubyte3_e32 v3, v4
	v_cvt_f32_ubyte2_e32 v2, v4
	v_rcp_f32_e32 v7, v53
	s_nop 0
	v_mul_f32_e32 v7, v6, v7
	v_rcp_f32_e32 v6, v52
	s_nop 0
	v_mul_f32_e32 v6, v0, v6
	v_cvt_f32_ubyte0_e32 v0, v8
	v_max_f32_e32 v134, 1.0, v0
	v_cvt_f32_ubyte1_e32 v0, v8
	v_max_f32_e32 v135, 1.0, v0
	v_cvt_f32_ubyte2_e32 v0, v8
	v_max_f32_e32 v136, 1.0, v0
	v_cvt_f32_ubyte3_e32 v0, v8
	v_max_f32_e32 v137, 1.0, v0
	v_pk_mul_f32 v[42:43], v[6:7], v[42:43]
	v_cvt_f32_ubyte0_e32 v0, v4
	v_cvt_f32_ubyte1_e32 v6, v4
	v_rcp_f32_e32 v4, v137
	s_nop 0
	v_mul_f32_e32 v3, v3, v4
	v_rcp_f32_e32 v4, v136
	s_nop 0
	v_mul_f32_e32 v2, v2, v4
	v_pk_mul_f32 v[36:37], v[2:3], v[36:37]
	v_cvt_f32_ubyte1_e32 v2, v5
	v_cvt_f32_ubyte2_e32 v3, v5
	v_rcp_f32_e32 v4, v135
	s_nop 0
	v_mul_f32_e32 v7, v6, v4
	v_rcp_f32_e32 v4, v134
	s_nop 0
	v_mul_f32_e32 v6, v0, v4
	v_cvt_f32_ubyte0_e32 v0, v9
	v_max_f32_e32 v138, 1.0, v0
	v_cvt_f32_ubyte1_e32 v0, v9
	v_max_f32_e32 v139, 1.0, v0
	v_cvt_f32_ubyte2_e32 v0, v9
	v_max_f32_e32 v140, 1.0, v0
	v_cvt_f32_ubyte3_e32 v0, v9
	v_max_f32_e32 v141, 1.0, v0
	v_cvt_f32_ubyte3_e32 v4, v5
	v_cvt_f32_ubyte0_e32 v0, v5
	v_pk_mul_f32 v[34:35], v[6:7], v[34:35]
	v_rcp_f32_e32 v5, v141
	s_nop 0
	v_mul_f32_e32 v5, v4, v5
	v_rcp_f32_e32 v4, v140
	s_nop 0
	v_mul_f32_e32 v4, v3, v4
	v_pk_mul_f32 v[4:5], v[4:5], v[28:29]
	v_rcp_f32_e32 v3, v139
	s_nop 0
	v_mul_f32_e32 v3, v2, v3
	v_rcp_f32_e32 v2, v138
	s_nop 0
	v_mul_f32_e32 v2, v0, v2
	v_pk_mul_f32 v[2:3], v[2:3], v[26:27]
	v_mov_b32_e32 v26, v158
	s_waitcnt vmcnt(0) lgkmcnt(0)
	v_ashrrev_i32_e32 v8, 3, v26
	v_lshrrev_b32_e32 v0, 4, v26
	v_ashrrev_i32_e32 v9, 31, v8
	v_xor_b32_e32 v0, v0, v26
	v_lshlrev_b64 v[6:7], 10, v[8:9]
	v_lshlrev_b32_e32 v0, 4, v0
	v_readfirstlane_b32 s5, v26
	v_lshl_add_u64 v[6:7], s[10:11], 0, v[6:7]
	v_and_b32_e32 v0, 0x70, v0
	v_lshl_add_u64 v[6:7], v[6:7], 0, v[0:1]
	v_lshl_add_u64 v[50:51], s[8:9], 0, v[0:1]
	s_lshl_b32 s8, s5, 7
	v_lshlrev_b32_e32 v0, 7, v26
	s_lshl_b32 s5, s5, 6
	v_bfe_u32 v27, v26, 4, 2
	v_bfe_u32 v29, v26, 1, 3
	s_and_b32 s8, s8, 0x2000
	v_and_b32_e32 v0, 0x780, v0
	s_and_b32 s5, s5, 0xffffe000
	v_lshlrev_b32_e32 v156, 4, v26
	v_or_b32_e32 v157, s8, v0
	v_or_b32_e32 v179, s5, v0
	v_bitop3_b32 v0, v27, v29, 4 bitop3:0x36
	v_lshrrev_b32_e32 v28, 1, v26
	v_lshlrev_b32_e32 v220, 4, v0
	v_lshlrev_b32_e32 v0, 9, v8
	v_add_u32_e32 v143, 0x8000, v156
	v_bitop3_b32 v9, v28, v27, 7 bitop3:0x6c
	v_and_b32_e32 v26, 0xfe00, v0
	v_add_u32_e32 v8, 0x4000, v0
	v_bitop3_b32 v146, v0, s33, v167 bitop3:0x6c
	v_add_u32_e32 v0, 0xc000, v0
	v_readfirstlane_b32 s13, v143
	v_lshlrev_b32_e32 v145, 4, v9
	v_and_b32_e32 v28, 0xfe00, v8
	v_and_b32_e32 v148, 0xfe00, v0
	v_lshl_add_u64 v[8:9], v[6:7], 0, s[38:39]
	v_add_u32_e32 v142, 0xc000, v156
	s_mov_b32 m0, s13
	v_lshlrev_b32_e32 v0, 1, v26
	s_barrier
	global_load_lds_dwordx4 v[8:9], off
	v_lshl_add_u64 v[8:9], v[50:51], 0, v[0:1]
	v_readfirstlane_b32 s12, v142
	v_add_u32_e32 v144, 0x9000, v156
	v_lshl_add_u64 v[26:27], v[8:9], 0, s[38:39]
	s_mov_b32 m0, s12
	v_readfirstlane_b32 s21, v144
	global_load_lds_dwordx4 v[26:27], off
	v_lshl_add_u64 v[26:27], v[6:7], 0, s[58:59]
	s_mov_b32 m0, s21
	v_lshlrev_b32_e32 v0, 1, v28
	global_load_lds_dwordx4 v[26:27], off
	v_lshl_add_u64 v[26:27], v[50:51], 0, v[0:1]
	v_add_u32_e32 v0, 0xd000, v156
	v_lshl_add_u64 v[28:29], v[26:27], 0, s[38:39]
	v_readfirstlane_b32 s5, v0
	v_add_u32_e32 v0, 0xa000, v156
	s_mov_b32 m0, s5
	v_readfirstlane_b32 s8, v0
	global_load_lds_dwordx4 v[28:29], off
	v_lshl_add_u64 v[28:29], v[6:7], 0, s[62:63]
	s_mov_b32 m0, s8
	v_lshlrev_b32_e32 v0, 1, v146
	global_load_lds_dwordx4 v[28:29], off
	v_lshl_add_u64 v[28:29], v[50:51], 0, v[0:1]
	v_add_u32_e32 v0, 0xe000, v156
	v_lshl_add_u64 v[146:147], v[28:29], 0, s[38:39]
	v_readfirstlane_b32 s9, v0
	v_add_u32_e32 v0, 0xb000, v156
	s_mov_b32 m0, s9
	v_readfirstlane_b32 s10, v0
	v_lshlrev_b32_e32 v0, 1, v148
	v_lshl_add_u64 v[50:51], v[50:51], 0, v[0:1]
	v_add_u32_e32 v0, 0xf000, v156
	global_load_lds_dwordx4 v[146:147], off
	v_lshl_add_u64 v[146:147], v[6:7], 0, s[68:69]
	s_mov_b32 m0, s10
	v_readfirstlane_b32 s11, v0
	global_load_lds_dwordx4 v[146:147], off
	v_lshl_add_u64 v[146:147], v[50:51], 0, s[38:39]
	s_mov_b32 m0, s11
	v_or_b32_e32 v0, v145, v179
	global_load_lds_dwordx4 v[146:147], off
	v_or_b32_e32 v145, v145, v157
	v_or_b32_e32 v146, v220, v179
	v_or_b32_e32 v147, v220, v157
	ds_read_b128 v[148:151], v0
	ds_read_b128 v[152:155], v0 offset:2048
	ds_read_b128 v[180:183], v0 offset:4096
	ds_read_b128 v[184:187], v0 offset:6144
	ds_read_b128 v[188:191], v145 offset:16384
	ds_read_b128 v[192:195], v145 offset:18432
	ds_read_b128 v[196:199], v145 offset:20480
	ds_read_b128 v[200:203], v145 offset:22528
	ds_read_b128 v[204:207], v146
	ds_read_b128 v[208:211], v146 offset:2048
	ds_read_b128 v[212:215], v146 offset:4096
	ds_read_b128 v[216:219], v146 offset:6144
	ds_read_b128 v[220:223], v147 offset:16384
	ds_read_b128 v[224:227], v147 offset:18432
	ds_read_b128 v[228:231], v147 offset:20480
	ds_read_b128 v[232:235], v147 offset:22528
	s_setprio 1
	s_waitcnt lgkmcnt(0)
; #define MFMA16(a, b, c) __builtin_amdgcn_mfma_f32_16x16x32_bf16((a), (b), (c), 0, 0, 0)
; DI void gemm_tile(const bf16_t* __restrict__ A, int lda, const bf16_t* __restrict__ Bt, int ldb, int bvalid, int K, f32x4 (&acc)[4][4], char* lds, bool preloaded = false) {
;     ...
;   auto compute = [&](int st) {
;     const char* base = lds + st * 32768;
;     bf16x8 af[2][4], bfr[2][4];
; #pragma unroll
;     for (int s = 0; s < 2; ++s) {
;       const int ch = ((4 * s + fq) ^ fx) << 4;
; #pragma unroll
;       for (int mi = 0; mi < 4; ++mi) af[s][mi] = *(const bf16x8*)(base + (wm * 64 + mi * 16 + fr) * 128 + ch);
; #pragma unroll
;       for (int ni = 0; ni < 4; ++ni) bfr[s][ni] = *(const bf16x8*)(base + 16384 + (wn * 64 + ni * 16 + fr) * 128 + ch);
;     }
;     __builtin_amdgcn_s_setprio(1);
; #pragma unroll
;     for (int s = 0; s < 2; ++s)
; #pragma unroll
;       for (int mi = 0; mi < 4; ++mi)
; #pragma unroll
;         for (int ni = 0; ni < 4; ++ni) acc[mi][ni] = MFMA16(af[s][mi], bfr[s][ni], acc[mi][ni]);
;     __builtin_amdgcn_s_setprio(0);
;   };
;   const int nk = K >> 6;
;   if (!preloaded) { GLDS(0, 0) }
;   __syncthreads();
;   for (int kt = 0; kt < nk; ++kt) {
;     if (kt + 1 < nk) { GLDS((kt + 1) & 1, (kt + 1) << 6) }
;     compute(kt & 1);
;     __syncthreads();
	v_mfma_f32_16x16x32_bf16 v[2:5], v[184:187], v[200:203], v[2:5]
	v_mfma_f32_16x16x32_bf16 v[10:13], v[148:151], v[188:191], v[10:13]
	v_mfma_f32_16x16x32_bf16 v[22:25], v[148:151], v[192:195], v[22:25]
	v_mfma_f32_16x16x32_bf16 v[30:33], v[148:151], v[196:199], v[30:33]
	v_mfma_f32_16x16x32_bf16 v[38:41], v[148:151], v[200:203], v[38:41]
	v_mfma_f32_16x16x32_bf16 v[46:49], v[152:155], v[188:191], v[46:49]
	v_mfma_f32_16x16x32_bf16 v[62:65], v[152:155], v[192:195], v[62:65]
	v_mfma_f32_16x16x32_bf16 v[70:73], v[152:155], v[196:199], v[70:73]
	v_mfma_f32_16x16x32_bf16 v[54:57], v[152:155], v[200:203], v[54:57]
	v_mfma_f32_16x16x32_bf16 v[58:61], v[180:183], v[188:191], v[58:61]
	v_mfma_f32_16x16x32_bf16 v[78:81], v[180:183], v[192:195], v[78:81]
	v_mfma_f32_16x16x32_bf16 v[74:77], v[180:183], v[196:199], v[74:77]
	v_mfma_f32_16x16x32_bf16 v[14:17], v[180:183], v[200:203], v[14:17]
	v_mfma_f32_16x16x32_bf16 v[18:21], v[184:187], v[188:191], v[18:21]
	v_mfma_f32_16x16x32_bf16 v[42:45], v[184:187], v[192:195], v[42:45]
	v_mfma_f32_16x16x32_bf16 v[34:37], v[184:187], v[196:199], v[34:37]
	v_mfma_f32_16x16x32_bf16 v[2:5], v[216:219], v[232:235], v[2:5]
	v_mfma_f32_16x16x32_bf16 v[10:13], v[204:207], v[220:223], v[10:13]
	v_mfma_f32_16x16x32_bf16 v[22:25], v[204:207], v[224:227], v[22:25]
	v_mfma_f32_16x16x32_bf16 v[30:33], v[204:207], v[228:231], v[30:33]
	v_mfma_f32_16x16x32_bf16 v[38:41], v[204:207], v[232:235], v[38:41]
	v_mfma_f32_16x16x32_bf16 v[46:49], v[208:211], v[220:223], v[46:49]
	v_mfma_f32_16x16x32_bf16 v[62:65], v[208:211], v[224:227], v[62:65]
	v_mfma_f32_16x16x32_bf16 v[70:73], v[208:211], v[228:231], v[70:73]
	v_mfma_f32_16x16x32_bf16 v[54:57], v[208:211], v[232:235], v[54:57]
	v_mfma_f32_16x16x32_bf16 v[58:61], v[212:215], v[220:223], v[58:61]
	v_mfma_f32_16x16x32_bf16 v[78:81], v[212:215], v[224:227], v[78:81]
	v_mfma_f32_16x16x32_bf16 v[74:77], v[212:215], v[228:231], v[74:77]
	v_mfma_f32_16x16x32_bf16 v[14:17], v[212:215], v[232:235], v[14:17]
	v_mfma_f32_16x16x32_bf16 v[18:21], v[216:219], v[220:223], v[18:21]
	v_mfma_f32_16x16x32_bf16 v[42:45], v[216:219], v[224:227], v[42:45]
	v_mfma_f32_16x16x32_bf16 v[34:37], v[216:219], v[228:231], v[34:37]
	s_setprio 0
	v_add_u32_e32 v150, 0x4000, v156
	v_readfirstlane_b32 s25, v156
	v_lshl_add_u64 v[148:149], v[6:7], 0, s[30:31]
	s_mov_b32 m0, s25
	v_readfirstlane_b32 s22, v150
	v_add_u32_e32 v150, 0x1000, v156
	s_waitcnt vmcnt(0)
	s_barrier
	global_load_lds_dwordx4 v[148:149], off
	v_lshl_add_u64 v[148:149], v[8:9], 0, s[30:31]
	s_mov_b32 m0, s22
	v_readfirstlane_b32 s23, v150
	v_add_u32_e32 v150, 0x5000, v156
	global_load_lds_dwordx4 v[148:149], off
	v_lshl_add_u64 v[148:149], v[6:7], 0, s[70:71]
	s_mov_b32 m0, s23
	v_readfirstlane_b32 s24, v150
	v_add_u32_e32 v150, 0x2000, v156
	global_load_lds_dwordx4 v[148:149], off
	v_lshl_add_u64 v[148:149], v[26:27], 0, s[30:31]
	s_mov_b32 m0, s24
	v_readfirstlane_b32 s26, v150
	v_add_u32_e32 v150, 0x6000, v156
	global_load_lds_dwordx4 v[148:149], off
	v_lshl_add_u64 v[148:149], v[6:7], 0, s[92:93]
	s_mov_b32 m0, s26
	v_readfirstlane_b32 s27, v150
	global_load_lds_dwordx4 v[148:149], off
	v_lshl_add_u64 v[148:149], v[28:29], 0, s[30:31]
	s_mov_b32 m0, s27
	s_mov_b64 s[28:29], 0x18100
	v_add_u32_e32 v150, 0x3000, v156
	global_load_lds_dwordx4 v[148:149], off
	v_lshl_add_u64 v[148:149], v[6:7], 0, s[28:29]
	v_readfirstlane_b32 s28, v150
	v_add_u32_e32 v150, 0x7000, v156
	s_mov_b32 m0, s28
	v_readfirstlane_b32 s29, v150
	global_load_lds_dwordx4 v[148:149], off
	v_lshl_add_u64 v[148:149], v[50:51], 0, s[30:31]
	s_mov_b32 m0, s29
	s_nop 0
	global_load_lds_dwordx4 v[148:149], off
	ds_read_b128 v[148:151], v0 offset:32768
	ds_read_b128 v[152:155], v0 offset:34816
	ds_read_b128 v[180:183], v0 offset:36864
	ds_read_b128 v[184:187], v0 offset:38912
	ds_read_b128 v[188:191], v145 offset:49152
	ds_read_b128 v[192:195], v145 offset:51200
	ds_read_b128 v[196:199], v145 offset:53248
	ds_read_b128 v[200:203], v145 offset:55296
	ds_read_b128 v[204:207], v146 offset:32768
	ds_read_b128 v[208:211], v146 offset:34816
	ds_read_b128 v[212:215], v146 offset:36864
	ds_read_b128 v[216:219], v146 offset:38912
	ds_read_b128 v[220:223], v147 offset:49152
	ds_read_b128 v[224:227], v147 offset:51200
	ds_read_b128 v[228:231], v147 offset:53248
	ds_read_b128 v[232:235], v147 offset:55296
	s_setprio 1
	s_waitcnt lgkmcnt(0)
	v_mfma_f32_16x16x32_bf16 v[2:5], v[184:187], v[200:203], v[2:5]
	v_mfma_f32_16x16x32_bf16 v[10:13], v[148:151], v[188:191], v[10:13]
	v_mfma_f32_16x16x32_bf16 v[22:25], v[148:151], v[192:195], v[22:25]
	v_mfma_f32_16x16x32_bf16 v[30:33], v[148:151], v[196:199], v[30:33]
	v_mfma_f32_16x16x32_bf16 v[38:41], v[148:151], v[200:203], v[38:41]
	v_mfma_f32_16x16x32_bf16 v[46:49], v[152:155], v[188:191], v[46:49]
	v_mfma_f32_16x16x32_bf16 v[62:65], v[152:155], v[192:195], v[62:65]
	v_mfma_f32_16x16x32_bf16 v[70:73], v[152:155], v[196:199], v[70:73]
	v_mfma_f32_16x16x32_bf16 v[54:57], v[152:155], v[200:203], v[54:57]
	v_mfma_f32_16x16x32_bf16 v[58:61], v[180:183], v[188:191], v[58:61]
	v_mfma_f32_16x16x32_bf16 v[78:81], v[180:183], v[192:195], v[78:81]
	v_mfma_f32_16x16x32_bf16 v[74:77], v[180:183], v[196:199], v[74:77]
	v_mfma_f32_16x16x32_bf16 v[14:17], v[180:183], v[200:203], v[14:17]
	v_mfma_f32_16x16x32_bf16 v[18:21], v[184:187], v[188:191], v[18:21]
	v_mfma_f32_16x16x32_bf16 v[42:45], v[184:187], v[192:195], v[42:45]
	v_mfma_f32_16x16x32_bf16 v[34:37], v[184:187], v[196:199], v[34:37]
	v_mfma_f32_16x16x32_bf16 v[2:5], v[216:219], v[232:235], v[2:5]
	v_mfma_f32_16x16x32_bf16 v[10:13], v[204:207], v[220:223], v[10:13]
	v_mfma_f32_16x16x32_bf16 v[22:25], v[204:207], v[224:227], v[22:25]
	v_mfma_f32_16x16x32_bf16 v[30:33], v[204:207], v[228:231], v[30:33]
	v_mfma_f32_16x16x32_bf16 v[38:41], v[204:207], v[232:235], v[38:41]
	v_mfma_f32_16x16x32_bf16 v[46:49], v[208:211], v[220:223], v[46:49]
	v_mfma_f32_16x16x32_bf16 v[62:65], v[208:211], v[224:227], v[62:65]
	v_mfma_f32_16x16x32_bf16 v[70:73], v[208:211], v[228:231], v[70:73]
	v_mfma_f32_16x16x32_bf16 v[54:57], v[208:211], v[232:235], v[54:57]
	v_mfma_f32_16x16x32_bf16 v[58:61], v[212:215], v[220:223], v[58:61]
	v_mfma_f32_16x16x32_bf16 v[78:81], v[212:215], v[224:227], v[78:81]
	v_mfma_f32_16x16x32_bf16 v[74:77], v[212:215], v[228:231], v[74:77]
	v_mfma_f32_16x16x32_bf16 v[14:17], v[212:215], v[232:235], v[14:17]
	v_mfma_f32_16x16x32_bf16 v[18:21], v[216:219], v[220:223], v[18:21]
	v_mfma_f32_16x16x32_bf16 v[42:45], v[216:219], v[224:227], v[42:45]
	v_mfma_f32_16x16x32_bf16 v[34:37], v[216:219], v[228:231], v[34:37]
	s_setprio 0
	s_mov_b32 m0, s13
	v_lshl_add_u64 v[148:149], v[6:7], 0, s[0:1]
	s_waitcnt vmcnt(0)
	s_barrier
; #define MFMA16(a, b, c) __builtin_amdgcn_mfma_f32_16x16x32_bf16((a), (b), (c), 0, 0, 0)
; DI void gemm_tile(const bf16_t* __restrict__ A, int lda, const bf16_t* __restrict__ Bt, int ldb, int bvalid, int K, f32x4 (&acc)[4][4], char* lds, bool preloaded = false) {
;     ...
;   auto compute = [&](int st) {
;     const char* base = lds + st * 32768;
;     bf16x8 af[2][4], bfr[2][4];
; #pragma unroll
;     for (int s = 0; s < 2; ++s) {
;       const int ch = ((4 * s + fq) ^ fx) << 4;
; #pragma unroll
;       for (int mi = 0; mi < 4; ++mi) af[s][mi] = *(const bf16x8*)(base + (wm * 64 + mi * 16 + fr) * 128 + ch);
; #pragma unroll
;       for (int ni = 0; ni < 4; ++ni) bfr[s][ni] = *(const bf16x8*)(base + 16384 + (wn * 64 + ni * 16 + fr) * 128 + ch);
;     }
;     __builtin_amdgcn_s_setprio(1);
; #pragma unroll
;     for (int s = 0; s < 2; ++s)
; #pragma unroll
;       for (int mi = 0; mi < 4; ++mi)
; #pragma unroll
;         for (int ni = 0; ni < 4; ++ni) acc[mi][ni] = MFMA16(af[s][mi], bfr[s][ni], acc[mi][ni]);
;     __builtin_amdgcn_s_setprio(0);
;   };
;   const int nk = K >> 6;
;   if (!preloaded) { GLDS(0, 0) }
;   __syncthreads();
;   for (int kt = 0; kt < nk; ++kt) {
;     if (kt + 1 < nk) { GLDS((kt + 1) & 1, (kt + 1) << 6) }
;     compute(kt & 1);
;     __syncthreads();
	global_load_lds_dwordx4 v[148:149], off
	v_lshl_add_u64 v[148:149], v[8:9], 0, s[0:1]
	s_mov_b32 m0, s12
	s_mov_b64 s[30:31], 0x8180
	global_load_lds_dwordx4 v[148:149], off
	v_lshl_add_u64 v[148:149], v[6:7], 0, s[30:31]
	s_mov_b32 m0, s21
	s_mov_b64 s[30:31], 0x10180
	global_load_lds_dwordx4 v[148:149], off
	v_lshl_add_u64 v[148:149], v[26:27], 0, s[0:1]
	s_mov_b32 m0, s5
	s_nop 0
	global_load_lds_dwordx4 v[148:149], off
	v_lshl_add_u64 v[148:149], v[6:7], 0, s[30:31]
	s_mov_b32 m0, s8
	s_mov_b64 s[30:31], 0x18180
	global_load_lds_dwordx4 v[148:149], off
	v_lshl_add_u64 v[148:149], v[28:29], 0, s[0:1]
	s_mov_b32 m0, s9
	s_nop 0
	global_load_lds_dwordx4 v[148:149], off
	v_lshl_add_u64 v[148:149], v[6:7], 0, s[30:31]
	s_mov_b32 m0, s10
	s_nop 0
	global_load_lds_dwordx4 v[148:149], off
	v_lshl_add_u64 v[148:149], v[50:51], 0, s[0:1]
	s_mov_b32 m0, s11
	s_nop 0
	global_load_lds_dwordx4 v[148:149], off
	ds_read_b128 v[148:151], v0
	ds_read_b128 v[152:155], v0 offset:2048
	ds_read_b128 v[180:183], v0 offset:4096
	ds_read_b128 v[184:187], v0 offset:6144
	ds_read_b128 v[188:191], v145 offset:16384
	ds_read_b128 v[192:195], v145 offset:18432
	ds_read_b128 v[196:199], v145 offset:20480
	ds_read_b128 v[200:203], v145 offset:22528
	ds_read_b128 v[204:207], v146
	ds_read_b128 v[208:211], v146 offset:2048
	ds_read_b128 v[212:215], v146 offset:4096
	ds_read_b128 v[216:219], v146 offset:6144
	ds_read_b128 v[220:223], v147 offset:16384
	ds_read_b128 v[224:227], v147 offset:18432
	ds_read_b128 v[228:231], v147 offset:20480
	ds_read_b128 v[232:235], v147 offset:22528
	s_setprio 1
	s_waitcnt lgkmcnt(0)
	v_mfma_f32_16x16x32_bf16 v[2:5], v[184:187], v[200:203], v[2:5]
	v_mfma_f32_16x16x32_bf16 v[10:13], v[148:151], v[188:191], v[10:13]
	v_mfma_f32_16x16x32_bf16 v[22:25], v[148:151], v[192:195], v[22:25]
	v_mfma_f32_16x16x32_bf16 v[30:33], v[148:151], v[196:199], v[30:33]
	v_mfma_f32_16x16x32_bf16 v[38:41], v[148:151], v[200:203], v[38:41]
	v_mfma_f32_16x16x32_bf16 v[46:49], v[152:155], v[188:191], v[46:49]
	v_mfma_f32_16x16x32_bf16 v[62:65], v[152:155], v[192:195], v[62:65]
	v_mfma_f32_16x16x32_bf16 v[70:73], v[152:155], v[196:199], v[70:73]
	v_mfma_f32_16x16x32_bf16 v[54:57], v[152:155], v[200:203], v[54:57]
	v_mfma_f32_16x16x32_bf16 v[58:61], v[180:183], v[188:191], v[58:61]
	v_mfma_f32_16x16x32_bf16 v[78:81], v[180:183], v[192:195], v[78:81]
	v_mfma_f32_16x16x32_bf16 v[74:77], v[180:183], v[196:199], v[74:77]
	v_mfma_f32_16x16x32_bf16 v[14:17], v[180:183], v[200:203], v[14:17]
	v_mfma_f32_16x16x32_bf16 v[18:21], v[184:187], v[188:191], v[18:21]
	v_mfma_f32_16x16x32_bf16 v[42:45], v[184:187], v[192:195], v[42:45]
	v_mfma_f32_16x16x32_bf16 v[34:37], v[184:187], v[196:199], v[34:37]
	v_mfma_f32_16x16x32_bf16 v[2:5], v[216:219], v[232:235], v[2:5]
	v_mfma_f32_16x16x32_bf16 v[10:13], v[204:207], v[220:223], v[10:13]
	v_mfma_f32_16x16x32_bf16 v[22:25], v[204:207], v[224:227], v[22:25]
	v_mfma_f32_16x16x32_bf16 v[30:33], v[204:207], v[228:231], v[30:33]
	v_mfma_f32_16x16x32_bf16 v[38:41], v[204:207], v[232:235], v[38:41]
	v_mfma_f32_16x16x32_bf16 v[46:49], v[208:211], v[220:223], v[46:49]
	v_mfma_f32_16x16x32_bf16 v[62:65], v[208:211], v[224:227], v[62:65]
	v_mfma_f32_16x16x32_bf16 v[70:73], v[208:211], v[228:231], v[70:73]
	v_mfma_f32_16x16x32_bf16 v[54:57], v[208:211], v[232:235], v[54:57]
	v_mfma_f32_16x16x32_bf16 v[58:61], v[212:215], v[220:223], v[58:61]
	v_mfma_f32_16x16x32_bf16 v[78:81], v[212:215], v[224:227], v[78:81]
	v_mfma_f32_16x16x32_bf16 v[74:77], v[212:215], v[228:231], v[74:77]
	v_mfma_f32_16x16x32_bf16 v[14:17], v[212:215], v[232:235], v[14:17]
	v_mfma_f32_16x16x32_bf16 v[18:21], v[216:219], v[220:223], v[18:21]
	v_mfma_f32_16x16x32_bf16 v[42:45], v[216:219], v[224:227], v[42:45]
	v_mfma_f32_16x16x32_bf16 v[34:37], v[216:219], v[228:231], v[34:37]
	s_setprio 0
	s_mov_b32 m0, s25
	v_lshl_add_u64 v[148:149], v[6:7], 0, s[36:37]
	s_waitcnt vmcnt(0)
	s_barrier
	global_load_lds_dwordx4 v[148:149], off
	v_lshl_add_u64 v[148:149], v[8:9], 0, s[36:37]
	s_mov_b32 m0, s22
	s_mov_b64 s[0:1], 0x8200
	global_load_lds_dwordx4 v[148:149], off
	v_lshl_add_u64 v[148:149], v[6:7], 0, s[0:1]
	s_mov_b32 m0, s23
	s_mov_b64 s[0:1], 0x10200
	global_load_lds_dwordx4 v[148:149], off
	v_lshl_add_u64 v[148:149], v[26:27], 0, s[36:37]
	s_mov_b32 m0, s24
	s_nop 0
	global_load_lds_dwordx4 v[148:149], off
	v_lshl_add_u64 v[148:149], v[6:7], 0, s[0:1]
	s_mov_b32 m0, s26
	s_mov_b64 s[0:1], 0x18200
	global_load_lds_dwordx4 v[148:149], off
	v_lshl_add_u64 v[148:149], v[28:29], 0, s[36:37]
	s_mov_b32 m0, s27
	s_nop 0
	global_load_lds_dwordx4 v[148:149], off
	v_lshl_add_u64 v[148:149], v[6:7], 0, s[0:1]
	s_mov_b32 m0, s28
	s_nop 0
	global_load_lds_dwordx4 v[148:149], off
	v_lshl_add_u64 v[148:149], v[50:51], 0, s[36:37]
	s_mov_b32 m0, s29
	s_nop 0
	global_load_lds_dwordx4 v[148:149], off
	ds_read_b128 v[148:151], v0 offset:32768
	ds_read_b128 v[152:155], v0 offset:34816
	ds_read_b128 v[180:183], v0 offset:36864
	ds_read_b128 v[184:187], v0 offset:38912
	ds_read_b128 v[188:191], v145 offset:49152
	ds_read_b128 v[192:195], v145 offset:51200
	ds_read_b128 v[196:199], v145 offset:53248
	ds_read_b128 v[200:203], v145 offset:55296
	ds_read_b128 v[204:207], v146 offset:32768
	ds_read_b128 v[208:211], v146 offset:34816
	ds_read_b128 v[212:215], v146 offset:36864
	ds_read_b128 v[216:219], v146 offset:38912
	ds_read_b128 v[220:223], v147 offset:49152
	ds_read_b128 v[224:227], v147 offset:51200
	ds_read_b128 v[228:231], v147 offset:53248
	ds_read_b128 v[232:235], v147 offset:55296
	s_setprio 1
	s_waitcnt lgkmcnt(0)
; #define MFMA16(a, b, c) __builtin_amdgcn_mfma_f32_16x16x32_bf16((a), (b), (c), 0, 0, 0)
; DI void gemm_tile(const bf16_t* __restrict__ A, int lda, const bf16_t* __restrict__ Bt, int ldb, int bvalid, int K, f32x4 (&acc)[4][4], char* lds, bool preloaded = false) {
;     ...
;   auto compute = [&](int st) {
;     const char* base = lds + st * 32768;
;     bf16x8 af[2][4], bfr[2][4];
; #pragma unroll
;     for (int s = 0; s < 2; ++s) {
;       const int ch = ((4 * s + fq) ^ fx) << 4;
; #pragma unroll
;       for (int mi = 0; mi < 4; ++mi) af[s][mi] = *(const bf16x8*)(base + (wm * 64 + mi * 16 + fr) * 128 + ch);
; #pragma unroll
;       for (int ni = 0; ni < 4; ++ni) bfr[s][ni] = *(const bf16x8*)(base + 16384 + (wn * 64 + ni * 16 + fr) * 128 + ch);
;     }
;     __builtin_amdgcn_s_setprio(1);
; #pragma unroll
;     for (int s = 0; s < 2; ++s)
; #pragma unroll
;       for (int mi = 0; mi < 4; ++mi)
; #pragma unroll
;         for (int ni = 0; ni < 4; ++ni) acc[mi][ni] = MFMA16(af[s][mi], bfr[s][ni], acc[mi][ni]);
;     __builtin_amdgcn_s_setprio(0);
;   };
;   const int nk = K >> 6;
;   if (!preloaded) { GLDS(0, 0) }
;   __syncthreads();
;   for (int kt = 0; kt < nk; ++kt) {
;     if (kt + 1 < nk) { GLDS((kt + 1) & 1, (kt + 1) << 6) }
;     compute(kt & 1);
;     __syncthreads();
	v_mfma_f32_16x16x32_bf16 v[2:5], v[184:187], v[200:203], v[2:5]
	v_mfma_f32_16x16x32_bf16 v[10:13], v[148:151], v[188:191], v[10:13]
	v_mfma_f32_16x16x32_bf16 v[22:25], v[148:151], v[192:195], v[22:25]
	v_mfma_f32_16x16x32_bf16 v[30:33], v[148:151], v[196:199], v[30:33]
	v_mfma_f32_16x16x32_bf16 v[38:41], v[148:151], v[200:203], v[38:41]
	v_mfma_f32_16x16x32_bf16 v[46:49], v[152:155], v[188:191], v[46:49]
	v_mfma_f32_16x16x32_bf16 v[62:65], v[152:155], v[192:195], v[62:65]
	v_mfma_f32_16x16x32_bf16 v[70:73], v[152:155], v[196:199], v[70:73]
	v_mfma_f32_16x16x32_bf16 v[54:57], v[152:155], v[200:203], v[54:57]
	v_mfma_f32_16x16x32_bf16 v[58:61], v[180:183], v[188:191], v[58:61]
	v_mfma_f32_16x16x32_bf16 v[78:81], v[180:183], v[192:195], v[78:81]
	v_mfma_f32_16x16x32_bf16 v[74:77], v[180:183], v[196:199], v[74:77]
	v_mfma_f32_16x16x32_bf16 v[14:17], v[180:183], v[200:203], v[14:17]
	v_mfma_f32_16x16x32_bf16 v[18:21], v[184:187], v[188:191], v[18:21]
	v_mfma_f32_16x16x32_bf16 v[42:45], v[184:187], v[192:195], v[42:45]
	v_mfma_f32_16x16x32_bf16 v[34:37], v[184:187], v[196:199], v[34:37]
	v_mfma_f32_16x16x32_bf16 v[2:5], v[216:219], v[232:235], v[2:5]
	v_mfma_f32_16x16x32_bf16 v[10:13], v[204:207], v[220:223], v[10:13]
	v_mfma_f32_16x16x32_bf16 v[22:25], v[204:207], v[224:227], v[22:25]
	v_mfma_f32_16x16x32_bf16 v[30:33], v[204:207], v[228:231], v[30:33]
	v_mfma_f32_16x16x32_bf16 v[38:41], v[204:207], v[232:235], v[38:41]
	v_mfma_f32_16x16x32_bf16 v[46:49], v[208:211], v[220:223], v[46:49]
	v_mfma_f32_16x16x32_bf16 v[62:65], v[208:211], v[224:227], v[62:65]
	v_mfma_f32_16x16x32_bf16 v[70:73], v[208:211], v[228:231], v[70:73]
	v_mfma_f32_16x16x32_bf16 v[54:57], v[208:211], v[232:235], v[54:57]
	v_mfma_f32_16x16x32_bf16 v[58:61], v[212:215], v[220:223], v[58:61]
	v_mfma_f32_16x16x32_bf16 v[78:81], v[212:215], v[224:227], v[78:81]
	v_mfma_f32_16x16x32_bf16 v[74:77], v[212:215], v[228:231], v[74:77]
	v_mfma_f32_16x16x32_bf16 v[14:17], v[212:215], v[232:235], v[14:17]
	v_mfma_f32_16x16x32_bf16 v[18:21], v[216:219], v[220:223], v[18:21]
	v_mfma_f32_16x16x32_bf16 v[42:45], v[216:219], v[224:227], v[42:45]
	v_mfma_f32_16x16x32_bf16 v[34:37], v[216:219], v[228:231], v[34:37]
	s_setprio 0
	s_mov_b32 m0, s13
	v_lshl_add_u64 v[148:149], v[6:7], 0, s[2:3]
	s_waitcnt vmcnt(0)
	s_barrier
	global_load_lds_dwordx4 v[148:149], off
	v_lshl_add_u64 v[148:149], v[8:9], 0, s[2:3]
	s_mov_b32 m0, s12
	s_mov_b64 s[0:1], 0x8280
	global_load_lds_dwordx4 v[148:149], off
	v_lshl_add_u64 v[148:149], v[6:7], 0, s[0:1]
	s_mov_b32 m0, s21
	s_mov_b64 s[0:1], 0x10280
	global_load_lds_dwordx4 v[148:149], off
	v_lshl_add_u64 v[148:149], v[26:27], 0, s[2:3]
	s_mov_b32 m0, s5
	s_nop 0
	global_load_lds_dwordx4 v[148:149], off
	v_lshl_add_u64 v[148:149], v[6:7], 0, s[0:1]
	s_mov_b32 m0, s8
	s_mov_b64 s[0:1], 0x18280
	global_load_lds_dwordx4 v[148:149], off
	v_lshl_add_u64 v[148:149], v[28:29], 0, s[2:3]
	s_mov_b32 m0, s9
	s_nop 0
	global_load_lds_dwordx4 v[148:149], off
	v_lshl_add_u64 v[148:149], v[6:7], 0, s[0:1]
	s_mov_b32 m0, s10
	s_nop 0
	global_load_lds_dwordx4 v[148:149], off
	v_lshl_add_u64 v[148:149], v[50:51], 0, s[2:3]
	s_mov_b32 m0, s11
	s_nop 0
	global_load_lds_dwordx4 v[148:149], off
	ds_read_b128 v[148:151], v0
	ds_read_b128 v[152:155], v0 offset:2048
	ds_read_b128 v[180:183], v0 offset:4096
	ds_read_b128 v[184:187], v0 offset:6144
	ds_read_b128 v[188:191], v145 offset:16384
	ds_read_b128 v[192:195], v145 offset:18432
	ds_read_b128 v[196:199], v145 offset:20480
	ds_read_b128 v[200:203], v145 offset:22528
	ds_read_b128 v[204:207], v146
	ds_read_b128 v[208:211], v146 offset:2048
	ds_read_b128 v[212:215], v146 offset:4096
	ds_read_b128 v[216:219], v146 offset:6144
	ds_read_b128 v[220:223], v147 offset:16384
	ds_read_b128 v[224:227], v147 offset:18432
	ds_read_b128 v[228:231], v147 offset:20480
	ds_read_b128 v[232:235], v147 offset:22528
	s_setprio 1
	s_waitcnt lgkmcnt(0)
	v_mfma_f32_16x16x32_bf16 v[2:5], v[184:187], v[200:203], v[2:5]
	v_mfma_f32_16x16x32_bf16 v[10:13], v[148:151], v[188:191], v[10:13]
	v_mfma_f32_16x16x32_bf16 v[22:25], v[148:151], v[192:195], v[22:25]
	v_mfma_f32_16x16x32_bf16 v[30:33], v[148:151], v[196:199], v[30:33]
	v_mfma_f32_16x16x32_bf16 v[38:41], v[148:151], v[200:203], v[38:41]
	v_mfma_f32_16x16x32_bf16 v[46:49], v[152:155], v[188:191], v[46:49]
	v_mfma_f32_16x16x32_bf16 v[62:65], v[152:155], v[192:195], v[62:65]
	v_mfma_f32_16x16x32_bf16 v[70:73], v[152:155], v[196:199], v[70:73]
	v_mfma_f32_16x16x32_bf16 v[54:57], v[152:155], v[200:203], v[54:57]
	v_mfma_f32_16x16x32_bf16 v[58:61], v[180:183], v[188:191], v[58:61]
	v_mfma_f32_16x16x32_bf16 v[78:81], v[180:183], v[192:195], v[78:81]
	v_mfma_f32_16x16x32_bf16 v[74:77], v[180:183], v[196:199], v[74:77]
	v_mfma_f32_16x16x32_bf16 v[14:17], v[180:183], v[200:203], v[14:17]
	v_mfma_f32_16x16x32_bf16 v[18:21], v[184:187], v[188:191], v[18:21]
	v_mfma_f32_16x16x32_bf16 v[42:45], v[184:187], v[192:195], v[42:45]
	v_mfma_f32_16x16x32_bf16 v[34:37], v[184:187], v[196:199], v[34:37]
	v_mfma_f32_16x16x32_bf16 v[2:5], v[216:219], v[232:235], v[2:5]
	v_mfma_f32_16x16x32_bf16 v[10:13], v[204:207], v[220:223], v[10:13]
	v_mfma_f32_16x16x32_bf16 v[22:25], v[204:207], v[224:227], v[22:25]
	v_mfma_f32_16x16x32_bf16 v[30:33], v[204:207], v[228:231], v[30:33]
	v_mfma_f32_16x16x32_bf16 v[38:41], v[204:207], v[232:235], v[38:41]
	v_mfma_f32_16x16x32_bf16 v[46:49], v[208:211], v[220:223], v[46:49]
	v_mfma_f32_16x16x32_bf16 v[62:65], v[208:211], v[224:227], v[62:65]
	v_mfma_f32_16x16x32_bf16 v[70:73], v[208:211], v[228:231], v[70:73]
	v_mfma_f32_16x16x32_bf16 v[54:57], v[208:211], v[232:235], v[54:57]
	v_mfma_f32_16x16x32_bf16 v[58:61], v[212:215], v[220:223], v[58:61]
	v_mfma_f32_16x16x32_bf16 v[78:81], v[212:215], v[224:227], v[78:81]
	v_mfma_f32_16x16x32_bf16 v[74:77], v[212:215], v[228:231], v[74:77]
	v_mfma_f32_16x16x32_bf16 v[14:17], v[212:215], v[232:235], v[14:17]
	v_mfma_f32_16x16x32_bf16 v[18:21], v[216:219], v[220:223], v[18:21]
	v_mfma_f32_16x16x32_bf16 v[42:45], v[216:219], v[224:227], v[42:45]
	v_mfma_f32_16x16x32_bf16 v[34:37], v[216:219], v[228:231], v[34:37]
	s_setprio 0
	s_mov_b32 m0, s25
	v_lshl_add_u64 v[148:149], v[6:7], 0, s[14:15]
	s_waitcnt vmcnt(0)
	s_barrier
; #define MFMA16(a, b, c) __builtin_amdgcn_mfma_f32_16x16x32_bf16((a), (b), (c), 0, 0, 0)
; DI void gemm_tile(const bf16_t* __restrict__ A, int lda, const bf16_t* __restrict__ Bt, int ldb, int bvalid, int K, f32x4 (&acc)[4][4], char* lds, bool preloaded = false) {
;     ...
;   auto compute = [&](int st) {
;     const char* base = lds + st * 32768;
;     bf16x8 af[2][4], bfr[2][4];
; #pragma unroll
;     for (int s = 0; s < 2; ++s) {
;       const int ch = ((4 * s + fq) ^ fx) << 4;
; #pragma unroll
;       for (int mi = 0; mi < 4; ++mi) af[s][mi] = *(const bf16x8*)(base + (wm * 64 + mi * 16 + fr) * 128 + ch);
; #pragma unroll
;       for (int ni = 0; ni < 4; ++ni) bfr[s][ni] = *(const bf16x8*)(base + 16384 + (wn * 64 + ni * 16 + fr) * 128 + ch);
;     }
;     __builtin_amdgcn_s_setprio(1);
; #pragma unroll
;     for (int s = 0; s < 2; ++s)
; #pragma unroll
;       for (int mi = 0; mi < 4; ++mi)
; #pragma unroll
;         for (int ni = 0; ni < 4; ++ni) acc[mi][ni] = MFMA16(af[s][mi], bfr[s][ni], acc[mi][ni]);
;     __builtin_amdgcn_s_setprio(0);
;   };
;   const int nk = K >> 6;
;   if (!preloaded) { GLDS(0, 0) }
;   __syncthreads();
;   for (int kt = 0; kt < nk; ++kt) {
;     if (kt + 1 < nk) { GLDS((kt + 1) & 1, (kt + 1) << 6) }
;     compute(kt & 1);
;     __syncthreads();
	global_load_lds_dwordx4 v[148:149], off
	v_lshl_add_u64 v[148:149], v[8:9], 0, s[14:15]
	s_mov_b32 m0, s22
	s_mov_b64 s[0:1], 0x8300
	global_load_lds_dwordx4 v[148:149], off
	v_lshl_add_u64 v[148:149], v[6:7], 0, s[0:1]
	s_mov_b32 m0, s23
	s_mov_b64 s[0:1], 0x10300
	global_load_lds_dwordx4 v[148:149], off
	v_lshl_add_u64 v[148:149], v[26:27], 0, s[14:15]
	s_mov_b32 m0, s24
	s_nop 0
	global_load_lds_dwordx4 v[148:149], off
	v_lshl_add_u64 v[148:149], v[6:7], 0, s[0:1]
	s_mov_b32 m0, s26
	s_mov_b64 s[0:1], 0x18300
	global_load_lds_dwordx4 v[148:149], off
	v_lshl_add_u64 v[148:149], v[28:29], 0, s[14:15]
	s_mov_b32 m0, s27
	s_nop 0
	global_load_lds_dwordx4 v[148:149], off
	v_lshl_add_u64 v[148:149], v[6:7], 0, s[0:1]
	s_mov_b32 m0, s28
	s_nop 0
	global_load_lds_dwordx4 v[148:149], off
	v_lshl_add_u64 v[148:149], v[50:51], 0, s[14:15]
	s_mov_b32 m0, s29
	s_nop 0
	global_load_lds_dwordx4 v[148:149], off
	ds_read_b128 v[148:151], v0 offset:32768
	ds_read_b128 v[152:155], v0 offset:34816
	ds_read_b128 v[180:183], v0 offset:36864
	ds_read_b128 v[184:187], v0 offset:38912
	ds_read_b128 v[188:191], v145 offset:49152
	ds_read_b128 v[192:195], v145 offset:51200
	ds_read_b128 v[196:199], v145 offset:53248
	ds_read_b128 v[200:203], v145 offset:55296
	ds_read_b128 v[204:207], v146 offset:32768
	ds_read_b128 v[208:211], v146 offset:34816
	ds_read_b128 v[212:215], v146 offset:36864
	ds_read_b128 v[216:219], v146 offset:38912
	ds_read_b128 v[220:223], v147 offset:49152
	ds_read_b128 v[224:227], v147 offset:51200
	ds_read_b128 v[228:231], v147 offset:53248
	ds_read_b128 v[232:235], v147 offset:55296
	s_setprio 1
	s_waitcnt lgkmcnt(0)
	v_mfma_f32_16x16x32_bf16 v[2:5], v[184:187], v[200:203], v[2:5]
	v_mfma_f32_16x16x32_bf16 v[10:13], v[148:151], v[188:191], v[10:13]
	v_mfma_f32_16x16x32_bf16 v[22:25], v[148:151], v[192:195], v[22:25]
	v_mfma_f32_16x16x32_bf16 v[30:33], v[148:151], v[196:199], v[30:33]
	v_mfma_f32_16x16x32_bf16 v[38:41], v[148:151], v[200:203], v[38:41]
	v_mfma_f32_16x16x32_bf16 v[46:49], v[152:155], v[188:191], v[46:49]
	v_mfma_f32_16x16x32_bf16 v[62:65], v[152:155], v[192:195], v[62:65]
	v_mfma_f32_16x16x32_bf16 v[70:73], v[152:155], v[196:199], v[70:73]
	v_mfma_f32_16x16x32_bf16 v[54:57], v[152:155], v[200:203], v[54:57]
	v_mfma_f32_16x16x32_bf16 v[58:61], v[180:183], v[188:191], v[58:61]
	v_mfma_f32_16x16x32_bf16 v[78:81], v[180:183], v[192:195], v[78:81]
	v_mfma_f32_16x16x32_bf16 v[74:77], v[180:183], v[196:199], v[74:77]
	v_mfma_f32_16x16x32_bf16 v[14:17], v[180:183], v[200:203], v[14:17]
	v_mfma_f32_16x16x32_bf16 v[18:21], v[184:187], v[188:191], v[18:21]
	v_mfma_f32_16x16x32_bf16 v[42:45], v[184:187], v[192:195], v[42:45]
	v_mfma_f32_16x16x32_bf16 v[34:37], v[184:187], v[196:199], v[34:37]
	v_mfma_f32_16x16x32_bf16 v[2:5], v[216:219], v[232:235], v[2:5]
	v_mfma_f32_16x16x32_bf16 v[10:13], v[204:207], v[220:223], v[10:13]
	v_mfma_f32_16x16x32_bf16 v[22:25], v[204:207], v[224:227], v[22:25]
	v_mfma_f32_16x16x32_bf16 v[30:33], v[204:207], v[228:231], v[30:33]
	v_mfma_f32_16x16x32_bf16 v[38:41], v[204:207], v[232:235], v[38:41]
	v_mfma_f32_16x16x32_bf16 v[46:49], v[208:211], v[220:223], v[46:49]
	v_mfma_f32_16x16x32_bf16 v[62:65], v[208:211], v[224:227], v[62:65]
	v_mfma_f32_16x16x32_bf16 v[70:73], v[208:211], v[228:231], v[70:73]
	v_mfma_f32_16x16x32_bf16 v[54:57], v[208:211], v[232:235], v[54:57]
	v_mfma_f32_16x16x32_bf16 v[58:61], v[212:215], v[220:223], v[58:61]
	v_mfma_f32_16x16x32_bf16 v[78:81], v[212:215], v[224:227], v[78:81]
	v_mfma_f32_16x16x32_bf16 v[74:77], v[212:215], v[228:231], v[74:77]
	v_mfma_f32_16x16x32_bf16 v[14:17], v[212:215], v[232:235], v[14:17]
	v_mfma_f32_16x16x32_bf16 v[18:21], v[216:219], v[220:223], v[18:21]
	v_mfma_f32_16x16x32_bf16 v[42:45], v[216:219], v[224:227], v[42:45]
	v_mfma_f32_16x16x32_bf16 v[34:37], v[216:219], v[228:231], v[34:37]
	s_setprio 0
	v_readfirstlane_b32 s12, v143
	v_lshl_add_u64 v[148:149], v[6:7], 0, s[64:65]
	s_mov_b32 m0, s12
	v_readfirstlane_b32 s12, v142
	s_waitcnt vmcnt(0)
	s_barrier
	global_load_lds_dwordx4 v[148:149], off
	v_lshl_add_u64 v[8:9], v[8:9], 0, s[64:65]
	s_mov_b32 m0, s12
	s_mov_b64 s[0:1], 0x8380
	v_readfirstlane_b32 s12, v144
	global_load_lds_dwordx4 v[8:9], off
	v_lshl_add_u64 v[8:9], v[6:7], 0, s[0:1]
	s_mov_b32 m0, s12
	s_mov_b64 s[0:1], 0x10380
	global_load_lds_dwordx4 v[8:9], off
	v_lshl_add_u64 v[8:9], v[26:27], 0, s[64:65]
	s_mov_b32 m0, s5
	s_nop 0
	global_load_lds_dwordx4 v[8:9], off
	v_lshl_add_u64 v[8:9], v[6:7], 0, s[0:1]
	s_mov_b32 m0, s8
	s_mov_b64 s[0:1], 0x18380
	global_load_lds_dwordx4 v[8:9], off
	v_lshl_add_u64 v[8:9], v[28:29], 0, s[64:65]
	s_mov_b32 m0, s9
	v_lshl_add_u64 v[6:7], v[6:7], 0, s[0:1]
	global_load_lds_dwordx4 v[8:9], off
	s_mov_b32 m0, s10
	s_nop 0
	global_load_lds_dwordx4 v[6:7], off
	v_lshl_add_u64 v[6:7], v[50:51], 0, s[64:65]
	s_mov_b32 m0, s11
	s_nop 0
	global_load_lds_dwordx4 v[6:7], off
	ds_read_b128 v[6:9], v0
	ds_read_b128 v[26:29], v0 offset:2048
	ds_read_b128 v[148:151], v0 offset:4096
	ds_read_b128 v[152:155], v0 offset:6144
	ds_read_b128 v[180:183], v145 offset:16384
	ds_read_b128 v[184:187], v145 offset:18432
	ds_read_b128 v[188:191], v145 offset:20480
	ds_read_b128 v[192:195], v145 offset:22528
	ds_read_b128 v[196:199], v146
	ds_read_b128 v[200:203], v146 offset:2048
	ds_read_b128 v[204:207], v146 offset:4096
	ds_read_b128 v[208:211], v146 offset:6144
	ds_read_b128 v[212:215], v147 offset:16384
	ds_read_b128 v[216:219], v147 offset:18432
	ds_read_b128 v[220:223], v147 offset:20480
	ds_read_b128 v[224:227], v147 offset:22528
	s_setprio 1
	s_waitcnt lgkmcnt(0)
; #define MFMA16(a, b, c) __builtin_amdgcn_mfma_f32_16x16x32_bf16((a), (b), (c), 0, 0, 0)
; DI void gemm_tile(const bf16_t* __restrict__ A, int lda, const bf16_t* __restrict__ Bt, int ldb, int bvalid, int K, f32x4 (&acc)[4][4], char* lds, bool preloaded = false) {
;     ...
;   auto compute = [&](int st) {
;     const char* base = lds + st * 32768;
;     bf16x8 af[2][4], bfr[2][4];
; #pragma unroll
;     for (int s = 0; s < 2; ++s) {
;       const int ch = ((4 * s + fq) ^ fx) << 4;
; #pragma unroll
;       for (int mi = 0; mi < 4; ++mi) af[s][mi] = *(const bf16x8*)(base + (wm * 64 + mi * 16 + fr) * 128 + ch);
; #pragma unroll
;       for (int ni = 0; ni < 4; ++ni) bfr[s][ni] = *(const bf16x8*)(base + 16384 + (wn * 64 + ni * 16 + fr) * 128 + ch);
;     }
;     __builtin_amdgcn_s_setprio(1);
; #pragma unroll
;     for (int s = 0; s < 2; ++s)
; #pragma unroll
;       for (int mi = 0; mi < 4; ++mi)
; #pragma unroll
;         for (int ni = 0; ni < 4; ++ni) acc[mi][ni] = MFMA16(af[s][mi], bfr[s][ni], acc[mi][ni]);
;     __builtin_amdgcn_s_setprio(0);
;   };
;   const int nk = K >> 6;
;   if (!preloaded) { GLDS(0, 0) }
;   __syncthreads();
;   for (int kt = 0; kt < nk; ++kt) {
;     if (kt + 1 < nk) { GLDS((kt + 1) & 1, (kt + 1) << 6) }
;     compute(kt & 1);
;     __syncthreads();
;   }
; DI void phaseD_tile(const P& p, int layer, int mt, int nt, char* lds) {
;     ...
; #pragma unroll
;   for (int mi = 0; mi < 4; ++mi)
; #pragma unroll
;     for (int ni = 0; ni < 4; ++ni)
; #pragma unroll
;       for (int j = 0; j < 4; ++j) acc[mi][ni][j] *= fmaxf((float)((gav[mi][ni] >> (8 * j)) & 255u), 1.f) * (1.f / 255.f);
	v_mfma_f32_16x16x32_bf16 v[2:5], v[152:155], v[192:195], v[2:5]
	v_mfma_f32_16x16x32_bf16 v[10:13], v[6:9], v[180:183], v[10:13]
	v_mfma_f32_16x16x32_bf16 v[22:25], v[6:9], v[184:187], v[22:25]
	v_mfma_f32_16x16x32_bf16 v[30:33], v[6:9], v[188:191], v[30:33]
	v_mfma_f32_16x16x32_bf16 v[6:9], v[6:9], v[192:195], v[38:41]
	v_mfma_f32_16x16x32_bf16 v[38:41], v[26:29], v[180:183], v[46:49]
	v_mfma_f32_16x16x32_bf16 v[46:49], v[26:29], v[184:187], v[62:65]
	v_mfma_f32_16x16x32_bf16 v[62:65], v[26:29], v[188:191], v[70:73]
	v_mfma_f32_16x16x32_bf16 v[26:29], v[26:29], v[192:195], v[54:57]
	v_mfma_f32_16x16x32_bf16 v[54:57], v[148:151], v[180:183], v[58:61]
	v_mfma_f32_16x16x32_bf16 v[58:61], v[148:151], v[184:187], v[78:81]
	v_mfma_f32_16x16x32_bf16 v[70:73], v[148:151], v[188:191], v[74:77]
	v_mfma_f32_16x16x32_bf16 v[14:17], v[148:151], v[192:195], v[14:17]
	v_mfma_f32_16x16x32_bf16 v[18:21], v[152:155], v[180:183], v[18:21]
	v_mfma_f32_16x16x32_bf16 v[42:45], v[152:155], v[184:187], v[42:45]
	v_mfma_f32_16x16x32_bf16 v[34:37], v[152:155], v[188:191], v[34:37]
	v_mfma_f32_16x16x32_bf16 v[2:5], v[208:211], v[224:227], v[2:5]
	v_mfma_f32_16x16x32_bf16 v[10:13], v[196:199], v[212:215], v[10:13]
	v_mfma_f32_16x16x32_bf16 v[22:25], v[196:199], v[216:219], v[22:25]
	v_mfma_f32_16x16x32_bf16 v[30:33], v[196:199], v[220:223], v[30:33]
	v_mfma_f32_16x16x32_bf16 v[6:9], v[196:199], v[224:227], v[6:9]
	v_mfma_f32_16x16x32_bf16 v[38:41], v[200:203], v[212:215], v[38:41]
	v_mfma_f32_16x16x32_bf16 v[46:49], v[200:203], v[216:219], v[46:49]
	v_mfma_f32_16x16x32_bf16 v[62:65], v[200:203], v[220:223], v[62:65]
	v_mfma_f32_16x16x32_bf16 v[26:29], v[200:203], v[224:227], v[26:29]
	v_mfma_f32_16x16x32_bf16 v[54:57], v[204:207], v[212:215], v[54:57]
	v_mfma_f32_16x16x32_bf16 v[58:61], v[204:207], v[216:219], v[58:61]
	v_mfma_f32_16x16x32_bf16 v[70:73], v[204:207], v[220:223], v[70:73]
	v_mfma_f32_16x16x32_bf16 v[14:17], v[204:207], v[224:227], v[14:17]
	v_mfma_f32_16x16x32_bf16 v[18:21], v[208:211], v[212:215], v[18:21]
	v_mfma_f32_16x16x32_bf16 v[42:45], v[208:211], v[216:219], v[42:45]
	v_mfma_f32_16x16x32_bf16 v[34:37], v[208:211], v[220:223], v[34:37]
	s_setprio 0
	s_waitcnt vmcnt(0)
	s_barrier
	ds_read_b128 v[74:77], v0 offset:32768
	ds_read_b128 v[78:81], v0 offset:34816
	ds_read_b128 v[148:151], v0 offset:36864
	ds_read_b128 v[152:155], v0 offset:38912
	ds_read_b128 v[180:183], v145 offset:49152
	ds_read_b128 v[184:187], v145 offset:51200
	ds_read_b128 v[188:191], v145 offset:53248
	ds_read_b128 v[142:145], v145 offset:55296
	ds_read_b128 v[192:195], v146 offset:32768
	ds_read_b128 v[196:199], v146 offset:34816
	ds_read_b128 v[200:203], v146 offset:36864
	ds_read_b128 v[204:207], v146 offset:38912
	ds_read_b128 v[208:211], v147 offset:49152
	ds_read_b128 v[212:215], v147 offset:51200
	ds_read_b128 v[216:219], v147 offset:53248
	ds_read_b128 v[220:223], v147 offset:55296
	s_setprio 1
	s_waitcnt lgkmcnt(8)
	v_mfma_f32_16x16x32_bf16 v[2:5], v[152:155], v[142:145], v[2:5]
	v_mfma_f32_16x16x32_bf16 v[10:13], v[74:77], v[180:183], v[10:13]
	v_mfma_f32_16x16x32_bf16 v[22:25], v[74:77], v[184:187], v[22:25]
	v_mfma_f32_16x16x32_bf16 v[30:33], v[74:77], v[188:191], v[30:33]
	v_mfma_f32_16x16x32_bf16 v[6:9], v[74:77], v[142:145], v[6:9]
	v_mfma_f32_16x16x32_bf16 v[38:41], v[78:81], v[180:183], v[38:41]
	v_mfma_f32_16x16x32_bf16 v[46:49], v[78:81], v[184:187], v[46:49]
	v_mfma_f32_16x16x32_bf16 v[62:65], v[78:81], v[188:191], v[62:65]
	v_mfma_f32_16x16x32_bf16 v[26:29], v[78:81], v[142:145], v[26:29]
	v_mfma_f32_16x16x32_bf16 v[54:57], v[148:151], v[180:183], v[54:57]
	v_mfma_f32_16x16x32_bf16 v[58:61], v[148:151], v[184:187], v[58:61]
	v_mfma_f32_16x16x32_bf16 v[70:73], v[148:151], v[188:191], v[70:73]
	v_mfma_f32_16x16x32_bf16 v[14:17], v[148:151], v[142:145], v[14:17]
	v_mfma_f32_16x16x32_bf16 v[18:21], v[152:155], v[180:183], v[18:21]
	v_mfma_f32_16x16x32_bf16 v[42:45], v[152:155], v[184:187], v[42:45]
	v_mfma_f32_16x16x32_bf16 v[34:37], v[152:155], v[188:191], v[34:37]
	s_waitcnt lgkmcnt(0)
	v_mfma_f32_16x16x32_bf16 v[2:5], v[204:207], v[220:223], v[2:5]
	v_mfma_f32_16x16x32_bf16 v[10:13], v[192:195], v[208:211], v[10:13]
	v_mfma_f32_16x16x32_bf16 v[22:25], v[192:195], v[212:215], v[22:25]
	v_mfma_f32_16x16x32_bf16 v[30:33], v[192:195], v[216:219], v[30:33]
	v_mfma_f32_16x16x32_bf16 v[6:9], v[192:195], v[220:223], v[6:9]
	v_mfma_f32_16x16x32_bf16 v[38:41], v[196:199], v[208:211], v[38:41]
	v_mfma_f32_16x16x32_bf16 v[46:49], v[196:199], v[212:215], v[46:49]
	v_mfma_f32_16x16x32_bf16 v[62:65], v[196:199], v[216:219], v[62:65]
	v_mfma_f32_16x16x32_bf16 v[26:29], v[196:199], v[220:223], v[26:29]
	v_mfma_f32_16x16x32_bf16 v[54:57], v[200:203], v[208:211], v[54:57]
	v_mfma_f32_16x16x32_bf16 v[58:61], v[200:203], v[212:215], v[58:61]
	v_mfma_f32_16x16x32_bf16 v[70:73], v[200:203], v[216:219], v[70:73]
	v_mfma_f32_16x16x32_bf16 v[14:17], v[200:203], v[220:223], v[14:17]
	v_mfma_f32_16x16x32_bf16 v[18:21], v[204:207], v[208:211], v[18:21]
	v_mfma_f32_16x16x32_bf16 v[42:45], v[204:207], v[212:215], v[42:45]
	v_mfma_f32_16x16x32_bf16 v[34:37], v[204:207], v[216:219], v[34:37]
	s_setprio 0
	v_mul_f32_e32 v0, 0x3b808081, v100
	v_mul_f32_e32 v10, v0, v10
	v_mul_f32_e32 v0, 0x3b808081, v101
	v_mul_f32_e32 v11, v0, v11
	v_mul_f32_e32 v0, 0x3b808081, v102
	v_mul_f32_e32 v12, v0, v12
	v_mul_f32_e32 v0, 0x3b808081, v103
	v_mul_f32_e32 v13, v0, v13
	v_mul_f32_e32 v0, 0x3b808081, v104
	v_mul_f32_e32 v22, v0, v22
	v_mul_f32_e32 v0, 0x3b808081, v105
	v_mul_f32_e32 v23, v0, v23
	v_mul_f32_e32 v0, 0x3b808081, v106
	v_mul_f32_e32 v24, v0, v24
	v_mul_f32_e32 v0, 0x3b808081, v107
; DI unsigned pk2(float lo, float hi) { unsigned r; asm("v_cvt_pk_bf16_f32 %0, %1, %2" : "=v"(r) : "v"(lo), "v"(hi)); return r; }
; DI void stage_acc(const f32x4 (&acc)[4][4], float* tile, int wm, int wn, int fr, int fq) {
; #pragma unroll
;   for (int mi = 0; mi < 4; ++mi)
; #pragma unroll
;     for (int ni = 0; ni < 4; ++ni)
; #pragma unroll
;       for (int j = 0; j < 4; ++j) tile[(wm * 64 + mi * 16 + fq * 4 + j) * EPS + wn * 64 + ni * 16 + fr] = acc[mi][ni][j];
; }
; DI void phaseD_tile(const P& p, int layer, int mt, int nt, char* lds) {
;     ...
; #pragma unroll
;   for (int mi = 0; mi < 4; ++mi)
; #pragma unroll
;     for (int ni = 0; ni < 4; ++ni)
; #pragma unroll
;       for (int j = 0; j < 4; ++j) acc[mi][ni][j] *= fmaxf((float)((gav[mi][ni] >> (8 * j)) & 255u), 1.f) * (1.f / 255.f);
;   float* tile = (float*)lds;
;   stage_acc(acc, tile, wm, wn, fr, fq);
;   __syncthreads();
;   bf16_t* MG = (bf16_t*)(p.ws + W_MERGED);
; #pragma unroll 1
;   for (int ps = 0; ps < 16; ++ps) {
;     const int lr = ps * 8 + wm * 4 + fq;
;     const f32x4 v = *(const f32x4*)(tile + lr * EPS + wn * 64 + fr * 4);
;     *(u32x2*)(MG + (size_t)(row0 + lr) * LDX + col0 + wn * 64 + fr * 4) = u32x2{pk2(v.x, v.y), pk2(v.z, v.w)};
	v_mul_f32_e32 v25, v0, v25
	v_mul_f32_e32 v0, 0x3b808081, v108
	v_mul_f32_e32 v30, v0, v30
	v_mul_f32_e32 v0, 0x3b808081, v109
	v_mul_f32_e32 v31, v0, v31
	v_mul_f32_e32 v0, 0x3b808081, v110
	v_mul_f32_e32 v32, v0, v32
	v_mul_f32_e32 v0, 0x3b808081, v111
	v_mul_f32_e32 v33, v0, v33
	v_mul_f32_e32 v0, 0x3b808081, v112
	v_mul_f32_e32 v6, v0, v6
	v_mul_f32_e32 v0, 0x3b808081, v113
	v_mul_f32_e32 v7, v0, v7
	v_mul_f32_e32 v0, 0x3b808081, v114
	v_mul_f32_e32 v8, v0, v8
	v_mul_f32_e32 v0, 0x3b808081, v115
	v_mul_f32_e32 v9, v0, v9
	v_mul_f32_e32 v0, 0x3b808081, v94
	v_mul_f32_e32 v38, v0, v38
	v_mul_f32_e32 v0, 0x3b808081, v95
	v_mul_f32_e32 v39, v0, v39
	v_mul_f32_e32 v0, 0x3b808081, v96
	v_mul_f32_e32 v40, v0, v40
	v_mul_f32_e32 v0, 0x3b808081, v97
	v_mul_f32_e32 v41, v0, v41
	v_mul_f32_e32 v0, 0x3b808081, v90
	v_mul_f32_e32 v46, v0, v46
	v_mul_f32_e32 v0, 0x3b808081, v91
	v_mul_f32_e32 v47, v0, v47
	v_mul_f32_e32 v0, 0x3b808081, v92
	v_mul_f32_e32 v48, v0, v48
	v_mul_f32_e32 v0, 0x3b808081, v93
	v_mul_f32_e32 v49, v0, v49
	v_mul_f32_e32 v0, 0x3b808081, v116
	v_mul_f32_e32 v50, v0, v62
	v_mul_f32_e32 v0, 0x3b808081, v117
	v_mul_f32_e32 v51, v0, v63
	v_mul_f32_e32 v0, 0x3b808081, v118
	v_mul_f32_e32 v62, v0, v64
	v_mul_f32_e32 v0, 0x3b808081, v119
	v_mul_f32_e32 v63, v0, v65
	v_mul_f32_e32 v0, 0x3b808081, v120
	v_mul_f32_e32 v26, v0, v26
	v_mul_f32_e32 v0, 0x3b808081, v121
	v_mul_f32_e32 v27, v0, v27
	v_mul_f32_e32 v0, 0x3b808081, v122
	v_mul_f32_e32 v28, v0, v28
	v_mul_f32_e32 v0, 0x3b808081, v123
	v_mul_f32_e32 v29, v0, v29
	v_mul_f32_e32 v0, 0x3b808081, v86
	v_mul_f32_e32 v54, v0, v54
	v_mul_f32_e32 v0, 0x3b808081, v87
	v_mul_f32_e32 v55, v0, v55
	v_mul_f32_e32 v0, 0x3b808081, v88
	v_mul_f32_e32 v56, v0, v56
	v_mul_f32_e32 v0, 0x3b808081, v89
	v_mul_f32_e32 v57, v0, v57
	v_mul_f32_e32 v0, 0x3b808081, v82
	v_mul_f32_e32 v58, v0, v58
	v_mul_f32_e32 v0, 0x3b808081, v83
	v_mul_f32_e32 v59, v0, v59
	v_mul_f32_e32 v0, 0x3b808081, v84
	v_mul_f32_e32 v60, v0, v60
	v_mul_f32_e32 v0, 0x3b808081, v85
	v_mul_f32_e32 v61, v0, v61
	v_mul_f32_e32 v0, 0x3b808081, v124
	v_mul_f32_e32 v64, v0, v70
	v_mul_f32_e32 v0, 0x3b808081, v125
	v_mul_f32_e32 v65, v0, v71
	v_mul_f32_e32 v0, 0x3b808081, v126
	v_mul_f32_e32 v70, v0, v72
	v_mul_f32_e32 v0, 0x3b808081, v127
	v_mul_f32_e32 v71, v0, v73
	v_mul_f32_e32 v0, 0x3b808081, v128
	v_mul_f32_e32 v14, v0, v14
	v_mul_f32_e32 v0, 0x3b808081, v129
	v_mul_f32_e32 v15, v0, v15
	v_mul_f32_e32 v0, 0x3b808081, v130
	v_mul_f32_e32 v16, v0, v16
	v_mul_f32_e32 v0, 0x3b808081, v131
	v_mul_f32_e32 v17, v0, v17
	v_mul_f32_e32 v0, 0x3b808081, v66
	v_mul_f32_e32 v18, v0, v18
	v_mul_f32_e32 v0, 0x3b808081, v67
	v_mul_f32_e32 v19, v0, v19
	v_mul_f32_e32 v0, 0x3b808081, v68
	v_mul_f32_e32 v20, v0, v20
	v_mul_f32_e32 v0, 0x3b808081, v69
	v_mul_f32_e32 v21, v0, v21
	v_mul_f32_e32 v0, 0x3b808081, v52
	v_mul_f32_e32 v42, v0, v42
	v_mul_f32_e32 v0, 0x3b808081, v53
	v_mul_f32_e32 v43, v0, v43
	v_mul_f32_e32 v0, 0x3b808081, v132
	v_mul_f32_e32 v44, v0, v44
	v_mul_f32_e32 v0, 0x3b808081, v133
	v_mul_f32_e32 v45, v0, v45
	v_mul_f32_e32 v0, 0x3b808081, v134
	v_mul_f32_e32 v34, v0, v34
	v_mul_f32_e32 v0, 0x3b808081, v135
	v_mul_f32_e32 v35, v0, v35
	v_mul_f32_e32 v0, 0x3b808081, v136
	v_mul_f32_e32 v36, v0, v36
	v_mul_f32_e32 v0, 0x3b808081, v137
	v_mul_f32_e32 v37, v0, v37
	v_mul_f32_e32 v0, 0x3b808081, v138
	v_mul_f32_e32 v52, v0, v2
	v_mul_f32_e32 v0, 0x3b808081, v139
	v_mul_f32_e32 v53, v0, v3
	v_mul_f32_e32 v0, 0x3b808081, v140
	v_mul_f32_e32 v4, v0, v4
	v_mul_f32_e32 v0, 0x3b808081, v141
	v_bfe_u32 v66, v99, 4, 2
	v_mul_f32_e32 v5, v0, v5
	v_lshlrev_b32_e32 v0, 2, v66
	s_lshl_b32 s5, s20, 8
	v_lshl_or_b32 v2, s19, 6, v0
	v_lshl_or_b32 v0, v98, 2, s5
	v_mad_u64_u32 v[2:3], s[8:9], v2, s56, v[0:1]
	v_add_u32_e32 v0, 0x400, v2
	s_lshl_b32 s8, s19, 2
	s_lshl_b64 s[6:7], s[6:7], 1
	s_mov_b64 s[58:59], s[60:61]
	s_barrier
	ds_write2_b32 v2, v10, v22 offset1:16
	ds_write2_b32 v2, v11, v23 offset0:132 offset1:148
	ds_write2_b32 v0, v12, v24 offset0:8 offset1:24
	ds_write2_b32 v0, v13, v25 offset0:140 offset1:156
	ds_write2_b32 v2, v30, v6 offset0:32 offset1:48
	ds_write2_b32 v2, v31, v7 offset0:164 offset1:180
	ds_write2_b32 v0, v32, v8 offset0:40 offset1:56
	ds_write2_b32 v0, v33, v9 offset0:172 offset1:188
	v_add_u32_e32 v0, 0x2000, v2
	v_add_u32_e32 v3, 0x2400, v2
	s_add_u32 s6, s58, s6
	ds_write2_b32 v0, v38, v46 offset0:64 offset1:80
	ds_write2_b32 v0, v39, v47 offset0:196 offset1:212
	ds_write2_b32 v3, v40, v48 offset0:72 offset1:88
	ds_write2_b32 v3, v41, v49 offset0:204 offset1:220
	ds_write2_b32 v0, v50, v26 offset0:96 offset1:112
	ds_write2_b32 v0, v51, v27 offset0:228 offset1:244
	ds_write2_b32 v3, v62, v28 offset0:104 offset1:120
	ds_write2_b32 v3, v63, v29 offset0:236 offset1:252
	v_add_u32_e32 v0, 0x4000, v2
	v_add_u32_e32 v3, 0x4400, v2
	v_add_u32_e32 v6, 0x4800, v2
	s_addc_u32 s7, s59, s7
	s_lshl_b32 s9, s20, 7
	ds_write2_b32 v0, v54, v58 offset0:128 offset1:144
	ds_write2_b32 v3, v55, v59 offset0:4 offset1:20
	ds_write2_b32 v3, v56, v60 offset0:136 offset1:152
	ds_write2_b32 v6, v57, v61 offset0:12 offset1:28
	ds_write2_b32 v0, v64, v14 offset0:160 offset1:176
	ds_write2_b32 v3, v65, v15 offset0:36 offset1:52
	ds_write2_b32 v3, v70, v16 offset0:168 offset1:184
	ds_write2_b32 v6, v71, v17 offset0:44 offset1:60
	v_add_u32_e32 v0, 0x6000, v2
	v_add_u32_e32 v3, 0x6400, v2
	v_add_u32_e32 v2, 0x6800, v2
	s_add_u32 s6, s6, s9
	s_mulk_i32 s19, 0x840
	ds_write2_b32 v0, v18, v42 offset0:192 offset1:208
	ds_write2_b32 v3, v19, v43 offset0:68 offset1:84
	ds_write2_b32 v3, v20, v44 offset0:200 offset1:216
	ds_write2_b32 v2, v21, v45 offset0:76 offset1:92
	ds_write2_b32 v0, v34, v52 offset0:224 offset1:240
	ds_write2_b32 v3, v35, v53 offset0:100 offset1:116
	ds_write2_b32 v3, v36, v4 offset0:232 offset1:248
	ds_write2_b32 v2, v37, v5 offset0:108 offset1:124
	s_addc_u32 s7, s7, 0
	v_lshlrev_b32_e32 v0, 3, v98
	s_add_i32 s8, s8, s4
	v_mul_u32_u24_e32 v4, 0x210, v66
	s_add_i32 s5, s5, s19
	v_lshlrev_b32_e32 v5, 4, v98
	v_lshl_add_u64 v[2:3], s[6:7], 0, v[0:1]
	v_or_b32_e32 v0, s8, v66
	v_add3_u32 v4, s5, v4, v5
	s_mov_b32 s4, 0
	s_movk_i32 s5, 0x880
	s_waitcnt lgkmcnt(0)
	s_barrier

; #define MFMA32(a, b, c) __builtin_amdgcn_mfma_f32_32x32x16_bf16((a), (b), (c), 0, 0, 0)
; DI void attn_item(const P& p, bool isS, int b, int h, int qblk, char* lds) {
;     ...
;   auto tile_compute = [&](const char* base, const u32x2 mw) {
;     f32x16 st[2];
;     bf16x8 kf[2][4];
; #pragma unroll
;     for (int kb = 0; kb < 2; ++kb)
; #pragma unroll
;       for (int s = 0; s < 4; ++s) kf[kb][s] = *(const bf16x8*)(base + (kb * 32 + r) * 128 + (((2 * s + hl) ^ fxk) << 4));
;     __builtin_amdgcn_s_setprio(1);
; #pragma unroll
;     for (int kb = 0; kb < 2; ++kb) {
; #pragma unroll
;       for (int i = 0; i < 16; ++i) st[kb][i] = 0.f;
; #pragma unroll
;       for (int s = 0; s < 4; ++s) st[kb] = MFMA32(kf[kb][s], qf[s], st[kb]);
;     }
;     __builtin_amdgcn_s_setprio(0);
;     float tmax = -INFINITY;
; #pragma unroll
;     for (int kb = 0; kb < 2; ++kb) {
;       const unsigned wk = mw[kb] >> (4 * hl);
; #pragma unroll
;       for (int i = 0; i < 16; ++i) {
;         const int bit = (i & 3) + 8 * (i >> 2);
;         const float v = ((wk >> bit) & 1u) ? st[kb][i] : -INFINITY;
;         st[kb][i] = v;
;         tmax = fmaxf(tmax, v);
;       }
;     }
;     if (__any(tmax - mrun > 32.f)) {
;       const float mnew = fmaxf(mrun, fmaxf(tmax, __shfl_xor(tmax, 32)));
;       const float alpha = __builtin_amdgcn_exp2f(mrun - mnew);
;       mrun = mnew;
;       lsum *= alpha;
; #pragma unroll
;       for (int i = 0; i < 16; ++i) { ot[0][i] *= alpha; ot[1][i] *= alpha; }
;     }
.LBB0_301:
	ds_read_b128 v[34:37], v141
	ds_read_b128 v[38:41], v141 offset:4096
	ds_read_b128 v[42:45], v142
	ds_read_b128 v[146:149], v142 offset:4096
	ds_read_b128 v[46:49], v143
	ds_read_b128 v[150:153], v143 offset:4096
	ds_read_b128 v[154:157], v144
	ds_read_b128 v[180:183], v144 offset:4096
	s_setprio 1
	s_waitcnt lgkmcnt(7)
	v_mfma_f32_32x32x16_bf16 v[50:65], v[34:37], v[66:69], 0
	s_waitcnt lgkmcnt(5)
	v_mfma_f32_32x32x16_bf16 v[50:65], v[42:45], v[70:73], v[50:65]
	s_waitcnt lgkmcnt(3)
	v_mfma_f32_32x32x16_bf16 v[50:65], v[46:49], v[74:77], v[50:65]
	v_mfma_f32_32x32x16_bf16 v[34:49], v[38:41], v[66:69], 0
	v_mfma_f32_32x32x16_bf16 v[34:49], v[146:149], v[70:73], v[34:49]
	s_waitcnt lgkmcnt(2)
	v_mfma_f32_32x32x16_bf16 v[34:49], v[150:153], v[74:77], v[34:49]
	s_waitcnt lgkmcnt(1)
	v_mfma_f32_32x32x16_bf16 v[50:65], v[154:157], v[78:81], v[50:65]
	s_waitcnt lgkmcnt(0)
	v_mfma_f32_32x32x16_bf16 v[34:49], v[180:183], v[78:81], v[34:49]
	s_setprio 0
	s_waitcnt vmcnt(3)
	v_lshrrev_b32_e32 v114, v119, v114
	v_and_b32_e32 v133, 1, v114
	v_cmp_eq_u32_e32 vcc, 1, v133
	v_and_b32_e32 v133, 2, v114
	v_and_b32_e32 v136, 4, v114
	s_nop 2
	v_cndmask_b32_e32 v50, v169, v50, vcc
	v_cmp_ne_u32_e32 vcc, 0, v133
	v_lshrrev_b32_e32 v156, v119, v115
	s_nop 0
	v_cndmask_b32_e32 v51, v169, v51, vcc
	v_cmp_ne_u32_e32 vcc, 0, v136
	v_bfe_i32 v136, v114, 3, 1
	v_max3_f32 v133, v50, s73, v51
	v_cndmask_b32_e32 v52, v169, v52, vcc
	v_bfi_b32 v53, v136, v53, v169
	v_bfe_i32 v136, v114, 8, 1
	v_bfi_b32 v54, v136, v54, v169
	v_bfe_i32 v136, v114, 9, 1
	v_max3_f32 v133, v133, v52, v53
	v_bfi_b32 v55, v136, v55, v169
	v_bfe_i32 v136, v114, 10, 1
	v_bfi_b32 v56, v136, v56, v169
	v_bfe_i32 v136, v114, 11, 1
	v_max3_f32 v133, v133, v54, v55
	v_bfi_b32 v57, v136, v57, v169
	v_bfe_i32 v136, v114, 16, 1
	v_bfi_b32 v58, v136, v58, v169
	v_bfe_i32 v136, v114, 17, 1
	v_max3_f32 v133, v133, v56, v57
	v_bfi_b32 v59, v136, v59, v169
	v_bfe_i32 v136, v114, 18, 1
	v_bfi_b32 v60, v136, v60, v169
	v_bfe_i32 v136, v114, 19, 1
	v_max3_f32 v133, v133, v58, v59
	v_bfi_b32 v61, v136, v61, v169
	v_bfe_i32 v136, v114, 24, 1
	v_bfi_b32 v62, v136, v62, v169
	v_bfe_i32 v136, v114, 25, 1
	v_max3_f32 v133, v133, v60, v61
	v_bfi_b32 v63, v136, v63, v169
	v_bfe_i32 v136, v114, 26, 1
	v_bfe_i32 v114, v114, 27, 1
	v_bfi_b32 v64, v136, v64, v169
	v_max3_f32 v133, v133, v62, v63
	v_bfi_b32 v65, v114, v65, v169
	v_bfe_i32 v114, v156, 0, 1
	v_bfi_b32 v114, v114, v34, v169
	v_max3_f32 v133, v133, v64, v65
	v_bfe_i32 v34, v156, 1, 1
	v_bfi_b32 v115, v34, v35, v169
	v_and_b32_e32 v35, 4, v156
	v_cmp_ne_u32_e32 vcc, 0, v35
	v_bfe_i32 v35, v156, 3, 1
	v_max3_f32 v34, v133, v114, v115
	v_cndmask_b32_e32 v133, v169, v36, vcc
	v_bfi_b32 v136, v35, v37, v169
	v_bfe_i32 v35, v156, 8, 1
	v_bfi_b32 v137, v35, v38, v169
	v_bfe_i32 v35, v156, 9, 1
	v_max3_f32 v34, v34, v133, v136
	v_bfi_b32 v146, v35, v39, v169
	v_bfe_i32 v35, v156, 10, 1
	v_bfi_b32 v147, v35, v40, v169
	v_bfe_i32 v35, v156, 11, 1
	v_max3_f32 v34, v34, v137, v146
	v_bfi_b32 v148, v35, v41, v169
	v_bfe_i32 v35, v156, 16, 1
	v_bfi_b32 v149, v35, v42, v169
	v_bfe_i32 v35, v156, 17, 1
	v_max3_f32 v34, v34, v147, v148
	v_bfi_b32 v150, v35, v43, v169
	v_bfe_i32 v35, v156, 18, 1
	v_bfi_b32 v151, v35, v44, v169
	v_bfe_i32 v35, v156, 19, 1
	v_max3_f32 v34, v34, v149, v150
	v_bfi_b32 v152, v35, v45, v169
	v_bfe_i32 v35, v156, 24, 1
	v_bfi_b32 v153, v35, v46, v169
	v_bfe_i32 v35, v156, 25, 1
	v_max3_f32 v34, v34, v151, v152
	v_bfi_b32 v154, v35, v47, v169
	v_bfe_i32 v35, v156, 26, 1
	v_bfi_b32 v155, v35, v48, v169
	v_bfe_i32 v35, v156, 27, 1
	v_max3_f32 v34, v34, v153, v154
	v_bfi_b32 v156, v35, v49, v169
	v_max3_f32 v34, v34, v155, v156
	v_sub_f32_e32 v35, v34, v145
	v_cmp_lt_f32_e32 vcc, s96, v35
	s_cbranch_vccz .LBB0_303
	v_and_b32_e32 v36, 64, v170
	v_xor_b32_e32 v35, 32, v170
	v_add_u32_e32 v36, 64, v36
	v_cmp_lt_i32_e32 vcc, v35, v36
	s_nop 1
	v_cndmask_b32_e32 v35, v170, v35, vcc
	v_lshlrev_b32_e32 v35, 2, v35
	ds_bpermute_b32 v35, v35, v34
	s_waitcnt lgkmcnt(0)
	v_max3_f32 v35, v145, v34, v35
	v_sub_f32_e32 v34, v145, v35
	v_exp_f32_e32 v34, v34
	v_mov_b32_e32 v145, v35
	v_mul_f32_e32 v140, v140, v34
	v_pk_mul_f32 v[32:33], v[32:33], v[34:35] op_sel_hi:[1,0]
	v_pk_mul_f32 v[30:31], v[30:31], v[34:35] op_sel_hi:[1,0]
	v_pk_mul_f32 v[28:29], v[28:29], v[34:35] op_sel_hi:[1,0]
	v_pk_mul_f32 v[26:27], v[26:27], v[34:35] op_sel_hi:[1,0]
	v_pk_mul_f32 v[24:25], v[24:25], v[34:35] op_sel_hi:[1,0]
	v_pk_mul_f32 v[22:23], v[22:23], v[34:35] op_sel_hi:[1,0]
	v_pk_mul_f32 v[20:21], v[20:21], v[34:35] op_sel_hi:[1,0]
	v_pk_mul_f32 v[18:19], v[18:19], v[34:35] op_sel_hi:[1,0]
	v_pk_mul_f32 v[16:17], v[16:17], v[34:35] op_sel_hi:[1,0]
	v_pk_mul_f32 v[14:15], v[14:15], v[34:35] op_sel_hi:[1,0]
	v_pk_mul_f32 v[12:13], v[12:13], v[34:35] op_sel_hi:[1,0]
	v_pk_mul_f32 v[10:11], v[10:11], v[34:35] op_sel_hi:[1,0]
	v_pk_mul_f32 v[8:9], v[8:9], v[34:35] op_sel_hi:[1,0]
	v_pk_mul_f32 v[6:7], v[6:7], v[34:35] op_sel_hi:[1,0]
	v_pk_mul_f32 v[4:5], v[4:5], v[34:35] op_sel_hi:[1,0]
	v_pk_mul_f32 v[2:3], v[2:3], v[34:35] op_sel_hi:[1,0]

; #define MFMA32(a, b, c) __builtin_amdgcn_mfma_f32_32x32x16_bf16((a), (b), (c), 0, 0, 0)
; DI void attn_item(const P& p, bool isS, int b, int h, int qblk, char* lds) {
;     ...
;   auto tile_compute = [&](const char* base, const u32x2 mw) {
;     f32x16 st[2];
;     bf16x8 kf[2][4];
; #pragma unroll
;     for (int kb = 0; kb < 2; ++kb)
; #pragma unroll
;       for (int s = 0; s < 4; ++s) kf[kb][s] = *(const bf16x8*)(base + (kb * 32 + r) * 128 + (((2 * s + hl) ^ fxk) << 4));
;     __builtin_amdgcn_s_setprio(1);
; #pragma unroll
;     for (int kb = 0; kb < 2; ++kb) {
; #pragma unroll
;       for (int i = 0; i < 16; ++i) st[kb][i] = 0.f;
; #pragma unroll
;       for (int s = 0; s < 4; ++s) st[kb] = MFMA32(kf[kb][s], qf[s], st[kb]);
;     }
;     __builtin_amdgcn_s_setprio(0);
;     float tmax = -INFINITY;
; #pragma unroll
;     for (int kb = 0; kb < 2; ++kb) {
;       const unsigned wk = mw[kb] >> (4 * hl);
; #pragma unroll
;       for (int i = 0; i < 16; ++i) {
;         const int bit = (i & 3) + 8 * (i >> 2);
;         const float v = ((wk >> bit) & 1u) ? st[kb][i] : -INFINITY;
;         st[kb][i] = v;
;         tmax = fmaxf(tmax, v);
;       }
;     }
;     if (__any(tmax - mrun > 32.f)) {
;       const float mnew = fmaxf(mrun, fmaxf(tmax, __shfl_xor(tmax, 32)));
;       const float alpha = __builtin_amdgcn_exp2f(mrun - mnew);
;       mrun = mnew;
;       lsum *= alpha;
; #pragma unroll
;       for (int i = 0; i < 16; ++i) { ot[0][i] *= alpha; ot[1][i] *= alpha; }
;     }
.LBB0_308:
	ds_read_b128 v[34:37], v141 offset:16384
	ds_read_b128 v[38:41], v141 offset:20480
	ds_read_b128 v[42:45], v142 offset:16384
	ds_read_b128 v[146:149], v142 offset:20480
	ds_read_b128 v[46:49], v143 offset:16384
	ds_read_b128 v[150:153], v143 offset:20480
	ds_read_b128 v[154:157], v144 offset:16384
	ds_read_b128 v[180:183], v144 offset:20480
	s_setprio 1
	s_waitcnt lgkmcnt(7)
	v_mfma_f32_32x32x16_bf16 v[50:65], v[34:37], v[66:69], 0
	s_waitcnt lgkmcnt(5)
	v_mfma_f32_32x32x16_bf16 v[50:65], v[42:45], v[70:73], v[50:65]
	s_waitcnt lgkmcnt(3)
	v_mfma_f32_32x32x16_bf16 v[50:65], v[46:49], v[74:77], v[50:65]
	v_mfma_f32_32x32x16_bf16 v[34:49], v[38:41], v[66:69], 0
	v_mfma_f32_32x32x16_bf16 v[34:49], v[146:149], v[70:73], v[34:49]
	s_waitcnt lgkmcnt(2)
	v_mfma_f32_32x32x16_bf16 v[34:49], v[150:153], v[74:77], v[34:49]
	s_waitcnt lgkmcnt(1)
	v_mfma_f32_32x32x16_bf16 v[50:65], v[154:157], v[78:81], v[50:65]
	s_waitcnt lgkmcnt(0)
	v_mfma_f32_32x32x16_bf16 v[34:49], v[180:183], v[78:81], v[34:49]
	s_setprio 0
	v_lshrrev_b32_e32 v114, v119, v116
	v_and_b32_e32 v115, 1, v114
	v_cmp_eq_u32_e32 vcc, 1, v115
	v_and_b32_e32 v115, 2, v114
	v_and_b32_e32 v116, 4, v114
	s_nop 3
	v_cndmask_b32_e32 v50, v169, v50, vcc
	v_cmp_ne_u32_e32 vcc, 0, v115
	v_lshrrev_b32_e32 v156, v119, v117
	s_nop 0
	v_cndmask_b32_e32 v51, v169, v51, vcc
	v_cmp_ne_u32_e32 vcc, 0, v116
	v_bfe_i32 v116, v114, 3, 1
	v_max3_f32 v115, v50, s73, v51
	v_cndmask_b32_e32 v52, v169, v52, vcc
	v_bfi_b32 v53, v116, v53, v169
	v_bfe_i32 v116, v114, 8, 1
	v_bfi_b32 v54, v116, v54, v169
	v_bfe_i32 v116, v114, 9, 1
	v_max3_f32 v115, v115, v52, v53
	v_bfi_b32 v55, v116, v55, v169
	v_bfe_i32 v116, v114, 10, 1
	v_bfi_b32 v56, v116, v56, v169
	v_bfe_i32 v116, v114, 11, 1
	v_max3_f32 v115, v115, v54, v55
	v_bfi_b32 v57, v116, v57, v169
	v_bfe_i32 v116, v114, 16, 1
	v_bfi_b32 v58, v116, v58, v169
	v_bfe_i32 v116, v114, 17, 1
	v_max3_f32 v115, v115, v56, v57
	v_bfi_b32 v59, v116, v59, v169
	v_bfe_i32 v116, v114, 18, 1
	v_bfi_b32 v60, v116, v60, v169
	v_bfe_i32 v116, v114, 19, 1
	v_max3_f32 v115, v115, v58, v59
	v_bfi_b32 v61, v116, v61, v169
	v_bfe_i32 v116, v114, 24, 1
	v_bfi_b32 v62, v116, v62, v169
	v_bfe_i32 v116, v114, 25, 1
	v_max3_f32 v115, v115, v60, v61
	v_bfi_b32 v63, v116, v63, v169
	v_bfe_i32 v116, v114, 26, 1
	v_bfe_i32 v114, v114, 27, 1
	v_bfi_b32 v64, v116, v64, v169
	v_max3_f32 v115, v115, v62, v63
	v_bfi_b32 v65, v114, v65, v169
	v_bfe_i32 v114, v156, 0, 1
	v_bfi_b32 v114, v114, v34, v169
	v_max3_f32 v116, v115, v64, v65
	v_bfe_i32 v34, v156, 1, 1
	v_bfi_b32 v115, v34, v35, v169
	v_and_b32_e32 v35, 4, v156
	v_cmp_ne_u32_e32 vcc, 0, v35
	v_bfe_i32 v35, v156, 3, 1
	v_max3_f32 v34, v116, v114, v115
	v_cndmask_b32_e32 v116, v169, v36, vcc
	v_bfi_b32 v117, v35, v37, v169
	v_bfe_i32 v35, v156, 8, 1
	v_bfi_b32 v133, v35, v38, v169
	v_bfe_i32 v35, v156, 9, 1
	v_max3_f32 v34, v34, v116, v117
	v_bfi_b32 v146, v35, v39, v169
	v_bfe_i32 v35, v156, 10, 1
	v_bfi_b32 v147, v35, v40, v169
	v_bfe_i32 v35, v156, 11, 1
	v_max3_f32 v34, v34, v133, v146
	v_bfi_b32 v148, v35, v41, v169
	v_bfe_i32 v35, v156, 16, 1
	v_bfi_b32 v149, v35, v42, v169
	v_bfe_i32 v35, v156, 17, 1
	v_max3_f32 v34, v34, v147, v148
	v_bfi_b32 v150, v35, v43, v169
	v_bfe_i32 v35, v156, 18, 1
	v_bfi_b32 v151, v35, v44, v169
	v_bfe_i32 v35, v156, 19, 1
	v_max3_f32 v34, v34, v149, v150
	v_bfi_b32 v152, v35, v45, v169
	v_bfe_i32 v35, v156, 24, 1
	v_bfi_b32 v153, v35, v46, v169
	v_bfe_i32 v35, v156, 25, 1
	v_max3_f32 v34, v34, v151, v152
	v_bfi_b32 v154, v35, v47, v169
	v_bfe_i32 v35, v156, 26, 1
	v_bfi_b32 v155, v35, v48, v169
	v_bfe_i32 v35, v156, 27, 1
	v_max3_f32 v34, v34, v153, v154
	v_bfi_b32 v156, v35, v49, v169
	v_max3_f32 v34, v34, v155, v156
	v_sub_f32_e32 v35, v34, v145
	v_cmp_lt_f32_e32 vcc, s96, v35
	s_cbranch_vccz .LBB0_310
	v_and_b32_e32 v36, 64, v170
	v_xor_b32_e32 v35, 32, v170
	v_add_u32_e32 v36, 64, v36
	v_cmp_lt_i32_e32 vcc, v35, v36
	s_nop 1
	v_cndmask_b32_e32 v35, v170, v35, vcc
	v_lshlrev_b32_e32 v35, 2, v35
	ds_bpermute_b32 v35, v35, v34
	s_waitcnt lgkmcnt(0)
	v_max3_f32 v35, v145, v34, v35
	v_sub_f32_e32 v34, v145, v35
	v_exp_f32_e32 v34, v34
	v_mov_b32_e32 v145, v35
	v_mul_f32_e32 v140, v140, v34
	v_pk_mul_f32 v[32:33], v[32:33], v[34:35] op_sel_hi:[1,0]
	v_pk_mul_f32 v[30:31], v[30:31], v[34:35] op_sel_hi:[1,0]
	v_pk_mul_f32 v[28:29], v[28:29], v[34:35] op_sel_hi:[1,0]
	v_pk_mul_f32 v[26:27], v[26:27], v[34:35] op_sel_hi:[1,0]
	v_pk_mul_f32 v[24:25], v[24:25], v[34:35] op_sel_hi:[1,0]
	v_pk_mul_f32 v[22:23], v[22:23], v[34:35] op_sel_hi:[1,0]
	v_pk_mul_f32 v[20:21], v[20:21], v[34:35] op_sel_hi:[1,0]
	v_pk_mul_f32 v[18:19], v[18:19], v[34:35] op_sel_hi:[1,0]
	v_pk_mul_f32 v[16:17], v[16:17], v[34:35] op_sel_hi:[1,0]
	v_pk_mul_f32 v[14:15], v[14:15], v[34:35] op_sel_hi:[1,0]
	v_pk_mul_f32 v[12:13], v[12:13], v[34:35] op_sel_hi:[1,0]
	v_pk_mul_f32 v[10:11], v[10:11], v[34:35] op_sel_hi:[1,0]
	v_pk_mul_f32 v[8:9], v[8:9], v[34:35] op_sel_hi:[1,0]
	v_pk_mul_f32 v[6:7], v[6:7], v[34:35] op_sel_hi:[1,0]
	v_pk_mul_f32 v[4:5], v[4:5], v[34:35] op_sel_hi:[1,0]
	v_pk_mul_f32 v[2:3], v[2:3], v[34:35] op_sel_hi:[1,0]

; DI unsigned pk2(float lo, float hi) { unsigned r; asm("v_cvt_pk_bf16_f32 %0, %1, %2" : "=v"(r) : "v"(lo), "v"(hi)); return r; }
; DI void attn_item(const P& p, bool isS, int b, int h, int qblk, char* lds) {
;     ...
;   const float ltot = lsum + __shfl_xor(lsum, 32);
;   const float inv = 1.f / ltot;
;   if (wvalid) {
;     bf16_t* za = (bf16_t*)(p.ws + W_ZA) + (size_t)qrow * 512 + h * 64;
; #pragma unroll
;     for (int db = 0; db < 2; ++db)
; #pragma unroll
;       for (int g4 = 0; g4 < 4; ++g4) {
;         const int d = db * 32 + 8 * g4 + 4 * hl;
;         const u32x2 z = *(const u32x2*)(za + d);
;         const float z0 = __uint_as_float(z.x << 16), z1 = __uint_as_float(z.x & 0xffff0000u), z2 = __uint_as_float(z.y << 16), z3 = __uint_as_float(z.y & 0xffff0000u);
;         *(u32x2*)(za + d) = u32x2{pk2(ot[db][4 * g4] * inv * z0, ot[db][4 * g4 + 1] * inv * z1), pk2(ot[db][4 * g4 + 2] * inv * z2, ot[db][4 * g4 + 3] * inv * z3)};
;       }
;   }
.LBB0_313:
	v_and_b32_e32 v34, 64, v170
	v_xor_b32_e32 v0, 32, v170
	v_add_u32_e32 v34, 64, v34
	v_cmp_lt_i32_e32 vcc, v0, v34
	s_nop 1
	v_cndmask_b32_e32 v0, v170, v0, vcc
	v_lshlrev_b32_e32 v0, 2, v0
	ds_bpermute_b32 v0, v0, v140
	s_waitcnt lgkmcnt(0)
	v_add_f32_e32 v0, v140, v0
	v_rcp_f32_e32 v36, v0
	v_lshl_add_u64 v[34:35], v[120:121], 1, s[8:9]
	v_lshlrev_b32_e32 v0, 1, v119
	v_lshl_add_u64 v[34:35], v[34:35], 0, v[0:1]
	global_load_dwordx2 v[38:39], v[34:35], off
	v_mul_f32_e32 v18, v18, v36
	v_mul_f32_e32 v2, v2, v36
	s_waitcnt vmcnt(0)
	v_lshlrev_b32_e32 v0, 16, v38
	v_and_b32_e32 v37, 0xffff0000, v38
	v_mul_f32_e32 v0, v18, v0
	v_mul_f32_e32 v18, v19, v36
	v_lshlrev_b32_e32 v38, 16, v39
	v_and_b32_e32 v39, 0xffff0000, v39
	v_mul_f32_e32 v18, v18, v37
	v_mul_f32_e32 v19, v21, v36
	v_cvt_pk_bf16_f32 v18, v0, v18
	v_mul_f32_e32 v0, v20, v36
	v_mul_f32_e32 v19, v19, v39
	v_mul_f32_e32 v0, v0, v38
	v_cvt_pk_bf16_f32 v19, v0, v19
	global_store_dwordx2 v[34:35], v[18:19], off
	global_load_dwordx2 v[18:19], v[34:35], off offset:16
	v_mul_f32_e32 v21, v22, v36
	s_waitcnt vmcnt(0)
	v_lshlrev_b32_e32 v0, 16, v18
	v_and_b32_e32 v18, 0xffff0000, v18
	v_mul_f32_e32 v0, v21, v0
	v_mul_f32_e32 v21, v23, v36
	v_mul_f32_e32 v18, v21, v18
	v_lshlrev_b32_e32 v20, 16, v19
	v_cvt_pk_bf16_f32 v18, v0, v18
	v_mul_f32_e32 v0, v24, v36
	v_and_b32_e32 v19, 0xffff0000, v19
	v_mul_f32_e32 v0, v0, v20
	v_mul_f32_e32 v20, v25, v36
	v_mul_f32_e32 v19, v20, v19
	v_cvt_pk_bf16_f32 v19, v0, v19
	global_store_dwordx2 v[34:35], v[18:19], off offset:16
	global_load_dwordx2 v[18:19], v[34:35], off offset:32
	v_mul_f32_e32 v21, v26, v36
	s_waitcnt vmcnt(0)
	v_lshlrev_b32_e32 v0, 16, v18
	v_and_b32_e32 v18, 0xffff0000, v18
	v_mul_f32_e32 v0, v21, v0
	v_mul_f32_e32 v21, v27, v36
	v_mul_f32_e32 v18, v21, v18
	v_lshlrev_b32_e32 v20, 16, v19
	v_cvt_pk_bf16_f32 v18, v0, v18
	v_mul_f32_e32 v0, v28, v36
	v_and_b32_e32 v19, 0xffff0000, v19
	v_mul_f32_e32 v0, v0, v20
	v_mul_f32_e32 v20, v29, v36
	v_mul_f32_e32 v19, v20, v19
	v_cvt_pk_bf16_f32 v19, v0, v19
	global_store_dwordx2 v[34:35], v[18:19], off offset:32
	global_load_dwordx2 v[18:19], v[34:35], off offset:48
	v_mul_f32_e32 v21, v30, v36
	s_waitcnt vmcnt(0)
	v_lshlrev_b32_e32 v0, 16, v18
	v_and_b32_e32 v18, 0xffff0000, v18
	v_mul_f32_e32 v0, v21, v0
	v_mul_f32_e32 v21, v31, v36
	v_mul_f32_e32 v18, v21, v18
	v_lshlrev_b32_e32 v20, 16, v19
	v_cvt_pk_bf16_f32 v18, v0, v18
	v_mul_f32_e32 v0, v32, v36
	v_and_b32_e32 v19, 0xffff0000, v19
	v_mul_f32_e32 v0, v0, v20
	v_mul_f32_e32 v20, v33, v36
	v_mul_f32_e32 v19, v20, v19
	v_cvt_pk_bf16_f32 v19, v0, v19
	global_store_dwordx2 v[34:35], v[18:19], off offset:48
	global_load_dwordx2 v[18:19], v[34:35], off offset:64
	s_waitcnt vmcnt(0)
	v_lshlrev_b32_e32 v0, 16, v18
	v_and_b32_e32 v18, 0xffff0000, v18
	v_mul_f32_e32 v0, v2, v0
	v_mul_f32_e32 v2, v3, v36
	v_lshlrev_b32_e32 v20, 16, v19
	v_and_b32_e32 v19, 0xffff0000, v19
	v_mul_f32_e32 v2, v2, v18
	v_mul_f32_e32 v3, v5, v36
	v_cvt_pk_bf16_f32 v2, v0, v2
	v_mul_f32_e32 v0, v4, v36
	v_mul_f32_e32 v3, v3, v19
	v_mul_f32_e32 v0, v0, v20
	v_cvt_pk_bf16_f32 v3, v0, v3
	global_store_dwordx2 v[34:35], v[2:3], off offset:64
	global_load_dwordx2 v[2:3], v[34:35], off offset:80
	v_mul_f32_e32 v5, v6, v36
	s_waitcnt vmcnt(0)
	v_lshlrev_b32_e32 v0, 16, v2
	v_and_b32_e32 v2, 0xffff0000, v2
	v_mul_f32_e32 v0, v5, v0
	v_mul_f32_e32 v5, v7, v36
	v_mul_f32_e32 v2, v5, v2
	v_lshlrev_b32_e32 v4, 16, v3
	v_cvt_pk_bf16_f32 v2, v0, v2
	v_mul_f32_e32 v0, v8, v36
	v_and_b32_e32 v3, 0xffff0000, v3
	v_mul_f32_e32 v0, v0, v4
	v_mul_f32_e32 v4, v9, v36
	v_mul_f32_e32 v3, v4, v3
	v_cvt_pk_bf16_f32 v3, v0, v3
	global_store_dwordx2 v[34:35], v[2:3], off offset:80
	global_load_dwordx2 v[2:3], v[34:35], off offset:96
	v_mul_f32_e32 v5, v10, v36
	s_waitcnt vmcnt(0)
	v_lshlrev_b32_e32 v0, 16, v2
	v_and_b32_e32 v2, 0xffff0000, v2
	v_mul_f32_e32 v0, v5, v0
	v_mul_f32_e32 v5, v11, v36
	v_mul_f32_e32 v2, v5, v2
	v_lshlrev_b32_e32 v4, 16, v3
	v_cvt_pk_bf16_f32 v2, v0, v2
	v_mul_f32_e32 v0, v12, v36
	v_and_b32_e32 v3, 0xffff0000, v3
	v_mul_f32_e32 v0, v0, v4
	v_mul_f32_e32 v4, v13, v36
	v_mul_f32_e32 v3, v4, v3
	v_cvt_pk_bf16_f32 v3, v0, v3
	global_store_dwordx2 v[34:35], v[2:3], off offset:96
	global_load_dwordx2 v[2:3], v[34:35], off offset:112
	v_mul_f32_e32 v5, v14, v36
	s_waitcnt vmcnt(0)
	v_lshlrev_b32_e32 v0, 16, v2
	v_and_b32_e32 v2, 0xffff0000, v2
	v_mul_f32_e32 v0, v5, v0
	v_mul_f32_e32 v5, v15, v36
	v_mul_f32_e32 v2, v5, v2
	v_lshlrev_b32_e32 v4, 16, v3
	v_cvt_pk_bf16_f32 v2, v0, v2
	v_mul_f32_e32 v0, v16, v36
	v_and_b32_e32 v3, 0xffff0000, v3
	v_mul_f32_e32 v0, v0, v4
	v_mul_f32_e32 v4, v17, v36
	v_mul_f32_e32 v3, v4, v3
	v_cvt_pk_bf16_f32 v3, v0, v3
	global_store_dwordx2 v[34:35], v[2:3], off offset:112

; #define MFMA32(a, b, c) __builtin_amdgcn_mfma_f32_32x32x16_bf16((a), (b), (c), 0, 0, 0)
; DI void attn_item(const P& p, bool isS, int b, int h, int qblk, char* lds) {
;     ...
;   auto tile_compute = [&](const char* base, const u32x2 mw) {
;     f32x16 st[2];
;     bf16x8 kf[2][4];
; #pragma unroll
;     for (int kb = 0; kb < 2; ++kb)
; #pragma unroll
;       for (int s = 0; s < 4; ++s) kf[kb][s] = *(const bf16x8*)(base + (kb * 32 + r) * 128 + (((2 * s + hl) ^ fxk) << 4));
;     __builtin_amdgcn_s_setprio(1);
; #pragma unroll
;     for (int kb = 0; kb < 2; ++kb) {
; #pragma unroll
;       for (int i = 0; i < 16; ++i) st[kb][i] = 0.f;
; #pragma unroll
;       for (int s = 0; s < 4; ++s) st[kb] = MFMA32(kf[kb][s], qf[s], st[kb]);
;     }
;     __builtin_amdgcn_s_setprio(0);
;     float tmax = -INFINITY;
; #pragma unroll
;     for (int kb = 0; kb < 2; ++kb) {
;       const unsigned wk = mw[kb] >> (4 * hl);
; #pragma unroll
;       for (int i = 0; i < 16; ++i) {
;         const int bit = (i & 3) + 8 * (i >> 2);
;         const float v = ((wk >> bit) & 1u) ? st[kb][i] : -INFINITY;
;         st[kb][i] = v;
;         tmax = fmaxf(tmax, v);
;       }
;     }
;     if (__any(tmax - mrun > 32.f)) {
;       const float mnew = fmaxf(mrun, fmaxf(tmax, __shfl_xor(tmax, 32)));
;       const float alpha = __builtin_amdgcn_exp2f(mrun - mnew);
;       mrun = mnew;
;       lsum *= alpha;
; #pragma unroll
;       for (int i = 0; i < 16; ++i) { ot[0][i] *= alpha; ot[1][i] *= alpha; }
;     }
.LBB0_321:
	ds_read_b128 v[2:5], v182
	ds_read_b128 v[6:9], v182 offset:4096
	ds_read_b128 v[10:13], v183
	ds_read_b128 v[128:131], v183 offset:4096
	ds_read_b128 v[14:17], v184
	ds_read_b128 v[132:135], v184 offset:4096
	ds_read_b128 v[136:139], v185
	ds_read_b128 v[140:143], v185 offset:4096
	s_setprio 1
	s_waitcnt lgkmcnt(7)
	v_mfma_f32_32x32x16_bf16 v[34:49], v[2:5], v[66:69], 0
	s_waitcnt lgkmcnt(5)
	v_mfma_f32_32x32x16_bf16 v[34:49], v[10:13], v[70:73], v[34:49]
	s_waitcnt lgkmcnt(3)
	v_mfma_f32_32x32x16_bf16 v[34:49], v[14:17], v[74:77], v[34:49]
	v_mfma_f32_32x32x16_bf16 v[2:17], v[6:9], v[66:69], 0
	v_mfma_f32_32x32x16_bf16 v[2:17], v[128:131], v[70:73], v[2:17]
	s_waitcnt lgkmcnt(2)
	v_mfma_f32_32x32x16_bf16 v[2:17], v[132:135], v[74:77], v[2:17]
	s_waitcnt lgkmcnt(1)
	v_mfma_f32_32x32x16_bf16 v[34:49], v[136:139], v[78:81], v[34:49]
	s_waitcnt lgkmcnt(0)
	v_mfma_f32_32x32x16_bf16 v[2:17], v[140:143], v[78:81], v[2:17]
	s_setprio 0
	s_waitcnt vmcnt(4)
	v_lshrrev_b32_e32 v0, v179, v114
	v_and_b32_e32 v114, 1, v0
	v_cmp_eq_u32_e32 vcc, 1, v114
	v_lshrrev_b32_e32 v115, v179, v115
	s_nop 3
	v_cndmask_b32_e32 v114, v169, v34, vcc
	v_and_b32_e32 v34, 2, v0
	v_cmp_ne_u32_e32 vcc, 0, v34
	s_nop 1
	v_cndmask_b32_e32 v128, v169, v35, vcc
	v_and_b32_e32 v35, 4, v0
	v_cmp_ne_u32_e32 vcc, 0, v35
	v_bfe_i32 v35, v0, 3, 1
	v_max3_f32 v34, v114, s73, v128
	v_cndmask_b32_e32 v129, v169, v36, vcc
	v_bfi_b32 v130, v35, v37, v169
	v_bfe_i32 v35, v0, 8, 1
	v_bfi_b32 v38, v35, v38, v169
	v_bfe_i32 v35, v0, 9, 1
	v_max3_f32 v34, v34, v129, v130
	v_bfi_b32 v39, v35, v39, v169
	v_bfe_i32 v35, v0, 10, 1
	v_bfi_b32 v40, v35, v40, v169
	v_bfe_i32 v35, v0, 11, 1
	v_max3_f32 v34, v34, v38, v39
	v_bfi_b32 v41, v35, v41, v169
	v_bfe_i32 v35, v0, 16, 1
	v_bfi_b32 v42, v35, v42, v169
	v_bfe_i32 v35, v0, 17, 1
	v_max3_f32 v34, v34, v40, v41
	v_bfi_b32 v43, v35, v43, v169
	v_bfe_i32 v35, v0, 18, 1
	v_bfi_b32 v44, v35, v44, v169
	v_bfe_i32 v35, v0, 19, 1
	v_max3_f32 v34, v34, v42, v43
	v_bfi_b32 v45, v35, v45, v169
	v_bfe_i32 v35, v0, 24, 1
	v_bfi_b32 v46, v35, v46, v169
	v_bfe_i32 v35, v0, 25, 1
	v_max3_f32 v34, v34, v44, v45
	v_bfi_b32 v47, v35, v47, v169
	v_bfe_i32 v35, v0, 26, 1
	v_bfe_i32 v0, v0, 27, 1
	v_bfi_b32 v48, v35, v48, v169
	v_max3_f32 v34, v34, v46, v47
	v_bfi_b32 v49, v0, v49, v169
	v_max3_f32 v0, v34, v48, v49
	v_bfe_i32 v34, v115, 0, 1
	v_bfi_b32 v142, v34, v2, v169
	v_bfe_i32 v2, v115, 1, 1
	v_bfi_b32 v143, v2, v3, v169
	v_bfe_i32 v2, v115, 2, 1
	v_bfi_b32 v144, v2, v4, v169
	v_bfe_i32 v2, v115, 3, 1
	v_max3_f32 v0, v0, v142, v143
	v_bfi_b32 v36, v2, v5, v169
	v_bfe_i32 v2, v115, 8, 1
	v_and_b32_e32 v3, 0x8000000, v115
	v_bfi_b32 v37, v2, v6, v169
	v_bfe_i32 v2, v115, 9, 1
	v_max3_f32 v0, v0, v144, v36
	v_bfi_b32 v34, v2, v7, v169
	v_bfe_i32 v2, v115, 10, 1
	v_bfi_b32 v35, v2, v8, v169
	v_bfe_i32 v2, v115, 11, 1
	v_max3_f32 v0, v0, v37, v34
	v_bfi_b32 v9, v2, v9, v169
	v_bfe_i32 v2, v115, 16, 1
	v_bfi_b32 v8, v2, v10, v169
	v_bfe_i32 v2, v115, 17, 1
	v_max3_f32 v0, v0, v35, v9
	v_bfi_b32 v5, v2, v11, v169
	v_bfe_i32 v2, v115, 18, 1
	v_bfi_b32 v6, v2, v12, v169
	v_bfe_i32 v2, v115, 19, 1
	v_max3_f32 v0, v0, v8, v5
	v_bfi_b32 v7, v2, v13, v169
	v_max3_f32 v2, v0, v6, v7
	v_bfe_i32 v0, v115, 24, 1
	v_bfi_b32 v4, v0, v14, v169
	v_bfe_i32 v0, v115, 25, 1
	v_bfi_b32 v0, v0, v15, v169
	v_max3_f32 v10, v2, v4, v0
	v_bfe_i32 v2, v115, 26, 1
	v_bfi_b32 v2, v2, v16, v169
	v_cmp_ne_u32_e32 vcc, 0, v3
	s_nop 1
	v_cndmask_b32_e32 v3, v169, v17, vcc
	v_max3_f32 v10, v10, v2, v3
	v_sub_f32_e32 v11, v10, v186
	v_cmp_lt_f32_e32 vcc, s96, v11
	s_cbranch_vccz .LBB0_323
	v_and_b32_e32 v12, 64, v170
	v_xor_b32_e32 v11, 32, v170
	v_add_u32_e32 v12, 64, v12
	v_cmp_lt_i32_e32 vcc, v11, v12
	s_nop 1
	v_cndmask_b32_e32 v11, v170, v11, vcc
	v_lshlrev_b32_e32 v11, 2, v11
	ds_bpermute_b32 v11, v11, v10
	s_waitcnt lgkmcnt(0)
	v_max3_f32 v11, v186, v10, v11
	v_sub_f32_e32 v10, v186, v11
	v_exp_f32_e32 v10, v10
	v_mov_b32_e32 v186, v11
	v_mul_f32_e32 v187, v187, v10
	v_pk_mul_f32 v[32:33], v[32:33], v[10:11] op_sel_hi:[1,0]
	v_pk_mul_f32 v[30:31], v[30:31], v[10:11] op_sel_hi:[1,0]
	v_pk_mul_f32 v[28:29], v[28:29], v[10:11] op_sel_hi:[1,0]
	v_pk_mul_f32 v[26:27], v[26:27], v[10:11] op_sel_hi:[1,0]
	v_pk_mul_f32 v[24:25], v[24:25], v[10:11] op_sel_hi:[1,0]
	v_pk_mul_f32 v[22:23], v[22:23], v[10:11] op_sel_hi:[1,0]
	v_pk_mul_f32 v[20:21], v[20:21], v[10:11] op_sel_hi:[1,0]
	v_pk_mul_f32 v[18:19], v[18:19], v[10:11] op_sel_hi:[1,0]
	v_pk_mul_f32 v[64:65], v[64:65], v[10:11] op_sel_hi:[1,0]
	v_pk_mul_f32 v[62:63], v[62:63], v[10:11] op_sel_hi:[1,0]
	v_pk_mul_f32 v[60:61], v[60:61], v[10:11] op_sel_hi:[1,0]
	v_pk_mul_f32 v[58:59], v[58:59], v[10:11] op_sel_hi:[1,0]
	v_pk_mul_f32 v[56:57], v[56:57], v[10:11] op_sel_hi:[1,0]
	v_pk_mul_f32 v[54:55], v[54:55], v[10:11] op_sel_hi:[1,0]
	v_pk_mul_f32 v[52:53], v[52:53], v[10:11] op_sel_hi:[1,0]
	v_pk_mul_f32 v[50:51], v[50:51], v[10:11] op_sel_hi:[1,0]

; #define MFMA32(a, b, c) __builtin_amdgcn_mfma_f32_32x32x16_bf16((a), (b), (c), 0, 0, 0)
; DI void attn_item(const P& p, bool isS, int b, int h, int qblk, char* lds) {
;     ...
;   auto tile_compute = [&](const char* base, const u32x2 mw) {
;     f32x16 st[2];
;     bf16x8 kf[2][4];
; #pragma unroll
;     for (int kb = 0; kb < 2; ++kb)
; #pragma unroll
;       for (int s = 0; s < 4; ++s) kf[kb][s] = *(const bf16x8*)(base + (kb * 32 + r) * 128 + (((2 * s + hl) ^ fxk) << 4));
;     __builtin_amdgcn_s_setprio(1);
; #pragma unroll
;     for (int kb = 0; kb < 2; ++kb) {
; #pragma unroll
;       for (int i = 0; i < 16; ++i) st[kb][i] = 0.f;
; #pragma unroll
;       for (int s = 0; s < 4; ++s) st[kb] = MFMA32(kf[kb][s], qf[s], st[kb]);
;     }
;     __builtin_amdgcn_s_setprio(0);
;     float tmax = -INFINITY;
; #pragma unroll
;     for (int kb = 0; kb < 2; ++kb) {
;       const unsigned wk = mw[kb] >> (4 * hl);
; #pragma unroll
;       for (int i = 0; i < 16; ++i) {
;         const int bit = (i & 3) + 8 * (i >> 2);
;         const float v = ((wk >> bit) & 1u) ? st[kb][i] : -INFINITY;
;         st[kb][i] = v;
;         tmax = fmaxf(tmax, v);
;       }
;     }
;     if (__any(tmax - mrun > 32.f)) {
;       const float mnew = fmaxf(mrun, fmaxf(tmax, __shfl_xor(tmax, 32)));
;       const float alpha = __builtin_amdgcn_exp2f(mrun - mnew);
;       mrun = mnew;
;       lsum *= alpha;
; #pragma unroll
;       for (int i = 0; i < 16; ++i) { ot[0][i] *= alpha; ot[1][i] *= alpha; }
;     }
.LBB0_328:
	ds_read_b128 v[18:21], v182 offset:16384
	ds_read_b128 v[22:25], v182 offset:20480
	ds_read_b128 v[26:29], v183 offset:16384
	ds_read_b128 v[130:133], v183 offset:20480
	ds_read_b128 v[30:33], v184 offset:16384
	ds_read_b128 v[134:137], v184 offset:20480
	ds_read_b128 v[138:141], v185 offset:16384
	ds_read_b128 v[142:145], v185 offset:20480
	s_setprio 1
	s_waitcnt lgkmcnt(7)
	v_mfma_f32_32x32x16_bf16 v[50:65], v[18:21], v[66:69], 0
	s_waitcnt lgkmcnt(5)
	v_mfma_f32_32x32x16_bf16 v[50:65], v[26:29], v[70:73], v[50:65]
	s_waitcnt lgkmcnt(3)
	v_mfma_f32_32x32x16_bf16 v[50:65], v[30:33], v[74:77], v[50:65]
	v_mfma_f32_32x32x16_bf16 v[18:33], v[22:25], v[66:69], 0
	v_mfma_f32_32x32x16_bf16 v[18:33], v[130:133], v[70:73], v[18:33]
	s_waitcnt lgkmcnt(2)
	v_mfma_f32_32x32x16_bf16 v[18:33], v[134:137], v[74:77], v[18:33]
	s_waitcnt lgkmcnt(0)
	v_mfma_f32_32x32x16_bf16 v[18:33], v[142:145], v[78:81], v[18:33]
	v_mfma_f32_32x32x16_bf16 v[50:65], v[138:141], v[78:81], v[50:65]
	s_setprio 0
	v_lshrrev_b32_e32 v142, v179, v116
	v_and_b32_e32 v114, 1, v142
	v_cmp_eq_u32_e32 vcc, 1, v114
	s_nop 7
	v_cndmask_b32_e32 v114, v169, v50, vcc
	v_and_b32_e32 v50, 2, v142
	v_cmp_ne_u32_e32 vcc, 0, v50
	s_nop 1
	v_cndmask_b32_e32 v115, v169, v51, vcc
	v_and_b32_e32 v51, 4, v142
	v_cmp_ne_u32_e32 vcc, 0, v51
	v_bfe_i32 v51, v142, 3, 1
	v_max3_f32 v50, v114, s73, v115
	v_cndmask_b32_e32 v116, v169, v52, vcc
	v_bfi_b32 v130, v51, v53, v169
	v_bfe_i32 v51, v142, 8, 1
	v_bfi_b32 v131, v51, v54, v169
	v_bfe_i32 v51, v142, 9, 1
	v_max3_f32 v50, v50, v116, v130
	v_bfi_b32 v132, v51, v55, v169
	v_bfe_i32 v51, v142, 10, 1
	v_bfi_b32 v133, v51, v56, v169
	v_bfe_i32 v51, v142, 11, 1
	v_max3_f32 v50, v50, v131, v132
	v_bfi_b32 v134, v51, v57, v169
	v_bfe_i32 v51, v142, 16, 1
	v_bfi_b32 v135, v51, v58, v169
	v_bfe_i32 v51, v142, 17, 1
	v_max3_f32 v50, v50, v133, v134
	v_bfi_b32 v136, v51, v59, v169
	v_bfe_i32 v51, v142, 18, 1
	v_bfi_b32 v137, v51, v60, v169
	v_bfe_i32 v51, v142, 19, 1
	v_max3_f32 v50, v50, v135, v136
	v_bfi_b32 v138, v51, v61, v169
	v_bfe_i32 v51, v142, 24, 1
	v_bfi_b32 v139, v51, v62, v169
	v_bfe_i32 v51, v142, 25, 1
	v_max3_f32 v50, v50, v137, v138
	v_bfi_b32 v140, v51, v63, v169
	v_bfe_i32 v51, v142, 26, 1
	v_bfi_b32 v141, v51, v64, v169
	v_bfe_i32 v51, v142, 27, 1
	v_max3_f32 v50, v50, v139, v140
	v_bfi_b32 v142, v51, v65, v169
	v_lshrrev_b32_e32 v51, v179, v117
	v_bfe_i32 v52, v51, 0, 1
	v_bfi_b32 v143, v52, v18, v169
	v_max3_f32 v50, v50, v141, v142
	v_bfe_i32 v18, v51, 1, 1
	v_bfi_b32 v144, v18, v19, v169
	v_bfe_i32 v19, v51, 2, 1
	v_bfi_b32 v145, v19, v20, v169
	v_bfe_i32 v19, v51, 3, 1
	v_max3_f32 v18, v50, v143, v144
	v_bfi_b32 v146, v19, v21, v169
	v_bfe_i32 v19, v51, 8, 1
	v_bfi_b32 v147, v19, v22, v169
	v_bfe_i32 v19, v51, 9, 1
	v_max3_f32 v18, v18, v145, v146
	v_bfi_b32 v148, v19, v23, v169
	v_bfe_i32 v19, v51, 10, 1
	v_bfi_b32 v149, v19, v24, v169
	v_bfe_i32 v19, v51, 11, 1
	v_max3_f32 v18, v18, v147, v148
	v_bfi_b32 v150, v19, v25, v169
	v_bfe_i32 v19, v51, 16, 1
	v_bfi_b32 v151, v19, v26, v169
	v_bfe_i32 v19, v51, 17, 1
	v_max3_f32 v18, v18, v149, v150
	v_bfi_b32 v152, v19, v27, v169
	v_bfe_i32 v19, v51, 18, 1
	v_bfi_b32 v153, v19, v28, v169
	v_bfe_i32 v19, v51, 19, 1
	v_max3_f32 v18, v18, v151, v152
	v_bfi_b32 v154, v19, v29, v169
	v_bfe_i32 v19, v51, 24, 1
	v_bfi_b32 v155, v19, v30, v169
	v_bfe_i32 v19, v51, 25, 1
	v_max3_f32 v18, v18, v153, v154
	v_bfi_b32 v156, v19, v31, v169
	v_bfe_i32 v19, v51, 26, 1
	v_bfi_b32 v157, v19, v32, v169
	v_bfe_i32 v19, v51, 27, 1
	v_max3_f32 v18, v18, v155, v156
	v_bfi_b32 v188, v19, v33, v169
	v_max3_f32 v18, v18, v157, v188
	v_sub_f32_e32 v19, v18, v186
	v_cmp_lt_f32_e32 vcc, s96, v19
	s_cbranch_vccz .LBB0_330
	v_and_b32_e32 v20, 64, v170
	v_xor_b32_e32 v19, 32, v170
	v_add_u32_e32 v20, 64, v20
	v_cmp_lt_i32_e32 vcc, v19, v20
	s_nop 1
	v_cndmask_b32_e32 v19, v170, v19, vcc
	v_lshlrev_b32_e32 v19, 2, v19
	ds_bpermute_b32 v19, v19, v18
	s_waitcnt lgkmcnt(0)
	v_max3_f32 v117, v186, v18, v19
	v_sub_f32_e32 v18, v186, v117
	v_exp_f32_e32 v50, v18
	v_mov_b32_e32 v186, v117
	v_mul_f32_e32 v187, v0, v50
	v_pk_mul_f32 v[32:33], v[48:49], v[50:51] op_sel_hi:[1,0]
	v_pk_mul_f32 v[30:31], v[46:47], v[50:51] op_sel_hi:[1,0]
	v_pk_mul_f32 v[28:29], v[44:45], v[50:51] op_sel_hi:[1,0]
	v_pk_mul_f32 v[26:27], v[42:43], v[50:51] op_sel_hi:[1,0]
	v_pk_mul_f32 v[24:25], v[40:41], v[50:51] op_sel_hi:[1,0]
	v_pk_mul_f32 v[22:23], v[38:39], v[50:51] op_sel_hi:[1,0]
	v_pk_mul_f32 v[20:21], v[36:37], v[50:51] op_sel_hi:[1,0]
	v_pk_mul_f32 v[18:19], v[34:35], v[50:51] op_sel_hi:[1,0]
	v_pk_mul_f32 v[64:65], v[16:17], v[50:51] op_sel_hi:[1,0]
	v_pk_mul_f32 v[62:63], v[14:15], v[50:51] op_sel_hi:[1,0]
	v_pk_mul_f32 v[60:61], v[12:13], v[50:51] op_sel_hi:[1,0]
	v_pk_mul_f32 v[58:59], v[10:11], v[50:51] op_sel_hi:[1,0]
	v_pk_mul_f32 v[56:57], v[8:9], v[50:51] op_sel_hi:[1,0]
	v_pk_mul_f32 v[54:55], v[6:7], v[50:51] op_sel_hi:[1,0]
	v_pk_mul_f32 v[52:53], v[4:5], v[50:51] op_sel_hi:[1,0]
	v_pk_mul_f32 v[50:51], v[2:3], v[50:51] op_sel_hi:[1,0]
	s_branch .LBB0_331

; DI unsigned pk2(float lo, float hi) { unsigned r; asm("v_cvt_pk_bf16_f32 %0, %1, %2" : "=v"(r) : "v"(lo), "v"(hi)); return r; }
; DI void attn_item(const P& p, bool isS, int b, int h, int qblk, char* lds) {
;     ...
;   const float ltot = lsum + __shfl_xor(lsum, 32);
;   const float inv = 1.f / ltot;
;   if (wvalid) {
;     bf16_t* za = (bf16_t*)(p.ws + W_ZA) + (size_t)qrow * 512 + h * 64;
; #pragma unroll
;     for (int db = 0; db < 2; ++db)
; #pragma unroll
;       for (int g4 = 0; g4 < 4; ++g4) {
;         const int d = db * 32 + 8 * g4 + 4 * hl;
;         const u32x2 z = *(const u32x2*)(za + d);
;         const float z0 = __uint_as_float(z.x << 16), z1 = __uint_as_float(z.x & 0xffff0000u), z2 = __uint_as_float(z.y << 16), z3 = __uint_as_float(z.y & 0xffff0000u);
;         *(u32x2*)(za + d) = u32x2{pk2(ot[db][4 * g4] * inv * z0, ot[db][4 * g4 + 1] * inv * z1), pk2(ot[db][4 * g4 + 2] * inv * z2, ot[db][4 * g4 + 3] * inv * z3)};
;       }
;   }
.LBB0_333:
	v_and_b32_e32 v19, 64, v170
	v_xor_b32_e32 v18, 32, v170
	v_add_u32_e32 v19, 64, v19
	v_cmp_lt_i32_e32 vcc, v18, v19
	s_nop 1
	v_cndmask_b32_e32 v18, v170, v18, vcc
	v_lshlrev_b32_e32 v18, 2, v18
	ds_bpermute_b32 v18, v18, v0
	s_andn2_b64 vcc, exec, s[10:11]
	s_cbranch_vccnz .LBB0_285
	s_waitcnt lgkmcnt(0)
	v_add_f32_e32 v0, v0, v18
	v_rcp_f32_e32 v20, v0
	v_lshl_add_u64 v[18:19], v[118:119], 1, s[8:9]
	v_lshlrev_b32_e32 v0, 1, v179
	v_lshl_add_u64 v[18:19], v[18:19], 0, v[0:1]
	global_load_dwordx2 v[22:23], v[18:19], off
	v_mul_f32_e32 v2, v2, v20
	s_waitcnt vmcnt(0)
	v_lshlrev_b32_e32 v0, 16, v22
	v_and_b32_e32 v21, 0xffff0000, v22
	v_mul_f32_e32 v22, v34, v20
	v_mul_f32_e32 v0, v22, v0
	v_mul_f32_e32 v22, v35, v20
	v_mul_f32_e32 v21, v22, v21
	v_lshlrev_b32_e32 v24, 16, v23
	v_and_b32_e32 v23, 0xffff0000, v23
	v_cvt_pk_bf16_f32 v22, v0, v21
	v_mul_f32_e32 v0, v36, v20
	v_mul_f32_e32 v21, v37, v20
	v_mul_f32_e32 v0, v0, v24
	v_mul_f32_e32 v21, v21, v23
	v_cvt_pk_bf16_f32 v23, v0, v21
	global_store_dwordx2 v[18:19], v[22:23], off
	global_load_dwordx2 v[22:23], v[18:19], off offset:16
	s_waitcnt vmcnt(0)
	v_lshlrev_b32_e32 v0, 16, v22
	v_and_b32_e32 v21, 0xffff0000, v22
	v_mul_f32_e32 v22, v38, v20
	v_mul_f32_e32 v0, v22, v0
	v_mul_f32_e32 v22, v39, v20
	v_mul_f32_e32 v21, v22, v21
	v_lshlrev_b32_e32 v24, 16, v23
	v_and_b32_e32 v23, 0xffff0000, v23
	v_cvt_pk_bf16_f32 v22, v0, v21
	v_mul_f32_e32 v0, v40, v20
	v_mul_f32_e32 v21, v41, v20
	v_mul_f32_e32 v0, v0, v24
	v_mul_f32_e32 v21, v21, v23
	v_cvt_pk_bf16_f32 v23, v0, v21
	global_store_dwordx2 v[18:19], v[22:23], off offset:16
	global_load_dwordx2 v[22:23], v[18:19], off offset:32
	s_waitcnt vmcnt(0)
	v_lshlrev_b32_e32 v0, 16, v22
	v_and_b32_e32 v21, 0xffff0000, v22
	v_mul_f32_e32 v22, v42, v20
	v_mul_f32_e32 v0, v22, v0
	v_mul_f32_e32 v22, v43, v20
	v_mul_f32_e32 v21, v22, v21
	v_lshlrev_b32_e32 v24, 16, v23
	v_and_b32_e32 v23, 0xffff0000, v23
	v_cvt_pk_bf16_f32 v22, v0, v21
	v_mul_f32_e32 v0, v44, v20
	v_mul_f32_e32 v21, v45, v20
	v_mul_f32_e32 v0, v0, v24
	v_mul_f32_e32 v21, v21, v23
	v_cvt_pk_bf16_f32 v23, v0, v21
	global_store_dwordx2 v[18:19], v[22:23], off offset:32
	global_load_dwordx2 v[22:23], v[18:19], off offset:48
	s_waitcnt vmcnt(0)
	v_lshlrev_b32_e32 v0, 16, v22
	v_and_b32_e32 v21, 0xffff0000, v22
	v_mul_f32_e32 v22, v46, v20
	v_mul_f32_e32 v0, v22, v0
	v_mul_f32_e32 v22, v47, v20
	v_mul_f32_e32 v21, v22, v21
	v_lshlrev_b32_e32 v24, 16, v23
	v_and_b32_e32 v23, 0xffff0000, v23
	v_cvt_pk_bf16_f32 v22, v0, v21
	v_mul_f32_e32 v0, v48, v20
	v_mul_f32_e32 v21, v49, v20
	v_mul_f32_e32 v0, v0, v24
	v_mul_f32_e32 v21, v21, v23
	v_cvt_pk_bf16_f32 v23, v0, v21
	global_store_dwordx2 v[18:19], v[22:23], off offset:48
	global_load_dwordx2 v[22:23], v[18:19], off offset:64
	s_waitcnt vmcnt(0)
	v_lshlrev_b32_e32 v0, 16, v22
	v_and_b32_e32 v21, 0xffff0000, v22
	v_mul_f32_e32 v0, v2, v0
	v_mul_f32_e32 v2, v3, v20
	v_lshlrev_b32_e32 v22, 16, v23
	v_and_b32_e32 v23, 0xffff0000, v23
	v_mul_f32_e32 v2, v2, v21
	v_mul_f32_e32 v3, v5, v20
	v_cvt_pk_bf16_f32 v2, v0, v2
	v_mul_f32_e32 v0, v4, v20
	v_mul_f32_e32 v3, v3, v23
	v_mul_f32_e32 v0, v0, v22
	v_cvt_pk_bf16_f32 v3, v0, v3
	global_store_dwordx2 v[18:19], v[2:3], off offset:64
	global_load_dwordx2 v[2:3], v[18:19], off offset:80
	v_mul_f32_e32 v5, v6, v20
	s_waitcnt vmcnt(0)
	v_lshlrev_b32_e32 v0, 16, v2
	v_and_b32_e32 v2, 0xffff0000, v2
	v_mul_f32_e32 v0, v5, v0
	v_mul_f32_e32 v5, v7, v20
	v_mul_f32_e32 v2, v5, v2
	v_lshlrev_b32_e32 v4, 16, v3
	v_cvt_pk_bf16_f32 v2, v0, v2
	v_mul_f32_e32 v0, v8, v20
	v_and_b32_e32 v3, 0xffff0000, v3
	v_mul_f32_e32 v0, v0, v4
	v_mul_f32_e32 v4, v9, v20
	v_mul_f32_e32 v3, v4, v3
	v_cvt_pk_bf16_f32 v3, v0, v3
	global_store_dwordx2 v[18:19], v[2:3], off offset:80
	global_load_dwordx2 v[2:3], v[18:19], off offset:96
	v_mul_f32_e32 v5, v10, v20
	s_waitcnt vmcnt(0)
	v_lshlrev_b32_e32 v0, 16, v2
	v_and_b32_e32 v2, 0xffff0000, v2
	v_mul_f32_e32 v0, v5, v0
	v_mul_f32_e32 v5, v11, v20
	v_mul_f32_e32 v2, v5, v2
	v_lshlrev_b32_e32 v4, 16, v3
	v_cvt_pk_bf16_f32 v2, v0, v2
	v_mul_f32_e32 v0, v12, v20
	v_and_b32_e32 v3, 0xffff0000, v3
	v_mul_f32_e32 v0, v0, v4
	v_mul_f32_e32 v4, v13, v20
	v_mul_f32_e32 v3, v4, v3
	v_cvt_pk_bf16_f32 v3, v0, v3
	global_store_dwordx2 v[18:19], v[2:3], off offset:96
	global_load_dwordx2 v[2:3], v[18:19], off offset:112
	v_mul_f32_e32 v5, v14, v20
	s_waitcnt vmcnt(0)
	v_lshlrev_b32_e32 v0, 16, v2
	v_and_b32_e32 v2, 0xffff0000, v2
	v_mul_f32_e32 v0, v5, v0
	v_mul_f32_e32 v5, v15, v20
	v_mul_f32_e32 v2, v5, v2
	v_lshlrev_b32_e32 v4, 16, v3
	v_cvt_pk_bf16_f32 v2, v0, v2
	v_mul_f32_e32 v0, v16, v20
	v_and_b32_e32 v3, 0xffff0000, v3
	v_mul_f32_e32 v0, v0, v4
	v_mul_f32_e32 v4, v17, v20
	v_mul_f32_e32 v3, v4, v3
	v_cvt_pk_bf16_f32 v3, v0, v3
	global_store_dwordx2 v[18:19], v[2:3], off offset:112
	s_branch .LBB0_285

; DI int tidx() { int t = __builtin_amdgcn_workitem_id_x(); asm volatile("" : "+v"(t)); return t; }
; DI void gemm_tile(const bf16_t* __restrict__ A, int lda, const bf16_t* __restrict__ Bt, int ldb, int bvalid, int K, f32x4 (&acc)[4][4], char* lds, bool preloaded = false) {
;   const int tid = tidx(), lane = tid & 63, wave = __builtin_amdgcn_readfirstlane(tid >> 6);
;   const int wm = wave >> 1, wn = wave & 1;
;   const int lr = tid >> 3, lc = tid & 7;
;   const int fr = lane & 15, fq = lane >> 4;
;   const int fx = (fr >> 1) & 7;
;   const bf16_t* ap = A + (size_t)lr * lda + ((lc ^ ((lr >> 1) & 7)) << 3);
;   const bf16_t* bp = Bt + ((lc ^ ((lr >> 1) & 7)) << 3);
;   typedef __attribute__((address_space(1))) const unsigned gptr_t;
;   typedef __attribute__((address_space(3))) unsigned lptr_t;
;   const unsigned lbase = (unsigned)(size_t)lds + (unsigned)tid * 16u;
; DI void phaseA_tile(const P& p, int layer, int mt, int nt, char* lds) {
;   const int tid = tidx(), lane = tid & 63, wave = __builtin_amdgcn_readfirstlane(tid >> 6);
;   const int row0 = mt * 128, col0 = nt * 128;
;   const int bvalid = (NP - col0) < 128 ? 64 : 128;
;   float* rr = (float*)(lds + RR_OFF);
;   __syncthreads();
;   const float* sp = (const float*)(p.ws + W_SS) + (size_t)(row0 + (tid & 127)) * 16;
;   const f32x4 ssa = *(const f32x4*)sp, ssb = *(const f32x4*)(sp + 4), ssc = *(const f32x4*)(sp + 8), ssd = *(const f32x4*)(sp + 12);
;   f32x4 acc[4][4];
;   zero_acc(acc);
;   gemm_tile((const bf16_t*)(p.ws + W_XB) + (size_t)row0 * DM, DM, (const bf16_t*)(p.ws + W_WIN) + ((size_t)layer * NP + col0) * 1024, 1024, bvalid, 1024, acc, lds);
.LBB0_1192:
	s_lshl_b32 s10, s36, 7
	s_ashr_i32 s11, s10, 31
	v_mov_b32_e32 v92, v158
	s_lshl_b32 s0, s37, 7
	s_lshl_b64 s[4:5], s[10:11], 11
	s_add_u32 s12, s74, s4
	v_and_b32_e32 v0, 0x7f, v92
	s_addc_u32 s13, s75, s5
	s_ashr_i32 s1, s0, 31
	v_or_b32_e32 v2, s10, v0
	s_add_u32 s14, s31, s0
	v_ashrrev_i32_e32 v3, 31, v2
	s_addc_u32 s15, s30, s1
	v_lshlrev_b64 v[2:3], 6, v[2:3]
	s_lshl_b64 s[14:15], s[14:15], 11
	v_lshl_add_u64 v[2:3], s[66:67], 0, v[2:3]
	v_mov_b32_e32 v16, v158
	s_add_u32 s14, s90, s14
	s_waitcnt vmcnt(63) expcnt(7) lgkmcnt(15)
	s_barrier
	global_load_dwordx4 v[66:69], v[2:3], off offset:48
	global_load_dwordx4 v[70:73], v[2:3], off offset:32
	global_load_dwordx4 v[74:77], v[2:3], off offset:16
	global_load_dwordx4 v[78:81], v[2:3], off
	s_addc_u32 s15, s91, s15
	v_ashrrev_i32_e32 v2, 3, v16
	v_lshrrev_b32_e32 v17, 4, v16
	v_ashrrev_i32_e32 v3, 31, v2
	v_xor_b32_e32 v0, v17, v16
	s_cmp_gt_i32 s37, 41
	v_lshlrev_b64 v[4:5], 11, v[2:3]
	v_lshlrev_b32_e32 v0, 4, v0
	v_lshl_add_u64 v[6:7], s[12:13], 0, v[4:5]
	v_and_b32_e32 v0, 0x70, v0
	v_lshlrev_b32_e32 v93, 4, v16
	s_cselect_b32 s12, 63, 0x7f
	v_lshl_add_u64 v[6:7], v[6:7], 0, v[0:1]
	v_lshl_add_u64 v[8:9], s[14:15], 0, v[0:1]
	v_add_u32_e32 v3, 0x4000, v93
	v_readfirstlane_b32 s13, v93
	v_and_b32_e32 v0, s12, v2
	s_mov_b32 m0, s13
	v_lshlrev_b32_e32 v0, 11, v0
	v_readfirstlane_b32 s13, v3
	v_add_u32_e32 v3, 0x1000, v93
	global_load_lds_dwordx4 v[6:7], off
	v_lshl_add_u64 v[10:11], v[8:9], 0, v[0:1]
	s_mov_b32 m0, s13
	s_mov_b64 s[14:15], 0x10000
	v_readfirstlane_b32 s13, v3
	v_add_u32_e32 v3, 32, v2
	global_load_lds_dwordx4 v[10:11], off
	v_lshl_add_u64 v[10:11], v[6:7], 0, s[14:15]
	s_mov_b32 m0, s13
	v_and_b32_e32 v3, s12, v3
	global_load_lds_dwordx4 v[10:11], off
	v_lshlrev_b32_e32 v10, 11, v3
	v_add_u32_e32 v3, 0x5000, v93
	v_mov_b32_e32 v11, v1
	v_readfirstlane_b32 s13, v3
	v_add_u32_e32 v3, 0x2000, v93
	v_lshl_add_u64 v[12:13], v[8:9], 0, v[10:11]
	s_mov_b32 m0, s13
	v_readfirstlane_b32 s13, v3
	global_load_lds_dwordx4 v[12:13], off
	v_lshl_add_u64 v[12:13], v[6:7], 0, s[60:61]
	s_mov_b32 m0, s13
	v_bitop3_b32 v3, v2, s12, 64 bitop3:0x48
	global_load_lds_dwordx4 v[12:13], off
	v_lshlrev_b32_e32 v12, 11, v3
	v_add_u32_e32 v3, 0x6000, v93
	v_mov_b32_e32 v13, v1
	v_readfirstlane_b32 s13, v3
	v_add_u32_e32 v3, 0x3000, v93
	v_add_u32_e32 v2, 0x60, v2
	v_lshl_add_u64 v[14:15], v[8:9], 0, v[12:13]
	s_mov_b32 m0, s13
	s_mov_b64 s[14:15], 0x30000
	v_readfirstlane_b32 s13, v3
	v_and_b32_e32 v2, s12, v2
	global_load_lds_dwordx4 v[14:15], off
	v_lshl_add_u64 v[6:7], v[6:7], 0, s[14:15]
	s_mov_b32 m0, s13
	v_lshlrev_b32_e32 v2, 11, v2
	v_mov_b32_e32 v3, v1
	global_load_lds_dwordx4 v[6:7], off
	v_lshl_add_u64 v[6:7], v[8:9], 0, v[2:3]
	v_add_u32_e32 v3, 0x7000, v93
	v_readfirstlane_b32 s11, v16
	v_readfirstlane_b32 s12, v3
	s_mov_b32 m0, s12
	s_lshl_b32 s12, s11, 7
	global_load_lds_dwordx4 v[6:7], off
	v_lshlrev_b32_e32 v3, 7, v16
	s_lshl_b32 s11, s11, 6
	v_bfe_u32 v18, v16, 4, 2
	v_bfe_u32 v20, v16, 1, 3
	s_and_b32 s12, s12, 0x2000
	v_and_b32_e32 v3, 0x780, v3
	s_and_b32 s11, s11, 0xffffe000
	v_or_b32_e32 v94, s12, v3
	v_or_b32_e32 v96, s11, v3
	v_bitop3_b32 v3, v18, v20, 4 bitop3:0x36
	v_lshlrev_b32_e32 v95, 4, v3
	v_bitop3_b32 v3, v17, 7, v16 bitop3:0x48
	v_lshlrev_b32_e32 v3, 4, v3
	v_or_b32_e32 v82, v4, v3
	s_lshl_b64 s[0:1], s[0:1], 11
	s_add_u32 s12, s74, s4
	s_addc_u32 s13, s75, s5
	v_readfirstlane_b32 s33, v93
	s_add_u32 s12, s12, 0x80
	s_addc_u32 s13, s13, 0
	v_add_u32_e32 v83, 0x10000, v82
	v_add_u32_e32 v84, 0x20000, v82
	v_add_u32_e32 v85, 0x30000, v82
	s_add_u32 s14, s2, s0
	s_addc_u32 s15, s3, s1
	v_or_b32_e32 v86, v0, v3
	v_or_b32_e32 v87, v10, v3
	v_lshrrev_b32_e32 v19, 1, v16
	v_or_b32_e32 v88, v12, v3
	v_bitop3_b32 v6, v19, v18, 7 bitop3:0x6c
	v_or_b32_e32 v89, v2, v3
	v_mov_b32_e32 v2, 0
	v_lshlrev_b32_e32 v97, 4, v6
	s_mov_b64 s[0:1], 0
	s_mov_b32 s4, 0
	v_mov_b32_e32 v3, 0
	v_mov_b64_e32 v[4:5], v[2:3]
	v_mov_b64_e32 v[6:7], v[2:3]
	v_mov_b64_e32 v[8:9], v[2:3]
	v_mov_b64_e32 v[10:11], v[2:3]
	v_mov_b64_e32 v[12:13], v[2:3]
	v_mov_b64_e32 v[14:15], v[2:3]
	v_mov_b64_e32 v[16:17], v[2:3]
	v_mov_b64_e32 v[18:19], v[2:3]
	v_mov_b64_e32 v[20:21], v[2:3]
	v_mov_b64_e32 v[22:23], v[2:3]
	v_mov_b64_e32 v[24:25], v[2:3]
	v_mov_b64_e32 v[26:27], v[2:3]
	v_mov_b64_e32 v[28:29], v[2:3]
	v_mov_b64_e32 v[30:31], v[2:3]
	v_mov_b64_e32 v[32:33], v[2:3]
	v_mov_b64_e32 v[34:35], v[2:3]
	v_mov_b64_e32 v[36:37], v[2:3]
	v_mov_b64_e32 v[38:39], v[2:3]
	v_mov_b64_e32 v[40:41], v[2:3]
	v_mov_b64_e32 v[42:43], v[2:3]
	v_mov_b64_e32 v[44:45], v[2:3]
	v_mov_b64_e32 v[46:47], v[2:3]
	v_mov_b64_e32 v[48:49], v[2:3]
	v_mov_b64_e32 v[50:51], v[2:3]
	v_mov_b64_e32 v[52:53], v[2:3]
	v_mov_b64_e32 v[54:55], v[2:3]
	v_mov_b64_e32 v[56:57], v[2:3]
	v_mov_b64_e32 v[58:59], v[2:3]
	v_mov_b64_e32 v[60:61], v[2:3]
	v_mov_b64_e32 v[62:63], v[2:3]
	v_mov_b64_e32 v[64:65], v[2:3]
	s_waitcnt vmcnt(0) lgkmcnt(0)
	s_barrier
; #define MFMA16(a, b, c) __builtin_amdgcn_mfma_f32_16x16x32_bf16((a), (b), (c), 0, 0, 0)
; DI void gemm_tile(const bf16_t* __restrict__ A, int lda, const bf16_t* __restrict__ Bt, int ldb, int bvalid, int K, f32x4 (&acc)[4][4], char* lds, bool preloaded = false) {
;     ...
;   auto compute = [&](int st) {
;     const char* base = lds + st * 32768;
;     bf16x8 af[2][4], bfr[2][4];
; #pragma unroll
;     for (int s = 0; s < 2; ++s) {
;       const int ch = ((4 * s + fq) ^ fx) << 4;
; #pragma unroll
;       for (int mi = 0; mi < 4; ++mi) af[s][mi] = *(const bf16x8*)(base + (wm * 64 + mi * 16 + fr) * 128 + ch);
; #pragma unroll
;       for (int ni = 0; ni < 4; ++ni) bfr[s][ni] = *(const bf16x8*)(base + 16384 + (wn * 64 + ni * 16 + fr) * 128 + ch);
;     }
;     __builtin_amdgcn_s_setprio(1);
; #pragma unroll
;     for (int s = 0; s < 2; ++s)
; #pragma unroll
;       for (int mi = 0; mi < 4; ++mi)
; #pragma unroll
;         for (int ni = 0; ni < 4; ++ni) acc[mi][ni] = MFMA16(af[s][mi], bfr[s][ni], acc[mi][ni]);
;     __builtin_amdgcn_s_setprio(0);
;   };
;   const int nk = K >> 6;
;   if (!preloaded) { GLDS(0, 0) }
;   __syncthreads();
;   for (int kt = 0; kt < nk; ++kt) {
;     if (kt + 1 < nk) { GLDS((kt + 1) & 1, (kt + 1) << 6) }
;     compute(kt & 1);
;     __syncthreads();
.LBB0_1193:
	s_add_i32 s5, s4, 0x8000
	s_and_b32 s11, s5, 0x8000
	s_and_b32 s4, s4, 0x8000
	v_or_b32_e32 v0, s4, v97
	v_add_u32_e32 v110, v0, v96
	v_add_u32_e32 v0, v0, v94
	ds_read_b128 v[98:101], v110
	ds_read_b128 v[114:117], v0 offset:16384
	ds_read_b128 v[118:121], v0 offset:18432
	ds_read_b128 v[122:125], v0 offset:20480
	ds_read_b128 v[126:129], v0 offset:22528
	ds_read_b128 v[102:105], v110 offset:2048
	ds_read_b128 v[106:109], v110 offset:4096
	ds_read_b128 v[110:113], v110 offset:6144
	s_add_i32 m0, s33, s11
	v_or_b32_e32 v0, s4, v95
	global_load_lds_dwordx4 v82, s[12:13]
	s_addk_i32 m0, 0x1000
	v_add_u32_e32 v142, v0, v96
	global_load_lds_dwordx4 v83, s[12:13]
	s_addk_i32 m0, 0x1000
	v_add_u32_e32 v0, v0, v94
	global_load_lds_dwordx4 v84, s[12:13]
	s_addk_i32 m0, 0x1000
	ds_read_b128 v[130:133], v142
	global_load_lds_dwordx4 v85, s[12:13]
	s_addk_i32 m0, 0x1000
	ds_read_b128 v[146:149], v0 offset:16384
	global_load_lds_dwordx4 v86, s[14:15]
	s_addk_i32 m0, 0x1000
	ds_read_b128 v[150:153], v0 offset:18432
	global_load_lds_dwordx4 v87, s[14:15]
	s_addk_i32 m0, 0x1000
	ds_read_b128 v[154:157], v0 offset:20480
	global_load_lds_dwordx4 v88, s[14:15]
	s_addk_i32 m0, 0x1000
	ds_read_b128 v[180:183], v0 offset:22528
	global_load_lds_dwordx4 v89, s[14:15]
	ds_read_b128 v[134:137], v142 offset:2048
	ds_read_b128 v[138:141], v142 offset:4096
	ds_read_b128 v[142:145], v142 offset:6144
	s_add_u32 s12, s12, 0x80
	s_addc_u32 s13, s13, 0
	s_add_u32 s14, s14, 0x80
	s_addc_u32 s15, s15, 0
	s_setprio 1
	s_waitcnt lgkmcnt(11)
	v_mfma_f32_16x16x32_bf16 v[62:65], v[98:101], v[114:117], v[62:65]
	v_mfma_f32_16x16x32_bf16 v[58:61], v[98:101], v[118:121], v[58:61]
	v_mfma_f32_16x16x32_bf16 v[54:57], v[98:101], v[122:125], v[54:57]
	v_mfma_f32_16x16x32_bf16 v[50:53], v[98:101], v[126:129], v[50:53]
	s_waitcnt lgkmcnt(8)
	v_mfma_f32_16x16x32_bf16 v[46:49], v[102:105], v[114:117], v[46:49]
	v_mfma_f32_16x16x32_bf16 v[42:45], v[102:105], v[118:121], v[42:45]
	v_mfma_f32_16x16x32_bf16 v[38:41], v[102:105], v[122:125], v[38:41]
	v_mfma_f32_16x16x32_bf16 v[34:37], v[102:105], v[126:129], v[34:37]
	v_mfma_f32_16x16x32_bf16 v[30:33], v[106:109], v[114:117], v[30:33]
	v_mfma_f32_16x16x32_bf16 v[26:29], v[106:109], v[118:121], v[26:29]
	v_mfma_f32_16x16x32_bf16 v[22:25], v[106:109], v[122:125], v[22:25]
	v_mfma_f32_16x16x32_bf16 v[18:21], v[106:109], v[126:129], v[18:21]
	v_mfma_f32_16x16x32_bf16 v[14:17], v[110:113], v[114:117], v[14:17]
	v_mfma_f32_16x16x32_bf16 v[10:13], v[110:113], v[118:121], v[10:13]
	v_mfma_f32_16x16x32_bf16 v[6:9], v[110:113], v[122:125], v[6:9]
	v_mfma_f32_16x16x32_bf16 v[2:5], v[110:113], v[126:129], v[2:5]
	s_waitcnt lgkmcnt(3)
	v_mfma_f32_16x16x32_bf16 v[62:65], v[130:133], v[146:149], v[62:65]
	v_mfma_f32_16x16x32_bf16 v[58:61], v[130:133], v[150:153], v[58:61]
	v_mfma_f32_16x16x32_bf16 v[54:57], v[130:133], v[154:157], v[54:57]
	v_mfma_f32_16x16x32_bf16 v[50:53], v[130:133], v[180:183], v[50:53]
	s_waitcnt lgkmcnt(0)
	v_mfma_f32_16x16x32_bf16 v[46:49], v[134:137], v[146:149], v[46:49]
	v_mfma_f32_16x16x32_bf16 v[42:45], v[134:137], v[150:153], v[42:45]
	v_mfma_f32_16x16x32_bf16 v[38:41], v[134:137], v[154:157], v[38:41]
	v_mfma_f32_16x16x32_bf16 v[34:37], v[134:137], v[180:183], v[34:37]
	v_mfma_f32_16x16x32_bf16 v[30:33], v[138:141], v[146:149], v[30:33]
	v_mfma_f32_16x16x32_bf16 v[26:29], v[138:141], v[150:153], v[26:29]
	v_mfma_f32_16x16x32_bf16 v[22:25], v[138:141], v[154:157], v[22:25]
	v_mfma_f32_16x16x32_bf16 v[18:21], v[138:141], v[180:183], v[18:21]
	v_mfma_f32_16x16x32_bf16 v[14:17], v[142:145], v[146:149], v[14:17]
	v_mfma_f32_16x16x32_bf16 v[10:13], v[142:145], v[150:153], v[10:13]
	v_mfma_f32_16x16x32_bf16 v[6:9], v[142:145], v[154:157], v[6:9]
	v_mfma_f32_16x16x32_bf16 v[2:5], v[142:145], v[180:183], v[2:5]
	s_setprio 0
	s_add_u32 s0, s0, 0x80
	s_cmpk_eq_i32 s0, 0x780
	s_mov_b32 s4, s5
	s_waitcnt vmcnt(0)
	s_barrier
	s_cbranch_scc0 .LBB0_1193
; #define MFMA16(a, b, c) __builtin_amdgcn_mfma_f32_16x16x32_bf16((a), (b), (c), 0, 0, 0)
; DI void gemm_tile(const bf16_t* __restrict__ A, int lda, const bf16_t* __restrict__ Bt, int ldb, int bvalid, int K, f32x4 (&acc)[4][4], char* lds, bool preloaded = false) {
;     ...
;   auto compute = [&](int st) {
;     const char* base = lds + st * 32768;
;     bf16x8 af[2][4], bfr[2][4];
; #pragma unroll
;     for (int s = 0; s < 2; ++s) {
;       const int ch = ((4 * s + fq) ^ fx) << 4;
; #pragma unroll
;       for (int mi = 0; mi < 4; ++mi) af[s][mi] = *(const bf16x8*)(base + (wm * 64 + mi * 16 + fr) * 128 + ch);
; #pragma unroll
;       for (int ni = 0; ni < 4; ++ni) bfr[s][ni] = *(const bf16x8*)(base + 16384 + (wn * 64 + ni * 16 + fr) * 128 + ch);
;     }
;     __builtin_amdgcn_s_setprio(1);
; #pragma unroll
;     for (int s = 0; s < 2; ++s)
; #pragma unroll
;       for (int mi = 0; mi < 4; ++mi)
; #pragma unroll
;         for (int ni = 0; ni < 4; ++ni) acc[mi][ni] = MFMA16(af[s][mi], bfr[s][ni], acc[mi][ni]);
;     __builtin_amdgcn_s_setprio(0);
;   };
;   const int nk = K >> 6;
;   if (!preloaded) { GLDS(0, 0) }
;   __syncthreads();
;   for (int kt = 0; kt < nk; ++kt) {
;     if (kt + 1 < nk) { GLDS((kt + 1) & 1, (kt + 1) << 6) }
;     compute(kt & 1);
;     __syncthreads();
; DI void phaseA_tile(const P& p, int layer, int mt, int nt, char* lds) {
;     ...
;   if (tid < 128) {
;     const float ss = (ssa.x + ssa.y + ssa.z + ssa.w) + (ssb.x + ssb.y + ssb.z + ssb.w) + (ssc.x + ssc.y + ssc.z + ssc.w) + (ssd.x + ssd.y + ssd.z + ssd.w);
;     rr[tid] = rsqrtf(ss * (1.f / 1024.f) + 1e-6f);
;   }
	v_add_u32_e32 v0, v97, v96
	ds_read_b128 v[82:85], v0 offset:32768
	ds_read_b128 v[86:89], v0 offset:34816
	ds_read_b128 v[98:101], v0 offset:36864
	ds_read_b128 v[102:105], v0 offset:38912
	v_add_u32_e32 v0, v97, v94
	ds_read_b128 v[106:109], v0 offset:49152
	ds_read_b128 v[110:113], v0 offset:51200
	ds_read_b128 v[114:117], v0 offset:53248
	ds_read_b128 v[118:121], v0 offset:55296
	v_add_u32_e32 v0, v95, v96
	ds_read_b128 v[122:125], v0 offset:32768
	ds_read_b128 v[126:129], v0 offset:34816
	ds_read_b128 v[130:133], v0 offset:36864
	ds_read_b128 v[134:137], v0 offset:38912
	v_add_u32_e32 v0, v95, v94
	ds_read_b128 v[94:97], v0 offset:49152
	ds_read_b128 v[138:141], v0 offset:51200
	ds_read_b128 v[142:145], v0 offset:53248
	ds_read_b128 v[146:149], v0 offset:55296
	s_movk_i32 s33, 0x210
	v_readfirstlane_b32 s4, v92
	s_setprio 1
	s_waitcnt lgkmcnt(11)
	v_mfma_f32_16x16x32_bf16 v[62:65], v[82:85], v[106:109], v[62:65]
	s_waitcnt lgkmcnt(10)
	v_mfma_f32_16x16x32_bf16 v[58:61], v[82:85], v[110:113], v[58:61]
	s_waitcnt lgkmcnt(9)
	v_mfma_f32_16x16x32_bf16 v[54:57], v[82:85], v[114:117], v[54:57]
	s_waitcnt lgkmcnt(8)
	v_mfma_f32_16x16x32_bf16 v[50:53], v[82:85], v[118:121], v[50:53]
	v_mfma_f32_16x16x32_bf16 v[46:49], v[86:89], v[106:109], v[46:49]
	v_mfma_f32_16x16x32_bf16 v[42:45], v[86:89], v[110:113], v[42:45]
	v_mfma_f32_16x16x32_bf16 v[38:41], v[86:89], v[114:117], v[38:41]
	v_mfma_f32_16x16x32_bf16 v[34:37], v[86:89], v[118:121], v[34:37]
	v_mfma_f32_16x16x32_bf16 v[30:33], v[98:101], v[106:109], v[30:33]
	v_mfma_f32_16x16x32_bf16 v[26:29], v[98:101], v[110:113], v[26:29]
	v_mfma_f32_16x16x32_bf16 v[22:25], v[98:101], v[114:117], v[22:25]
	v_mfma_f32_16x16x32_bf16 v[18:21], v[98:101], v[118:121], v[18:21]
	v_mfma_f32_16x16x32_bf16 v[14:17], v[102:105], v[106:109], v[14:17]
	v_mfma_f32_16x16x32_bf16 v[10:13], v[102:105], v[110:113], v[10:13]
	v_mfma_f32_16x16x32_bf16 v[6:9], v[102:105], v[114:117], v[6:9]
	v_mfma_f32_16x16x32_bf16 v[2:5], v[102:105], v[118:121], v[2:5]
	s_waitcnt lgkmcnt(3)
	v_mfma_f32_16x16x32_bf16 v[62:65], v[122:125], v[94:97], v[62:65]
	s_waitcnt lgkmcnt(2)
	v_mfma_f32_16x16x32_bf16 v[58:61], v[122:125], v[138:141], v[58:61]
	s_waitcnt lgkmcnt(1)
	v_mfma_f32_16x16x32_bf16 v[54:57], v[122:125], v[142:145], v[54:57]
	s_waitcnt lgkmcnt(0)
	v_mfma_f32_16x16x32_bf16 v[50:53], v[122:125], v[146:149], v[50:53]
	v_mfma_f32_16x16x32_bf16 v[46:49], v[126:129], v[94:97], v[46:49]
	v_mfma_f32_16x16x32_bf16 v[42:45], v[126:129], v[138:141], v[42:45]
	v_mfma_f32_16x16x32_bf16 v[38:41], v[126:129], v[142:145], v[38:41]
	v_mfma_f32_16x16x32_bf16 v[34:37], v[126:129], v[146:149], v[34:37]
	v_mfma_f32_16x16x32_bf16 v[30:33], v[130:133], v[94:97], v[30:33]
	v_mfma_f32_16x16x32_bf16 v[26:29], v[130:133], v[138:141], v[26:29]
	v_mfma_f32_16x16x32_bf16 v[22:25], v[130:133], v[142:145], v[22:25]
	v_mfma_f32_16x16x32_bf16 v[18:21], v[130:133], v[146:149], v[18:21]
	v_mfma_f32_16x16x32_bf16 v[14:17], v[134:137], v[94:97], v[14:17]
	v_mfma_f32_16x16x32_bf16 v[10:13], v[134:137], v[138:141], v[10:13]
	v_mfma_f32_16x16x32_bf16 v[6:9], v[134:137], v[142:145], v[6:9]
	v_mfma_f32_16x16x32_bf16 v[2:5], v[134:137], v[146:149], v[2:5]
	s_setprio 0
	v_cmp_gt_i32_e32 vcc, s92, v92
	s_barrier
	s_and_saveexec_b64 s[0:1], vcc
	s_cbranch_execz .LBB0_1196
	v_mov_b32_e32 v82, v78
	v_mov_b32_e32 v83, v74
	v_mov_b32_e32 v74, v79
	v_pk_add_f32 v[74:75], v[82:83], v[74:75]
	v_mov_b32_e32 v78, v80
	v_mov_b32_e32 v79, v76
	v_pk_add_f32 v[74:75], v[78:79], v[74:75]
	v_mov_b32_e32 v76, v81
	v_pk_add_f32 v[74:75], v[76:77], v[74:75]
	v_mov_b32_e32 v76, v70
	v_mov_b32_e32 v77, v66
	v_mov_b32_e32 v66, v71
	v_pk_add_f32 v[66:67], v[76:77], v[66:67]
	v_mov_b32_e32 v70, v72
	v_mov_b32_e32 v71, v68
	v_pk_add_f32 v[66:67], v[70:71], v[66:67]
	v_mov_b32_e32 v68, v73
	v_pk_add_f32 v[66:67], v[68:69], v[66:67]
	v_add_f32_e32 v0, v74, v75
	v_add_f32_e32 v0, v0, v66
	v_add_f32_e32 v0, v0, v67
	v_fmamk_f32 v0, v0, 0x3a800000, v160
	s_mov_b32 s5, 0x800000
	v_mul_f32_e32 v66, 0x4b800000, v0
	v_cmp_gt_f32_e32 vcc, s5, v0
	s_nop 1
	v_cndmask_b32_e32 v0, v0, v66, vcc
	v_rsq_f32_e32 v0, v0
	s_nop 0
	v_mul_f32_e32 v66, 0x45800000, v0
	v_cndmask_b32_e32 v0, v0, v66, vcc
	v_lshl_add_u32 v66, v92, 2, v173
	ds_write_b32 v66, v0

; DI unsigned pk2(float lo, float hi) { unsigned r; asm("v_cvt_pk_bf16_f32 %0, %1, %2" : "=v"(r) : "v"(lo), "v"(hi)); return r; }
; DI float siluf_(float v) { return v / (1.f + __expf(-v)); }
; DI void phaseA_tile(const P& p, int layer, int mt, int nt, char* lds) {
;     ...
;     } else if (seg < 16 || (seg >= 45 && seg < 53)) {
;       bf16_t* Z = (bf16_t*)(p.ws + (seg < 16 ? W_ZP : W_ZA)) + (size_t)row * 512 + (seg < 16 ? seg - 8 : seg - 45) * 64 + cc * 4;
;       *(u32x2*)Z = u32x2{pk2(siluf_(v.x), siluf_(v.y)), pk2(siluf_(v.z), siluf_(v.w))};
.LBB0_1276:
	s_and_b64 vcc, exec, s[16:17]
	s_cbranch_vccz .LBB0_1278
	v_mul_f32_e32 v0, 0xbfb8aa3b, v66
	v_exp_f32_e32 v0, v0
	v_ashrrev_i32_e32 v85, 31, v84
	v_lshlrev_b64 v[86:87], 10, v[84:85]
	v_lshl_add_u64 v[86:87], v[80:81], 0, v[86:87]
	v_add_f32_e32 v0, 1.0, v0
	v_rcp_f32_e32 v85, v0
	s_nop 0
	v_mul_f32_e32 v0, v66, v85
	v_mul_f32_e32 v85, 0xbfb8aa3b, v67
	v_exp_f32_e32 v85, v85
	s_nop 0
	v_add_f32_e32 v85, 1.0, v85
	v_rcp_f32_e32 v98, v85
	s_nop 0
	v_mul_f32_e32 v85, v67, v98
	v_cvt_pk_bf16_f32 v98, v0, v85
	v_mul_f32_e32 v0, 0xbfb8aa3b, v68
	v_exp_f32_e32 v0, v0
	s_nop 0
	v_add_f32_e32 v0, 1.0, v0
	v_rcp_f32_e32 v85, v0
	s_nop 0
	v_mul_f32_e32 v0, v68, v85
	v_mul_f32_e32 v85, 0xbfb8aa3b, v69
	v_exp_f32_e32 v85, v85
	s_nop 0
	v_add_f32_e32 v85, 1.0, v85
	v_rcp_f32_e32 v99, v85
	s_nop 0
	v_mul_f32_e32 v85, v69, v99
	v_cvt_pk_bf16_f32 v99, v0, v85
	global_store_dwordx2 v[86:87], v[98:99], off

; DI unsigned pk2(float lo, float hi) { unsigned r; asm("v_cvt_pk_bf16_f32 %0, %1, %2" : "=v"(r) : "v"(lo), "v"(hi)); return r; }
; DI float siluf_(float v) { return v / (1.f + __expf(-v)); }
; DI void phaseA_tile(const P& p, int layer, int mt, int nt, char* lds) {
;     ...
;     } else if (seg < 16 || (seg >= 45 && seg < 53)) {
;       bf16_t* Z = (bf16_t*)(p.ws + (seg < 16 ? W_ZP : W_ZA)) + (size_t)row * 512 + (seg < 16 ? seg - 8 : seg - 45) * 64 + cc * 4;
;       *(u32x2*)Z = u32x2{pk2(siluf_(v.x), siluf_(v.y)), pk2(siluf_(v.z), siluf_(v.w))};
.LBB0_1296:
	s_and_b64 vcc, exec, s[16:17]
	s_cbranch_vccz .LBB0_1298
	v_mul_f32_e32 v0, 0xbfb8aa3b, v66
	v_exp_f32_e32 v0, v0
	v_ashrrev_i32_e32 v87, 31, v86
	v_lshlrev_b64 v[84:85], 10, v[86:87]
	v_lshl_add_u64 v[84:85], v[80:81], 0, v[84:85]
	v_add_f32_e32 v0, 1.0, v0
	v_rcp_f32_e32 v87, v0
	s_nop 0
	v_mul_f32_e32 v0, v66, v87
	v_mul_f32_e32 v87, 0xbfb8aa3b, v67
	v_exp_f32_e32 v87, v87
	s_nop 0
	v_add_f32_e32 v87, 1.0, v87
	v_rcp_f32_e32 v97, v87
	s_nop 0
	v_mul_f32_e32 v87, v67, v97
	v_cvt_pk_bf16_f32 v98, v0, v87
	v_mul_f32_e32 v0, 0xbfb8aa3b, v68
	v_exp_f32_e32 v0, v0
	s_nop 0
	v_add_f32_e32 v0, 1.0, v0
	v_rcp_f32_e32 v87, v0
	s_nop 0
	v_mul_f32_e32 v0, v68, v87
	v_mul_f32_e32 v87, 0xbfb8aa3b, v69
	v_exp_f32_e32 v87, v87
	s_nop 0
	v_add_f32_e32 v87, 1.0, v87
	v_rcp_f32_e32 v97, v87
	s_nop 0
	v_mul_f32_e32 v87, v69, v97
	v_cvt_pk_bf16_f32 v99, v0, v87
	global_store_dwordx2 v[84:85], v[98:99], off

; DI float sigmoidf_(float v) { return 1.f / (1.f + __expf(-v)); }
; DI void phaseA_tile(const P& p, int layer, int mt, int nt, char* lds) {
;     ...
;   if (seg >= 53) {
;     const bool isP = seg < 69;
;     unsigned* G = (unsigned*)(p.ws + (isP ? W_GP : W_GA)) + ((size_t)(((row0 >> 6) + wm) * 16 + (isP ? seg - 53 : seg - 69)) * 64 + lane) * 16;
; #pragma unroll
;     for (int mi = 0; mi < 4; ++mi) {
;       unsigned wv[4];
; #pragma unroll
;       for (int ni = 0; ni < 4; ++ni) {
;         unsigned w_ = 0u;
; #pragma unroll
;         for (int j = 0; j < 4; ++j) {
;           const float r = rr[wm * 64 + mi * 16 + fq * 4 + j];
;           w_ |= ((unsigned)(int)(sigmoidf_(acc[mi][ni][j] * r) * 255.f + 0.5f)) << (8 * j);
;         }
;         wv[ni] = w_;
;       }
;       *(u32x4*)(G + mi * 4) = u32x4{wv[0], wv[1], wv[2], wv[3]};
;     }
.LBB0_1584:
	s_and_b64 vcc, exec, s[0:1]
	s_cbranch_vccz .LBB0_1183
	v_lshlrev_b32_e32 v66, 2, v127
	v_lshl_add_u32 v66, s11, 2, v66
	v_add_u32_e32 v66, 0x10800, v66
	ds_read_b128 v[68:71], v66
	s_cmpk_lt_u32 s55, 0x45
	s_cselect_b64 s[0:1], -1, 0
	s_and_b64 s[4:5], s[0:1], exec
	s_mov_b32 s4, 0x17ca2000
	s_waitcnt lgkmcnt(0)
	v_mul_f32_e32 v63, v63, v69
	v_mul_f32_e32 v63, 0xbfb8aa3b, v63
	s_cselect_b32 s4, s4, 0x19d22000
	v_exp_f32_e32 v72, v63
	v_mul_f32_e32 v63, v64, v70
	s_add_u32 s4, s90, s4
	v_mul_f32_e32 v63, 0xbfb8aa3b, v63
	s_addc_u32 s5, s91, 0
	s_lshl_b32 s10, s36, 5
	s_lshl_b32 s12, s56, 4
	v_exp_f32_e32 v64, v63
	v_mul_f32_e32 v63, v65, v71
	v_mul_f32_e32 v58, v58, v68
	s_and_b64 s[0:1], s[0:1], exec
	v_mul_f32_e32 v63, 0xbfb8aa3b, v63
	v_mul_f32_e32 v58, 0xbfb8aa3b, v58
	s_movk_i32 s0, 0xffcb
	v_mul_f32_e32 v62, v62, v68
	v_exp_f32_e32 v74, v63
	v_exp_f32_e32 v63, v58
	v_mul_f32_e32 v58, v59, v69
	s_cselect_b32 s0, s0, 0xffffffbb
	s_add_i32 s1, s12, s10
	v_mul_f32_e32 v62, 0xbfb8aa3b, v62
	v_mul_f32_e32 v58, 0xbfb8aa3b, v58
	s_add_i32 s1, s1, s55
	v_exp_f32_e32 v62, v62
	v_exp_f32_e32 v73, v58
	v_mul_f32_e32 v58, v60, v70
	s_add_i32 s0, s1, s0
	v_mul_f32_e32 v58, 0xbfb8aa3b, v58
	s_ashr_i32 s1, s0, 31
	v_exp_f32_e32 v65, v58
	v_mul_f32_e32 v58, v61, v71
	s_lshl_b64 s[0:1], s[0:1], 12
	v_mul_f32_e32 v58, 0xbfb8aa3b, v58
	s_add_u32 s0, s4, s0
	v_exp_f32_e32 v75, v58
	v_pk_add_f32 v[58:59], v[62:63], 1.0 op_sel_hi:[1,0]
	s_addc_u32 s1, s5, s1
	s_mov_b32 s10, 0x437f0000
	v_mul_f32_e32 v55, v55, v69
	v_mul_f32_e32 v55, 0xbfb8aa3b, v55
	v_rcp_f32_e32 v59, v59
	v_mul_f32_e32 v50, v50, v68
	v_mul_f32_e32 v50, 0xbfb8aa3b, v50
	v_mul_f32_e32 v54, v54, v68
	v_rcp_f32_e32 v58, v58
	s_nop 0
	v_pk_fma_f32 v[58:59], v[58:59], s[10:11], 0.5 op_sel_hi:[1,0,0]
	v_mul_f32_e32 v54, 0xbfb8aa3b, v54
	v_cvt_i32_f32_e32 v60, v59
	v_cvt_i32_f32_e32 v61, v58
	v_pk_add_f32 v[58:59], v[72:73], 1.0 op_sel_hi:[1,0]
	v_exp_f32_e32 v54, v54
	v_lshlrev_b32_e32 v0, 6, v152
	v_rcp_f32_e32 v59, v59
	v_rcp_f32_e32 v58, v58
	s_nop 0
	v_pk_fma_f32 v[58:59], v[58:59], s[10:11], 0.5 op_sel_hi:[1,0,0]
	s_nop 0
	v_cvt_i32_f32_e32 v58, v58
	v_cvt_i32_f32_e32 v59, v59
	v_lshlrev_b32_e32 v58, 8, v58
	v_lshlrev_b32_e32 v59, 8, v59
	v_or_b32_e32 v60, v59, v60
	v_or_b32_e32 v61, v58, v61
	v_pk_add_f32 v[58:59], v[64:65], 1.0 op_sel_hi:[1,0]
	s_nop 0
	v_rcp_f32_e32 v59, v59
	v_rcp_f32_e32 v58, v58
	s_nop 0
	v_pk_fma_f32 v[58:59], v[58:59], s[10:11], 0.5 op_sel_hi:[1,0,0]
	s_nop 0
	v_cvt_i32_f32_sdwa v58, v58 dst_sel:WORD_1 dst_unused:UNUSED_PAD src0_sel:DWORD
	v_cvt_i32_f32_sdwa v59, v59 dst_sel:WORD_1 dst_unused:UNUSED_PAD src0_sel:DWORD
	v_or_b32_e32 v61, v61, v58
	v_or_b32_e32 v60, v60, v59
	v_pk_add_f32 v[58:59], v[74:75], 1.0 op_sel_hi:[1,0]
	s_nop 0
	v_rcp_f32_e32 v59, v59
	v_rcp_f32_e32 v58, v58
	s_nop 0
	v_pk_fma_f32 v[58:59], v[58:59], s[10:11], 0.5 op_sel_hi:[1,0,0]
	s_nop 0
	v_cvt_i32_f32_sdwa v59, v59 dst_sel:BYTE_3 dst_unused:UNUSED_PAD src0_sel:DWORD
	v_cvt_i32_f32_sdwa v58, v58 dst_sel:BYTE_3 dst_unused:UNUSED_PAD src0_sel:DWORD
	v_or_b32_e32 v59, v60, v59
	v_exp_f32_e32 v60, v55
	v_mul_f32_e32 v55, v56, v70
	v_mul_f32_e32 v55, 0xbfb8aa3b, v55
	v_exp_f32_e32 v56, v55
	v_mul_f32_e32 v55, v57, v71
	v_mul_f32_e32 v55, 0xbfb8aa3b, v55
	v_exp_f32_e32 v62, v55
	v_exp_f32_e32 v55, v50
	v_mul_f32_e32 v50, v51, v69
	v_mul_f32_e32 v50, 0xbfb8aa3b, v50
	v_or_b32_e32 v58, v61, v58
	v_exp_f32_e32 v61, v50
	v_mul_f32_e32 v50, v52, v70
	v_mul_f32_e32 v50, 0xbfb8aa3b, v50
	v_exp_f32_e32 v57, v50
	v_mul_f32_e32 v50, v53, v71
	v_mul_f32_e32 v50, 0xbfb8aa3b, v50
	v_exp_f32_e32 v63, v50
	v_pk_add_f32 v[50:51], v[54:55], 1.0 op_sel_hi:[1,0]
	s_nop 0
	v_rcp_f32_e32 v51, v51
	v_rcp_f32_e32 v50, v50
	s_nop 0
	v_pk_fma_f32 v[50:51], v[50:51], s[10:11], 0.5 op_sel_hi:[1,0,0]
	s_nop 0
	v_cvt_i32_f32_e32 v52, v51
	v_cvt_i32_f32_e32 v53, v50
	v_pk_add_f32 v[50:51], v[60:61], 1.0 op_sel_hi:[1,0]
	s_nop 0
	v_rcp_f32_e32 v51, v51
	v_rcp_f32_e32 v50, v50
	s_nop 0
	v_pk_fma_f32 v[50:51], v[50:51], s[10:11], 0.5 op_sel_hi:[1,0,0]
	s_nop 0
	v_cvt_i32_f32_e32 v50, v50
	v_cvt_i32_f32_e32 v51, v51
	v_lshlrev_b32_e32 v50, 8, v50
	v_lshlrev_b32_e32 v51, 8, v51
	v_or_b32_e32 v52, v51, v52
	v_or_b32_e32 v53, v50, v53
	v_pk_add_f32 v[50:51], v[56:57], 1.0 op_sel_hi:[1,0]
	s_nop 0
	v_rcp_f32_e32 v51, v51
	v_rcp_f32_e32 v50, v50
	s_nop 0
	v_pk_fma_f32 v[50:51], v[50:51], s[10:11], 0.5 op_sel_hi:[1,0,0]
	s_nop 0
	v_cvt_i32_f32_sdwa v50, v50 dst_sel:WORD_1 dst_unused:UNUSED_PAD src0_sel:DWORD
	v_cvt_i32_f32_sdwa v51, v51 dst_sel:WORD_1 dst_unused:UNUSED_PAD src0_sel:DWORD
	v_or_b32_e32 v53, v53, v50
	v_or_b32_e32 v52, v52, v51
	v_pk_add_f32 v[50:51], v[62:63], 1.0 op_sel_hi:[1,0]
	s_nop 0
	v_rcp_f32_e32 v51, v51
	v_rcp_f32_e32 v50, v50
	s_nop 0
	v_pk_fma_f32 v[50:51], v[50:51], s[10:11], 0.5 op_sel_hi:[1,0,0]
	s_nop 0
	v_cvt_i32_f32_sdwa v50, v50 dst_sel:BYTE_3 dst_unused:UNUSED_PAD src0_sel:DWORD
	v_cvt_i32_f32_sdwa v51, v51 dst_sel:BYTE_3 dst_unused:UNUSED_PAD src0_sel:DWORD
	v_or_b32_e32 v60, v53, v50
	v_or_b32_e32 v61, v52, v51
	ds_read_b128 v[50:53], v66 offset:64
	global_store_dwordx4 v0, v[58:61], s[0:1]
	s_waitcnt lgkmcnt(0)
; DI float sigmoidf_(float v) { return 1.f / (1.f + __expf(-v)); }
; DI void phaseA_tile(const P& p, int layer, int mt, int nt, char* lds) {
;     ...
;     for (int mi = 0; mi < 4; ++mi) {
;       unsigned wv[4];
; #pragma unroll
;       for (int ni = 0; ni < 4; ++ni) {
;         unsigned w_ = 0u;
; #pragma unroll
;         for (int j = 0; j < 4; ++j) {
;           const float r = rr[wm * 64 + mi * 16 + fq * 4 + j];
;           w_ |= ((unsigned)(int)(sigmoidf_(acc[mi][ni][j] * r) * 255.f + 0.5f)) << (8 * j);
;         }
;         wv[ni] = w_;
;       }
;       *(u32x4*)(G + mi * 4) = u32x4{wv[0], wv[1], wv[2], wv[3]};
;     }
	v_mul_f32_e32 v46, v46, v50
	v_mul_f32_e32 v42, v42, v50
	v_mul_f32_e32 v46, 0xbfb8aa3b, v46
	v_mul_f32_e32 v42, 0xbfb8aa3b, v42
	v_exp_f32_e32 v54, v46
	v_mul_f32_e32 v46, v47, v51
	v_exp_f32_e32 v55, v42
	v_mul_f32_e32 v42, v43, v51
	v_mul_f32_e32 v46, 0xbfb8aa3b, v46
	v_mul_f32_e32 v42, 0xbfb8aa3b, v42
	v_exp_f32_e32 v56, v46
	v_mul_f32_e32 v46, v48, v52
	v_exp_f32_e32 v57, v42
	v_mul_f32_e32 v42, v44, v52
	v_mul_f32_e32 v46, 0xbfb8aa3b, v46
	v_mul_f32_e32 v42, 0xbfb8aa3b, v42
	v_exp_f32_e32 v48, v46
	v_mul_f32_e32 v46, v49, v53
	v_exp_f32_e32 v49, v42
	v_mul_f32_e32 v42, v45, v53
	v_mul_f32_e32 v42, 0xbfb8aa3b, v42
	v_exp_f32_e32 v47, v42
	v_pk_add_f32 v[42:43], v[54:55], 1.0 op_sel_hi:[1,0]
	v_mul_f32_e32 v46, 0xbfb8aa3b, v46
	v_exp_f32_e32 v46, v46
	v_mul_f32_e32 v39, v39, v51
	v_mul_f32_e32 v39, 0xbfb8aa3b, v39
	v_rcp_f32_e32 v43, v43
	v_mul_f32_e32 v34, v34, v50
	v_mul_f32_e32 v34, 0xbfb8aa3b, v34
	v_mul_f32_e32 v38, v38, v50
	v_rcp_f32_e32 v42, v42
	s_nop 0
	v_pk_fma_f32 v[42:43], v[42:43], s[10:11], 0.5 op_sel_hi:[1,0,0]
	v_mul_f32_e32 v38, 0xbfb8aa3b, v38
	v_cvt_i32_f32_e32 v44, v43
	v_cvt_i32_f32_e32 v45, v42
	v_pk_add_f32 v[42:43], v[56:57], 1.0 op_sel_hi:[1,0]
	v_exp_f32_e32 v38, v38
	v_rcp_f32_e32 v43, v43
	v_rcp_f32_e32 v42, v42
	s_nop 0
	v_pk_fma_f32 v[42:43], v[42:43], s[10:11], 0.5 op_sel_hi:[1,0,0]
	s_nop 0
	v_cvt_i32_f32_e32 v42, v42
	v_cvt_i32_f32_e32 v43, v43
	v_lshlrev_b32_e32 v42, 8, v42
	v_lshlrev_b32_e32 v43, 8, v43
	v_or_b32_e32 v44, v43, v44
	v_or_b32_e32 v45, v42, v45
	v_pk_add_f32 v[42:43], v[48:49], 1.0 op_sel_hi:[1,0]
	s_nop 0
	v_rcp_f32_e32 v43, v43
	v_rcp_f32_e32 v42, v42
	s_nop 0
	v_pk_fma_f32 v[42:43], v[42:43], s[10:11], 0.5 op_sel_hi:[1,0,0]
	s_nop 0
	v_cvt_i32_f32_sdwa v42, v42 dst_sel:WORD_1 dst_unused:UNUSED_PAD src0_sel:DWORD
	v_cvt_i32_f32_sdwa v43, v43 dst_sel:WORD_1 dst_unused:UNUSED_PAD src0_sel:DWORD
	v_or_b32_e32 v45, v45, v42
	v_or_b32_e32 v44, v44, v43
	v_pk_add_f32 v[42:43], v[46:47], 1.0 op_sel_hi:[1,0]
	s_nop 0
	v_rcp_f32_e32 v43, v43
	v_rcp_f32_e32 v42, v42
	s_nop 0
	v_pk_fma_f32 v[42:43], v[42:43], s[10:11], 0.5 op_sel_hi:[1,0,0]
	s_nop 0
	v_cvt_i32_f32_sdwa v43, v43 dst_sel:BYTE_3 dst_unused:UNUSED_PAD src0_sel:DWORD
	v_cvt_i32_f32_sdwa v42, v42 dst_sel:BYTE_3 dst_unused:UNUSED_PAD src0_sel:DWORD
	v_or_b32_e32 v43, v44, v43
	v_exp_f32_e32 v44, v39
	v_mul_f32_e32 v39, v40, v52
	v_mul_f32_e32 v39, 0xbfb8aa3b, v39
	v_exp_f32_e32 v40, v39
	v_mul_f32_e32 v39, v41, v53
	v_mul_f32_e32 v39, 0xbfb8aa3b, v39
	v_exp_f32_e32 v46, v39
	v_exp_f32_e32 v39, v34
	v_mul_f32_e32 v34, v35, v51
	v_mul_f32_e32 v34, 0xbfb8aa3b, v34
	v_or_b32_e32 v42, v45, v42
	v_exp_f32_e32 v45, v34
	v_mul_f32_e32 v34, v36, v52
	v_mul_f32_e32 v34, 0xbfb8aa3b, v34
	v_exp_f32_e32 v41, v34
	v_mul_f32_e32 v34, v37, v53
	v_mul_f32_e32 v34, 0xbfb8aa3b, v34
	v_exp_f32_e32 v47, v34
	v_pk_add_f32 v[34:35], v[38:39], 1.0 op_sel_hi:[1,0]
	s_nop 0
	v_rcp_f32_e32 v35, v35
	v_rcp_f32_e32 v34, v34
	s_nop 0
	v_pk_fma_f32 v[34:35], v[34:35], s[10:11], 0.5 op_sel_hi:[1,0,0]
	s_nop 0
	v_cvt_i32_f32_e32 v36, v35
	v_cvt_i32_f32_e32 v37, v34
	v_pk_add_f32 v[34:35], v[44:45], 1.0 op_sel_hi:[1,0]
	s_nop 0
	v_rcp_f32_e32 v35, v35
	v_rcp_f32_e32 v34, v34
	s_nop 0
	v_pk_fma_f32 v[34:35], v[34:35], s[10:11], 0.5 op_sel_hi:[1,0,0]
	s_nop 0
	v_cvt_i32_f32_e32 v34, v34
	v_cvt_i32_f32_e32 v35, v35
	v_lshlrev_b32_e32 v34, 8, v34
	v_lshlrev_b32_e32 v35, 8, v35
	v_or_b32_e32 v36, v35, v36
	v_or_b32_e32 v37, v34, v37
	v_pk_add_f32 v[34:35], v[40:41], 1.0 op_sel_hi:[1,0]
	s_nop 0
	v_rcp_f32_e32 v35, v35
	v_rcp_f32_e32 v34, v34
	s_nop 0
	v_pk_fma_f32 v[34:35], v[34:35], s[10:11], 0.5 op_sel_hi:[1,0,0]
	s_nop 0
	v_cvt_i32_f32_sdwa v34, v34 dst_sel:WORD_1 dst_unused:UNUSED_PAD src0_sel:DWORD
	v_cvt_i32_f32_sdwa v35, v35 dst_sel:WORD_1 dst_unused:UNUSED_PAD src0_sel:DWORD
	v_or_b32_e32 v37, v37, v34
	v_or_b32_e32 v36, v36, v35
	v_pk_add_f32 v[34:35], v[46:47], 1.0 op_sel_hi:[1,0]
	s_nop 0
	v_rcp_f32_e32 v35, v35
	v_rcp_f32_e32 v34, v34
	s_nop 0
	v_pk_fma_f32 v[34:35], v[34:35], s[10:11], 0.5 op_sel_hi:[1,0,0]
	s_nop 0
	v_cvt_i32_f32_sdwa v34, v34 dst_sel:BYTE_3 dst_unused:UNUSED_PAD src0_sel:DWORD
	v_cvt_i32_f32_sdwa v35, v35 dst_sel:BYTE_3 dst_unused:UNUSED_PAD src0_sel:DWORD
	v_or_b32_e32 v44, v37, v34
	v_or_b32_e32 v45, v36, v35
	ds_read_b128 v[34:37], v66 offset:128
	global_store_dwordx4 v0, v[42:45], s[0:1] offset:16
	s_waitcnt lgkmcnt(0)
; DI float sigmoidf_(float v) { return 1.f / (1.f + __expf(-v)); }
; DI void phaseA_tile(const P& p, int layer, int mt, int nt, char* lds) {
;     ...
;     for (int mi = 0; mi < 4; ++mi) {
;       unsigned wv[4];
; #pragma unroll
;       for (int ni = 0; ni < 4; ++ni) {
;         unsigned w_ = 0u;
; #pragma unroll
;         for (int j = 0; j < 4; ++j) {
;           const float r = rr[wm * 64 + mi * 16 + fq * 4 + j];
;           w_ |= ((unsigned)(int)(sigmoidf_(acc[mi][ni][j] * r) * 255.f + 0.5f)) << (8 * j);
;         }
;         wv[ni] = w_;
;       }
;       *(u32x4*)(G + mi * 4) = u32x4{wv[0], wv[1], wv[2], wv[3]};
;     }
	v_mul_f32_e32 v31, v31, v35
	v_mul_f32_e32 v31, 0xbfb8aa3b, v31
	v_exp_f32_e32 v38, v31
	v_mul_f32_e32 v31, v32, v36
	v_mul_f32_e32 v31, 0xbfb8aa3b, v31
	v_exp_f32_e32 v32, v31
	v_mul_f32_e32 v31, v33, v37
	v_mul_f32_e32 v26, v26, v34
	v_mul_f32_e32 v31, 0xbfb8aa3b, v31
	v_mul_f32_e32 v26, 0xbfb8aa3b, v26
	v_mul_f32_e32 v30, v30, v34
	v_exp_f32_e32 v40, v31
	v_exp_f32_e32 v31, v26
	v_mul_f32_e32 v26, v27, v35
	v_mul_f32_e32 v30, 0xbfb8aa3b, v30
	v_mul_f32_e32 v26, 0xbfb8aa3b, v26
	v_exp_f32_e32 v30, v30
	v_exp_f32_e32 v39, v26
	v_mul_f32_e32 v26, v28, v36
	v_mul_f32_e32 v26, 0xbfb8aa3b, v26
	v_exp_f32_e32 v33, v26
	v_mul_f32_e32 v26, v29, v37
	v_mul_f32_e32 v26, 0xbfb8aa3b, v26
	v_exp_f32_e32 v41, v26
	v_pk_add_f32 v[26:27], v[30:31], 1.0 op_sel_hi:[1,0]
	v_mul_f32_e32 v23, v23, v35
	v_mul_f32_e32 v23, 0xbfb8aa3b, v23
	v_mul_f32_e32 v18, v18, v34
	v_mul_f32_e32 v18, 0xbfb8aa3b, v18
	v_rcp_f32_e32 v27, v27
	v_mul_f32_e32 v22, v22, v34
	v_mul_f32_e32 v22, 0xbfb8aa3b, v22
	v_exp_f32_e32 v22, v22
	v_rcp_f32_e32 v26, v26
	s_nop 0
	v_pk_fma_f32 v[26:27], v[26:27], s[10:11], 0.5 op_sel_hi:[1,0,0]
	s_nop 0
	v_cvt_i32_f32_e32 v28, v27
	v_cvt_i32_f32_e32 v29, v26
	v_pk_add_f32 v[26:27], v[38:39], 1.0 op_sel_hi:[1,0]
	s_nop 0
	v_rcp_f32_e32 v27, v27
	v_rcp_f32_e32 v26, v26
	s_nop 0
	v_pk_fma_f32 v[26:27], v[26:27], s[10:11], 0.5 op_sel_hi:[1,0,0]
	s_nop 0
	v_cvt_i32_f32_e32 v26, v26
	v_cvt_i32_f32_e32 v27, v27
	v_lshlrev_b32_e32 v26, 8, v26
	v_lshlrev_b32_e32 v27, 8, v27
	v_or_b32_e32 v28, v27, v28
	v_or_b32_e32 v29, v26, v29
	v_pk_add_f32 v[26:27], v[32:33], 1.0 op_sel_hi:[1,0]
	s_nop 0
	v_rcp_f32_e32 v27, v27
	v_rcp_f32_e32 v26, v26
	s_nop 0
	v_pk_fma_f32 v[26:27], v[26:27], s[10:11], 0.5 op_sel_hi:[1,0,0]
	s_nop 0
	v_cvt_i32_f32_sdwa v26, v26 dst_sel:WORD_1 dst_unused:UNUSED_PAD src0_sel:DWORD
	v_cvt_i32_f32_sdwa v27, v27 dst_sel:WORD_1 dst_unused:UNUSED_PAD src0_sel:DWORD
	v_or_b32_e32 v29, v29, v26
	v_or_b32_e32 v28, v28, v27
	v_pk_add_f32 v[26:27], v[40:41], 1.0 op_sel_hi:[1,0]
	s_nop 0
	v_rcp_f32_e32 v27, v27
	v_rcp_f32_e32 v26, v26
	s_nop 0
	v_pk_fma_f32 v[26:27], v[26:27], s[10:11], 0.5 op_sel_hi:[1,0,0]
	s_nop 0
	v_cvt_i32_f32_sdwa v27, v27 dst_sel:BYTE_3 dst_unused:UNUSED_PAD src0_sel:DWORD
	v_cvt_i32_f32_sdwa v26, v26 dst_sel:BYTE_3 dst_unused:UNUSED_PAD src0_sel:DWORD
	v_or_b32_e32 v27, v28, v27
	v_exp_f32_e32 v28, v23
	v_mul_f32_e32 v23, v24, v36
	v_mul_f32_e32 v23, 0xbfb8aa3b, v23
	v_exp_f32_e32 v24, v23
	v_mul_f32_e32 v23, v25, v37
	v_mul_f32_e32 v23, 0xbfb8aa3b, v23
	v_exp_f32_e32 v30, v23
	v_exp_f32_e32 v23, v18
	v_mul_f32_e32 v18, v19, v35
	v_mul_f32_e32 v18, 0xbfb8aa3b, v18
	v_or_b32_e32 v26, v29, v26
	v_exp_f32_e32 v29, v18
	v_mul_f32_e32 v18, v20, v36
	v_mul_f32_e32 v18, 0xbfb8aa3b, v18
	v_exp_f32_e32 v25, v18
	v_mul_f32_e32 v18, v21, v37
	v_mul_f32_e32 v18, 0xbfb8aa3b, v18
	v_exp_f32_e32 v31, v18
	v_pk_add_f32 v[18:19], v[22:23], 1.0 op_sel_hi:[1,0]
	s_nop 0
	v_rcp_f32_e32 v19, v19
	v_rcp_f32_e32 v18, v18
	s_nop 0
	v_pk_fma_f32 v[18:19], v[18:19], s[10:11], 0.5 op_sel_hi:[1,0,0]
	s_nop 0
	v_cvt_i32_f32_e32 v20, v19
	v_cvt_i32_f32_e32 v21, v18
	v_pk_add_f32 v[18:19], v[28:29], 1.0 op_sel_hi:[1,0]
	s_nop 0
	v_rcp_f32_e32 v19, v19
	v_rcp_f32_e32 v18, v18
	s_nop 0
	v_pk_fma_f32 v[18:19], v[18:19], s[10:11], 0.5 op_sel_hi:[1,0,0]
	s_nop 0
	v_cvt_i32_f32_e32 v18, v18
	v_cvt_i32_f32_e32 v19, v19
	v_lshlrev_b32_e32 v18, 8, v18
	v_lshlrev_b32_e32 v19, 8, v19
	v_or_b32_e32 v20, v19, v20
	v_or_b32_e32 v21, v18, v21
	v_pk_add_f32 v[18:19], v[24:25], 1.0 op_sel_hi:[1,0]
	s_nop 0
	v_rcp_f32_e32 v19, v19
	v_rcp_f32_e32 v18, v18
	s_nop 0
	v_pk_fma_f32 v[18:19], v[18:19], s[10:11], 0.5 op_sel_hi:[1,0,0]
	s_nop 0
	v_cvt_i32_f32_sdwa v18, v18 dst_sel:WORD_1 dst_unused:UNUSED_PAD src0_sel:DWORD
	v_cvt_i32_f32_sdwa v19, v19 dst_sel:WORD_1 dst_unused:UNUSED_PAD src0_sel:DWORD
	v_or_b32_e32 v21, v21, v18
	v_or_b32_e32 v20, v20, v19
	v_pk_add_f32 v[18:19], v[30:31], 1.0 op_sel_hi:[1,0]
	s_nop 0
	v_rcp_f32_e32 v19, v19
	v_rcp_f32_e32 v18, v18
	s_nop 0
	v_pk_fma_f32 v[18:19], v[18:19], s[10:11], 0.5 op_sel_hi:[1,0,0]
	s_nop 0
	v_cvt_i32_f32_sdwa v18, v18 dst_sel:BYTE_3 dst_unused:UNUSED_PAD src0_sel:DWORD
	v_cvt_i32_f32_sdwa v19, v19 dst_sel:BYTE_3 dst_unused:UNUSED_PAD src0_sel:DWORD
	v_or_b32_e32 v28, v21, v18
	v_or_b32_e32 v29, v20, v19
	ds_read_b128 v[18:21], v66 offset:192
	global_store_dwordx4 v0, v[26:29], s[0:1] offset:32
	s_waitcnt lgkmcnt(0)
; DI float sigmoidf_(float v) { return 1.f / (1.f + __expf(-v)); }
; DI void phaseA_tile(const P& p, int layer, int mt, int nt, char* lds) {
;     ...
;     for (int mi = 0; mi < 4; ++mi) {
;       unsigned wv[4];
; #pragma unroll
;       for (int ni = 0; ni < 4; ++ni) {
;         unsigned w_ = 0u;
; #pragma unroll
;         for (int j = 0; j < 4; ++j) {
;           const float r = rr[wm * 64 + mi * 16 + fq * 4 + j];
;           w_ |= ((unsigned)(int)(sigmoidf_(acc[mi][ni][j] * r) * 255.f + 0.5f)) << (8 * j);
;         }
;         wv[ni] = w_;
;       }
;       *(u32x4*)(G + mi * 4) = u32x4{wv[0], wv[1], wv[2], wv[3]};
;     }
	v_mul_f32_e32 v14, v14, v18
	v_mul_f32_e32 v10, v10, v18
	v_mul_f32_e32 v14, 0xbfb8aa3b, v14
	v_mul_f32_e32 v10, 0xbfb8aa3b, v10
	v_exp_f32_e32 v22, v14
	v_mul_f32_e32 v14, v15, v19
	v_exp_f32_e32 v23, v10
	v_mul_f32_e32 v10, v11, v19
	v_mul_f32_e32 v14, 0xbfb8aa3b, v14
	v_mul_f32_e32 v10, 0xbfb8aa3b, v10
	v_exp_f32_e32 v24, v14
	v_mul_f32_e32 v14, v16, v20
	v_exp_f32_e32 v25, v10
	v_mul_f32_e32 v10, v12, v20
	v_mul_f32_e32 v14, 0xbfb8aa3b, v14
	v_mul_f32_e32 v10, 0xbfb8aa3b, v10
	v_exp_f32_e32 v16, v14
	v_mul_f32_e32 v14, v17, v21
	v_exp_f32_e32 v17, v10
	v_mul_f32_e32 v10, v13, v21
	v_mul_f32_e32 v10, 0xbfb8aa3b, v10
	v_exp_f32_e32 v15, v10
	v_pk_add_f32 v[10:11], v[22:23], 1.0 op_sel_hi:[1,0]
	v_mul_f32_e32 v14, 0xbfb8aa3b, v14
	v_exp_f32_e32 v14, v14
	v_mul_f32_e32 v6, v6, v18
	v_mul_f32_e32 v2, v2, v18
	v_rcp_f32_e32 v11, v11
	v_mul_f32_e32 v6, 0xbfb8aa3b, v6
	v_mul_f32_e32 v2, 0xbfb8aa3b, v2
	v_rcp_f32_e32 v10, v10
	s_nop 0
	v_pk_fma_f32 v[10:11], v[10:11], s[10:11], 0.5 op_sel_hi:[1,0,0]
	s_nop 0
	v_cvt_i32_f32_e32 v12, v11
	v_cvt_i32_f32_e32 v13, v10
	v_pk_add_f32 v[10:11], v[24:25], 1.0 op_sel_hi:[1,0]
	s_nop 0
	v_rcp_f32_e32 v11, v11
	v_rcp_f32_e32 v10, v10
	s_nop 0
	v_pk_fma_f32 v[10:11], v[10:11], s[10:11], 0.5 op_sel_hi:[1,0,0]
	s_nop 0
	v_cvt_i32_f32_e32 v10, v10
	v_cvt_i32_f32_e32 v11, v11
	v_lshlrev_b32_e32 v10, 8, v10
	v_lshlrev_b32_e32 v11, 8, v11
	v_or_b32_e32 v12, v11, v12
	v_or_b32_e32 v13, v10, v13
	v_pk_add_f32 v[10:11], v[16:17], 1.0 op_sel_hi:[1,0]
	s_nop 0
	v_rcp_f32_e32 v11, v11
	v_rcp_f32_e32 v10, v10
	s_nop 0
	v_pk_fma_f32 v[10:11], v[10:11], s[10:11], 0.5 op_sel_hi:[1,0,0]
	s_nop 0
	v_cvt_i32_f32_sdwa v10, v10 dst_sel:WORD_1 dst_unused:UNUSED_PAD src0_sel:DWORD
	v_cvt_i32_f32_sdwa v11, v11 dst_sel:WORD_1 dst_unused:UNUSED_PAD src0_sel:DWORD
	v_or_b32_e32 v13, v13, v10
	v_or_b32_e32 v12, v12, v11
	v_pk_add_f32 v[10:11], v[14:15], 1.0 op_sel_hi:[1,0]
	s_nop 0
	v_rcp_f32_e32 v11, v11
	v_rcp_f32_e32 v10, v10
	s_nop 0
	v_pk_fma_f32 v[10:11], v[10:11], s[10:11], 0.5 op_sel_hi:[1,0,0]
	s_nop 0
	v_cvt_i32_f32_sdwa v10, v10 dst_sel:BYTE_3 dst_unused:UNUSED_PAD src0_sel:DWORD
	v_cvt_i32_f32_sdwa v11, v11 dst_sel:BYTE_3 dst_unused:UNUSED_PAD src0_sel:DWORD
	v_or_b32_e32 v10, v13, v10
	v_or_b32_e32 v11, v12, v11
	v_exp_f32_e32 v12, v6
	v_mul_f32_e32 v6, v7, v19
	v_exp_f32_e32 v13, v2
	v_mul_f32_e32 v2, v3, v19
	v_mul_f32_e32 v6, 0xbfb8aa3b, v6
	v_mul_f32_e32 v2, 0xbfb8aa3b, v2
	v_exp_f32_e32 v14, v6
	v_mul_f32_e32 v6, v8, v20
	v_exp_f32_e32 v15, v2
	v_mul_f32_e32 v2, v4, v20
	v_mul_f32_e32 v6, 0xbfb8aa3b, v6
	v_mul_f32_e32 v2, 0xbfb8aa3b, v2
	v_exp_f32_e32 v8, v6
	v_mul_f32_e32 v6, v9, v21
	v_exp_f32_e32 v9, v2
	v_mul_f32_e32 v2, v5, v21
	v_mul_f32_e32 v2, 0xbfb8aa3b, v2
	v_exp_f32_e32 v7, v2
	v_pk_add_f32 v[2:3], v[12:13], 1.0 op_sel_hi:[1,0]
	v_mul_f32_e32 v6, 0xbfb8aa3b, v6
	v_exp_f32_e32 v6, v6
	v_rcp_f32_e32 v3, v3
	v_rcp_f32_e32 v2, v2
	s_nop 0
	v_pk_fma_f32 v[2:3], v[2:3], s[10:11], 0.5 op_sel_hi:[1,0,0]
	s_nop 0
	v_cvt_i32_f32_e32 v4, v3
	v_cvt_i32_f32_e32 v5, v2
	v_pk_add_f32 v[2:3], v[14:15], 1.0 op_sel_hi:[1,0]
	s_nop 0
	v_rcp_f32_e32 v3, v3
	v_rcp_f32_e32 v2, v2
	s_nop 0
	v_pk_fma_f32 v[2:3], v[2:3], s[10:11], 0.5 op_sel_hi:[1,0,0]
	s_nop 0
	v_cvt_i32_f32_e32 v2, v2
	v_cvt_i32_f32_e32 v3, v3
	v_lshlrev_b32_e32 v2, 8, v2
	v_lshlrev_b32_e32 v3, 8, v3
	v_or_b32_e32 v4, v3, v4
	v_or_b32_e32 v5, v2, v5
	v_pk_add_f32 v[2:3], v[8:9], 1.0 op_sel_hi:[1,0]
	s_nop 0
	v_rcp_f32_e32 v3, v3
	v_rcp_f32_e32 v2, v2
	s_nop 0
	v_pk_fma_f32 v[2:3], v[2:3], s[10:11], 0.5 op_sel_hi:[1,0,0]
	s_nop 0
	v_cvt_i32_f32_sdwa v2, v2 dst_sel:WORD_1 dst_unused:UNUSED_PAD src0_sel:DWORD
	v_cvt_i32_f32_sdwa v3, v3 dst_sel:WORD_1 dst_unused:UNUSED_PAD src0_sel:DWORD
	v_or_b32_e32 v5, v5, v2
	v_or_b32_e32 v4, v4, v3
	v_pk_add_f32 v[2:3], v[6:7], 1.0 op_sel_hi:[1,0]
	s_nop 0
	v_rcp_f32_e32 v3, v3
	s_movk_i32 s5, 0x2000
	v_rcp_f32_e32 v2, v2
	s_nop 0
	v_pk_fma_f32 v[2:3], v[2:3], s[10:11], 0.5 op_sel_hi:[1,0,0]
	s_nop 0
	v_cvt_i32_f32_sdwa v2, v2 dst_sel:BYTE_3 dst_unused:UNUSED_PAD src0_sel:DWORD
	v_cvt_i32_f32_sdwa v3, v3 dst_sel:BYTE_3 dst_unused:UNUSED_PAD src0_sel:DWORD
	v_or_b32_e32 v12, v5, v2
	v_or_b32_e32 v13, v4, v3
	global_store_dwordx4 v0, v[10:13], s[0:1] offset:48
	s_branch .LBB0_1183

; DI unsigned pk2(float lo, float hi) { unsigned r; asm("v_cvt_pk_bf16_f32 %0, %1, %2" : "=v"(r) : "v"(lo), "v"(hi)); return r; }
; DI float siluf_(float v) { return v / (1.f + __expf(-v)); }
; DI void phaseA_tile(const P& p, int layer, int mt, int nt, char* lds) {
;     ...
;     } else if (seg < 16 || (seg >= 45 && seg < 53)) {
;       bf16_t* Z = (bf16_t*)(p.ws + (seg < 16 ? W_ZP : W_ZA)) + (size_t)row * 512 + (seg < 16 ? seg - 8 : seg - 45) * 64 + cc * 4;
;       *(u32x2*)Z = u32x2{pk2(siluf_(v.x), siluf_(v.y)), pk2(siluf_(v.z), siluf_(v.w))};
.LBB0_1677:
	s_and_b64 vcc, exec, s[12:13]
	s_cbranch_vccz .LBB0_1679
	v_mul_f32_e32 v0, 0xbfb8aa3b, v66
	v_exp_f32_e32 v0, v0
	v_ashrrev_i32_e32 v85, 31, v84
	v_lshlrev_b64 v[86:87], 10, v[84:85]
	v_lshl_add_u64 v[86:87], v[80:81], 0, v[86:87]
	v_add_f32_e32 v0, 1.0, v0
	v_rcp_f32_e32 v85, v0
	s_nop 0
	v_mul_f32_e32 v0, v66, v85
	v_mul_f32_e32 v85, 0xbfb8aa3b, v67
	v_exp_f32_e32 v85, v85
	s_nop 0
	v_add_f32_e32 v85, 1.0, v85
	v_rcp_f32_e32 v98, v85
	s_nop 0
	v_mul_f32_e32 v85, v67, v98
	v_cvt_pk_bf16_f32 v98, v0, v85
	v_mul_f32_e32 v0, 0xbfb8aa3b, v68
	v_exp_f32_e32 v0, v0
	s_nop 0
	v_add_f32_e32 v0, 1.0, v0
	v_rcp_f32_e32 v85, v0
	s_nop 0
	v_mul_f32_e32 v0, v68, v85
	v_mul_f32_e32 v85, 0xbfb8aa3b, v69
	v_exp_f32_e32 v85, v85
	s_nop 0
	v_add_f32_e32 v85, 1.0, v85
	v_rcp_f32_e32 v99, v85
	s_nop 0
	v_mul_f32_e32 v85, v69, v99
	v_cvt_pk_bf16_f32 v99, v0, v85
	global_store_dwordx2 v[86:87], v[98:99], off

; DI unsigned pk2(float lo, float hi) { unsigned r; asm("v_cvt_pk_bf16_f32 %0, %1, %2" : "=v"(r) : "v"(lo), "v"(hi)); return r; }
; DI float siluf_(float v) { return v / (1.f + __expf(-v)); }
; DI void phaseA_tile(const P& p, int layer, int mt, int nt, char* lds) {
;     ...
;     } else if (seg < 16 || (seg >= 45 && seg < 53)) {
;       bf16_t* Z = (bf16_t*)(p.ws + (seg < 16 ? W_ZP : W_ZA)) + (size_t)row * 512 + (seg < 16 ? seg - 8 : seg - 45) * 64 + cc * 4;
;       *(u32x2*)Z = u32x2{pk2(siluf_(v.x), siluf_(v.y)), pk2(siluf_(v.z), siluf_(v.w))};
.LBB0_1697:
	s_and_b64 vcc, exec, s[12:13]
	s_cbranch_vccz .LBB0_1699
	v_mul_f32_e32 v0, 0xbfb8aa3b, v66
	v_exp_f32_e32 v0, v0
	v_ashrrev_i32_e32 v87, 31, v86
	v_lshlrev_b64 v[84:85], 10, v[86:87]
	v_lshl_add_u64 v[84:85], v[80:81], 0, v[84:85]
	v_add_f32_e32 v0, 1.0, v0
	v_rcp_f32_e32 v87, v0
	s_nop 0
	v_mul_f32_e32 v0, v66, v87
	v_mul_f32_e32 v87, 0xbfb8aa3b, v67
	v_exp_f32_e32 v87, v87
	s_nop 0
	v_add_f32_e32 v87, 1.0, v87
	v_rcp_f32_e32 v97, v87
	s_nop 0
	v_mul_f32_e32 v87, v67, v97
	v_cvt_pk_bf16_f32 v98, v0, v87
	v_mul_f32_e32 v0, 0xbfb8aa3b, v68
	v_exp_f32_e32 v0, v0
	s_nop 0
	v_add_f32_e32 v0, 1.0, v0
	v_rcp_f32_e32 v87, v0
	s_nop 0
	v_mul_f32_e32 v0, v68, v87
	v_mul_f32_e32 v87, 0xbfb8aa3b, v69
	v_exp_f32_e32 v87, v87
	s_nop 0
	v_add_f32_e32 v87, 1.0, v87
	v_rcp_f32_e32 v97, v87
	s_nop 0
	v_mul_f32_e32 v87, v69, v97
	v_cvt_pk_bf16_f32 v99, v0, v87
	global_store_dwordx2 v[84:85], v[98:99], off

; DI float sigmoidf_(float v) { return 1.f / (1.f + __expf(-v)); }
; DI void phaseA_tile(const P& p, int layer, int mt, int nt, char* lds) {
;     ...
;   if (seg >= 53) {
;     const bool isP = seg < 69;
;     unsigned* G = (unsigned*)(p.ws + (isP ? W_GP : W_GA)) + ((size_t)(((row0 >> 6) + wm) * 16 + (isP ? seg - 53 : seg - 69)) * 64 + lane) * 16;
; #pragma unroll
;     for (int mi = 0; mi < 4; ++mi) {
;       unsigned wv[4];
; #pragma unroll
;       for (int ni = 0; ni < 4; ++ni) {
;         unsigned w_ = 0u;
; #pragma unroll
;         for (int j = 0; j < 4; ++j) {
;           const float r = rr[wm * 64 + mi * 16 + fq * 4 + j];
;           w_ |= ((unsigned)(int)(sigmoidf_(acc[mi][ni][j] * r) * 255.f + 0.5f)) << (8 * j);
;         }
;         wv[ni] = w_;
;       }
;       *(u32x4*)(G + mi * 4) = u32x4{wv[0], wv[1], wv[2], wv[3]};
;     }
.LBB0_1985:
	s_and_b64 vcc, exec, s[0:1]
	s_cbranch_vccz .LBB0_1588
	v_lshlrev_b32_e32 v66, 2, v127
	v_lshl_add_u32 v66, s7, 2, v66
	v_add_u32_e32 v66, 0x10800, v66
	ds_read_b128 v[68:71], v66
	s_cmpk_lt_u32 s29, 0x45
	s_cselect_b64 s[0:1], -1, 0
	s_and_b64 s[4:5], s[0:1], exec
	s_mov_b32 s4, 0x17ca2000
	s_waitcnt lgkmcnt(0)
	v_mul_f32_e32 v63, v63, v69
	v_mul_f32_e32 v63, 0xbfb8aa3b, v63
	s_cselect_b32 s4, s4, 0x19d22000
	v_exp_f32_e32 v72, v63
	v_mul_f32_e32 v63, v64, v70
	s_add_u32 s4, s90, s4
	v_mul_f32_e32 v63, 0xbfb8aa3b, v63
	s_addc_u32 s5, s91, 0
	s_lshl_b32 s6, s36, 5
	s_lshl_b32 s8, s48, 4
	v_exp_f32_e32 v64, v63
	v_mul_f32_e32 v63, v65, v71
	v_mul_f32_e32 v58, v58, v68
	s_and_b64 s[0:1], s[0:1], exec
	v_mul_f32_e32 v63, 0xbfb8aa3b, v63
	v_mul_f32_e32 v58, 0xbfb8aa3b, v58
	s_movk_i32 s0, 0xffcb
	v_mul_f32_e32 v62, v62, v68
	v_exp_f32_e32 v74, v63
	v_exp_f32_e32 v63, v58
	v_mul_f32_e32 v58, v59, v69
	s_cselect_b32 s0, s0, 0xffffffbb
	s_add_i32 s1, s8, s6
	v_mul_f32_e32 v62, 0xbfb8aa3b, v62
	v_mul_f32_e32 v58, 0xbfb8aa3b, v58
	s_add_i32 s1, s1, s29
	v_exp_f32_e32 v62, v62
	v_exp_f32_e32 v73, v58
	v_mul_f32_e32 v58, v60, v70
	s_add_i32 s0, s1, s0
	v_mul_f32_e32 v58, 0xbfb8aa3b, v58
	s_ashr_i32 s1, s0, 31
	v_exp_f32_e32 v65, v58
	v_mul_f32_e32 v58, v61, v71
	s_lshl_b64 s[0:1], s[0:1], 12
	v_mul_f32_e32 v58, 0xbfb8aa3b, v58
	s_add_u32 s0, s4, s0
	v_exp_f32_e32 v75, v58
	v_pk_add_f32 v[58:59], v[62:63], 1.0 op_sel_hi:[1,0]
	s_addc_u32 s1, s5, s1
	s_mov_b32 s6, 0x437f0000
	v_mul_f32_e32 v55, v55, v69
	v_mul_f32_e32 v55, 0xbfb8aa3b, v55
	v_rcp_f32_e32 v59, v59
	v_mul_f32_e32 v50, v50, v68
	v_mul_f32_e32 v50, 0xbfb8aa3b, v50
	v_mul_f32_e32 v54, v54, v68
	v_rcp_f32_e32 v58, v58
	s_nop 0
	v_pk_fma_f32 v[58:59], v[58:59], s[6:7], 0.5 op_sel_hi:[1,0,0]
	v_mul_f32_e32 v54, 0xbfb8aa3b, v54
	v_cvt_i32_f32_e32 v60, v59
	v_cvt_i32_f32_e32 v61, v58
	v_pk_add_f32 v[58:59], v[72:73], 1.0 op_sel_hi:[1,0]
	v_exp_f32_e32 v54, v54
	v_lshlrev_b32_e32 v0, 6, v152
	v_rcp_f32_e32 v59, v59
	v_rcp_f32_e32 v58, v58
	s_nop 0
	v_pk_fma_f32 v[58:59], v[58:59], s[6:7], 0.5 op_sel_hi:[1,0,0]
	s_nop 0
	v_cvt_i32_f32_e32 v58, v58
	v_cvt_i32_f32_e32 v59, v59
	v_lshlrev_b32_e32 v58, 8, v58
	v_lshlrev_b32_e32 v59, 8, v59
	v_or_b32_e32 v60, v59, v60
	v_or_b32_e32 v61, v58, v61
	v_pk_add_f32 v[58:59], v[64:65], 1.0 op_sel_hi:[1,0]
	s_nop 0
	v_rcp_f32_e32 v59, v59
	v_rcp_f32_e32 v58, v58
	s_nop 0
	v_pk_fma_f32 v[58:59], v[58:59], s[6:7], 0.5 op_sel_hi:[1,0,0]
	s_nop 0
	v_cvt_i32_f32_sdwa v58, v58 dst_sel:WORD_1 dst_unused:UNUSED_PAD src0_sel:DWORD
	v_cvt_i32_f32_sdwa v59, v59 dst_sel:WORD_1 dst_unused:UNUSED_PAD src0_sel:DWORD
	v_or_b32_e32 v61, v61, v58
	v_or_b32_e32 v60, v60, v59
	v_pk_add_f32 v[58:59], v[74:75], 1.0 op_sel_hi:[1,0]
	s_nop 0
	v_rcp_f32_e32 v59, v59
	v_rcp_f32_e32 v58, v58
	s_nop 0
	v_pk_fma_f32 v[58:59], v[58:59], s[6:7], 0.5 op_sel_hi:[1,0,0]
	s_nop 0
	v_cvt_i32_f32_sdwa v59, v59 dst_sel:BYTE_3 dst_unused:UNUSED_PAD src0_sel:DWORD
	v_cvt_i32_f32_sdwa v58, v58 dst_sel:BYTE_3 dst_unused:UNUSED_PAD src0_sel:DWORD
	v_or_b32_e32 v59, v60, v59
	v_exp_f32_e32 v60, v55
	v_mul_f32_e32 v55, v56, v70
	v_mul_f32_e32 v55, 0xbfb8aa3b, v55
	v_exp_f32_e32 v56, v55
	v_mul_f32_e32 v55, v57, v71
	v_mul_f32_e32 v55, 0xbfb8aa3b, v55
	v_exp_f32_e32 v62, v55
	v_exp_f32_e32 v55, v50
	v_mul_f32_e32 v50, v51, v69
	v_mul_f32_e32 v50, 0xbfb8aa3b, v50
	v_or_b32_e32 v58, v61, v58
	v_exp_f32_e32 v61, v50
	v_mul_f32_e32 v50, v52, v70
	v_mul_f32_e32 v50, 0xbfb8aa3b, v50
	v_exp_f32_e32 v57, v50
	v_mul_f32_e32 v50, v53, v71
	v_mul_f32_e32 v50, 0xbfb8aa3b, v50
	v_exp_f32_e32 v63, v50
	v_pk_add_f32 v[50:51], v[54:55], 1.0 op_sel_hi:[1,0]
	s_nop 0
	v_rcp_f32_e32 v51, v51
	v_rcp_f32_e32 v50, v50
	s_nop 0
	v_pk_fma_f32 v[50:51], v[50:51], s[6:7], 0.5 op_sel_hi:[1,0,0]
	s_nop 0
	v_cvt_i32_f32_e32 v52, v51
	v_cvt_i32_f32_e32 v53, v50
	v_pk_add_f32 v[50:51], v[60:61], 1.0 op_sel_hi:[1,0]
	s_nop 0
	v_rcp_f32_e32 v51, v51
	v_rcp_f32_e32 v50, v50
	s_nop 0
	v_pk_fma_f32 v[50:51], v[50:51], s[6:7], 0.5 op_sel_hi:[1,0,0]
	s_nop 0
	v_cvt_i32_f32_e32 v50, v50
	v_cvt_i32_f32_e32 v51, v51
	v_lshlrev_b32_e32 v50, 8, v50
	v_lshlrev_b32_e32 v51, 8, v51
	v_or_b32_e32 v52, v51, v52
	v_or_b32_e32 v53, v50, v53
	v_pk_add_f32 v[50:51], v[56:57], 1.0 op_sel_hi:[1,0]
	s_nop 0
	v_rcp_f32_e32 v51, v51
	v_rcp_f32_e32 v50, v50
	s_nop 0
	v_pk_fma_f32 v[50:51], v[50:51], s[6:7], 0.5 op_sel_hi:[1,0,0]
	s_nop 0
	v_cvt_i32_f32_sdwa v50, v50 dst_sel:WORD_1 dst_unused:UNUSED_PAD src0_sel:DWORD
	v_cvt_i32_f32_sdwa v51, v51 dst_sel:WORD_1 dst_unused:UNUSED_PAD src0_sel:DWORD
	v_or_b32_e32 v53, v53, v50
	v_or_b32_e32 v52, v52, v51
	v_pk_add_f32 v[50:51], v[62:63], 1.0 op_sel_hi:[1,0]
	s_nop 0
	v_rcp_f32_e32 v51, v51
	v_rcp_f32_e32 v50, v50
	s_nop 0
	v_pk_fma_f32 v[50:51], v[50:51], s[6:7], 0.5 op_sel_hi:[1,0,0]
	s_nop 0
	v_cvt_i32_f32_sdwa v50, v50 dst_sel:BYTE_3 dst_unused:UNUSED_PAD src0_sel:DWORD
	v_cvt_i32_f32_sdwa v51, v51 dst_sel:BYTE_3 dst_unused:UNUSED_PAD src0_sel:DWORD
	v_or_b32_e32 v60, v53, v50
	v_or_b32_e32 v61, v52, v51
	ds_read_b128 v[50:53], v66 offset:64
	global_store_dwordx4 v0, v[58:61], s[0:1]
	s_waitcnt lgkmcnt(0)
; DI float sigmoidf_(float v) { return 1.f / (1.f + __expf(-v)); }
; DI void phaseA_tile(const P& p, int layer, int mt, int nt, char* lds) {
;     ...
;     for (int mi = 0; mi < 4; ++mi) {
;       unsigned wv[4];
; #pragma unroll
;       for (int ni = 0; ni < 4; ++ni) {
;         unsigned w_ = 0u;
; #pragma unroll
;         for (int j = 0; j < 4; ++j) {
;           const float r = rr[wm * 64 + mi * 16 + fq * 4 + j];
;           w_ |= ((unsigned)(int)(sigmoidf_(acc[mi][ni][j] * r) * 255.f + 0.5f)) << (8 * j);
;         }
;         wv[ni] = w_;
;       }
;       *(u32x4*)(G + mi * 4) = u32x4{wv[0], wv[1], wv[2], wv[3]};
;     }
	v_mul_f32_e32 v46, v46, v50
	v_mul_f32_e32 v42, v42, v50
	v_mul_f32_e32 v46, 0xbfb8aa3b, v46
	v_mul_f32_e32 v42, 0xbfb8aa3b, v42
	v_exp_f32_e32 v54, v46
	v_mul_f32_e32 v46, v47, v51
	v_exp_f32_e32 v55, v42
	v_mul_f32_e32 v42, v43, v51
	v_mul_f32_e32 v46, 0xbfb8aa3b, v46
	v_mul_f32_e32 v42, 0xbfb8aa3b, v42
	v_exp_f32_e32 v56, v46
	v_mul_f32_e32 v46, v48, v52
	v_exp_f32_e32 v57, v42
	v_mul_f32_e32 v42, v44, v52
	v_mul_f32_e32 v46, 0xbfb8aa3b, v46
	v_mul_f32_e32 v42, 0xbfb8aa3b, v42
	v_exp_f32_e32 v48, v46
	v_mul_f32_e32 v46, v49, v53
	v_exp_f32_e32 v49, v42
	v_mul_f32_e32 v42, v45, v53
	v_mul_f32_e32 v42, 0xbfb8aa3b, v42
	v_exp_f32_e32 v47, v42
	v_pk_add_f32 v[42:43], v[54:55], 1.0 op_sel_hi:[1,0]
	v_mul_f32_e32 v46, 0xbfb8aa3b, v46
	v_exp_f32_e32 v46, v46
	v_mul_f32_e32 v39, v39, v51
	v_mul_f32_e32 v39, 0xbfb8aa3b, v39
	v_rcp_f32_e32 v43, v43
	v_mul_f32_e32 v34, v34, v50
	v_mul_f32_e32 v34, 0xbfb8aa3b, v34
	v_mul_f32_e32 v38, v38, v50
	v_rcp_f32_e32 v42, v42
	s_nop 0
	v_pk_fma_f32 v[42:43], v[42:43], s[6:7], 0.5 op_sel_hi:[1,0,0]
	v_mul_f32_e32 v38, 0xbfb8aa3b, v38
	v_cvt_i32_f32_e32 v44, v43
	v_cvt_i32_f32_e32 v45, v42
	v_pk_add_f32 v[42:43], v[56:57], 1.0 op_sel_hi:[1,0]
	v_exp_f32_e32 v38, v38
	v_rcp_f32_e32 v43, v43
	v_rcp_f32_e32 v42, v42
	s_nop 0
	v_pk_fma_f32 v[42:43], v[42:43], s[6:7], 0.5 op_sel_hi:[1,0,0]
	s_nop 0
	v_cvt_i32_f32_e32 v42, v42
	v_cvt_i32_f32_e32 v43, v43
	v_lshlrev_b32_e32 v42, 8, v42
	v_lshlrev_b32_e32 v43, 8, v43
	v_or_b32_e32 v44, v43, v44
	v_or_b32_e32 v45, v42, v45
	v_pk_add_f32 v[42:43], v[48:49], 1.0 op_sel_hi:[1,0]
	s_nop 0
	v_rcp_f32_e32 v43, v43
	v_rcp_f32_e32 v42, v42
	s_nop 0
	v_pk_fma_f32 v[42:43], v[42:43], s[6:7], 0.5 op_sel_hi:[1,0,0]
	s_nop 0
	v_cvt_i32_f32_sdwa v42, v42 dst_sel:WORD_1 dst_unused:UNUSED_PAD src0_sel:DWORD
	v_cvt_i32_f32_sdwa v43, v43 dst_sel:WORD_1 dst_unused:UNUSED_PAD src0_sel:DWORD
	v_or_b32_e32 v45, v45, v42
	v_or_b32_e32 v44, v44, v43
	v_pk_add_f32 v[42:43], v[46:47], 1.0 op_sel_hi:[1,0]
	s_nop 0
	v_rcp_f32_e32 v43, v43
	v_rcp_f32_e32 v42, v42
	s_nop 0
	v_pk_fma_f32 v[42:43], v[42:43], s[6:7], 0.5 op_sel_hi:[1,0,0]
	s_nop 0
	v_cvt_i32_f32_sdwa v43, v43 dst_sel:BYTE_3 dst_unused:UNUSED_PAD src0_sel:DWORD
	v_cvt_i32_f32_sdwa v42, v42 dst_sel:BYTE_3 dst_unused:UNUSED_PAD src0_sel:DWORD
	v_or_b32_e32 v43, v44, v43
	v_exp_f32_e32 v44, v39
	v_mul_f32_e32 v39, v40, v52
	v_mul_f32_e32 v39, 0xbfb8aa3b, v39
	v_exp_f32_e32 v40, v39
	v_mul_f32_e32 v39, v41, v53
	v_mul_f32_e32 v39, 0xbfb8aa3b, v39
	v_exp_f32_e32 v46, v39
	v_exp_f32_e32 v39, v34
	v_mul_f32_e32 v34, v35, v51
	v_mul_f32_e32 v34, 0xbfb8aa3b, v34
	v_or_b32_e32 v42, v45, v42
	v_exp_f32_e32 v45, v34
	v_mul_f32_e32 v34, v36, v52
	v_mul_f32_e32 v34, 0xbfb8aa3b, v34
	v_exp_f32_e32 v41, v34
	v_mul_f32_e32 v34, v37, v53
	v_mul_f32_e32 v34, 0xbfb8aa3b, v34
	v_exp_f32_e32 v47, v34
	v_pk_add_f32 v[34:35], v[38:39], 1.0 op_sel_hi:[1,0]
	s_nop 0
	v_rcp_f32_e32 v35, v35
	v_rcp_f32_e32 v34, v34
	s_nop 0
	v_pk_fma_f32 v[34:35], v[34:35], s[6:7], 0.5 op_sel_hi:[1,0,0]
	s_nop 0
	v_cvt_i32_f32_e32 v36, v35
	v_cvt_i32_f32_e32 v37, v34
	v_pk_add_f32 v[34:35], v[44:45], 1.0 op_sel_hi:[1,0]
	s_nop 0
	v_rcp_f32_e32 v35, v35
	v_rcp_f32_e32 v34, v34
	s_nop 0
	v_pk_fma_f32 v[34:35], v[34:35], s[6:7], 0.5 op_sel_hi:[1,0,0]
	s_nop 0
	v_cvt_i32_f32_e32 v34, v34
	v_cvt_i32_f32_e32 v35, v35
	v_lshlrev_b32_e32 v34, 8, v34
	v_lshlrev_b32_e32 v35, 8, v35
	v_or_b32_e32 v36, v35, v36
	v_or_b32_e32 v37, v34, v37
	v_pk_add_f32 v[34:35], v[40:41], 1.0 op_sel_hi:[1,0]
	s_nop 0
	v_rcp_f32_e32 v35, v35
	v_rcp_f32_e32 v34, v34
	s_nop 0
	v_pk_fma_f32 v[34:35], v[34:35], s[6:7], 0.5 op_sel_hi:[1,0,0]
	s_nop 0
	v_cvt_i32_f32_sdwa v34, v34 dst_sel:WORD_1 dst_unused:UNUSED_PAD src0_sel:DWORD
	v_cvt_i32_f32_sdwa v35, v35 dst_sel:WORD_1 dst_unused:UNUSED_PAD src0_sel:DWORD
	v_or_b32_e32 v37, v37, v34
	v_or_b32_e32 v36, v36, v35
	v_pk_add_f32 v[34:35], v[46:47], 1.0 op_sel_hi:[1,0]
	s_nop 0
	v_rcp_f32_e32 v35, v35
	v_rcp_f32_e32 v34, v34
	s_nop 0
	v_pk_fma_f32 v[34:35], v[34:35], s[6:7], 0.5 op_sel_hi:[1,0,0]
	s_nop 0
	v_cvt_i32_f32_sdwa v34, v34 dst_sel:BYTE_3 dst_unused:UNUSED_PAD src0_sel:DWORD
	v_cvt_i32_f32_sdwa v35, v35 dst_sel:BYTE_3 dst_unused:UNUSED_PAD src0_sel:DWORD
	v_or_b32_e32 v44, v37, v34
	v_or_b32_e32 v45, v36, v35
	ds_read_b128 v[34:37], v66 offset:128
	global_store_dwordx4 v0, v[42:45], s[0:1] offset:16
	s_waitcnt lgkmcnt(0)
; DI float sigmoidf_(float v) { return 1.f / (1.f + __expf(-v)); }
; DI void phaseA_tile(const P& p, int layer, int mt, int nt, char* lds) {
;     ...
;     for (int mi = 0; mi < 4; ++mi) {
;       unsigned wv[4];
; #pragma unroll
;       for (int ni = 0; ni < 4; ++ni) {
;         unsigned w_ = 0u;
; #pragma unroll
;         for (int j = 0; j < 4; ++j) {
;           const float r = rr[wm * 64 + mi * 16 + fq * 4 + j];
;           w_ |= ((unsigned)(int)(sigmoidf_(acc[mi][ni][j] * r) * 255.f + 0.5f)) << (8 * j);
;         }
;         wv[ni] = w_;
;       }
;       *(u32x4*)(G + mi * 4) = u32x4{wv[0], wv[1], wv[2], wv[3]};
;     }
	v_mul_f32_e32 v31, v31, v35
	v_mul_f32_e32 v31, 0xbfb8aa3b, v31
	v_exp_f32_e32 v38, v31
	v_mul_f32_e32 v31, v32, v36
	v_mul_f32_e32 v31, 0xbfb8aa3b, v31
	v_exp_f32_e32 v32, v31
	v_mul_f32_e32 v31, v33, v37
	v_mul_f32_e32 v26, v26, v34
	v_mul_f32_e32 v31, 0xbfb8aa3b, v31
	v_mul_f32_e32 v26, 0xbfb8aa3b, v26
	v_mul_f32_e32 v30, v30, v34
	v_exp_f32_e32 v40, v31
	v_exp_f32_e32 v31, v26
	v_mul_f32_e32 v26, v27, v35
	v_mul_f32_e32 v30, 0xbfb8aa3b, v30
	v_mul_f32_e32 v26, 0xbfb8aa3b, v26
	v_exp_f32_e32 v30, v30
	v_exp_f32_e32 v39, v26
	v_mul_f32_e32 v26, v28, v36
	v_mul_f32_e32 v26, 0xbfb8aa3b, v26
	v_exp_f32_e32 v33, v26
	v_mul_f32_e32 v26, v29, v37
	v_mul_f32_e32 v26, 0xbfb8aa3b, v26
	v_exp_f32_e32 v41, v26
	v_pk_add_f32 v[26:27], v[30:31], 1.0 op_sel_hi:[1,0]
	v_mul_f32_e32 v23, v23, v35
	v_mul_f32_e32 v23, 0xbfb8aa3b, v23
	v_mul_f32_e32 v18, v18, v34
	v_mul_f32_e32 v18, 0xbfb8aa3b, v18
	v_rcp_f32_e32 v27, v27
	v_mul_f32_e32 v22, v22, v34
	v_mul_f32_e32 v22, 0xbfb8aa3b, v22
	v_exp_f32_e32 v22, v22
	v_rcp_f32_e32 v26, v26
	s_nop 0
	v_pk_fma_f32 v[26:27], v[26:27], s[6:7], 0.5 op_sel_hi:[1,0,0]
	s_nop 0
	v_cvt_i32_f32_e32 v28, v27
	v_cvt_i32_f32_e32 v29, v26
	v_pk_add_f32 v[26:27], v[38:39], 1.0 op_sel_hi:[1,0]
	s_nop 0
	v_rcp_f32_e32 v27, v27
	v_rcp_f32_e32 v26, v26
	s_nop 0
	v_pk_fma_f32 v[26:27], v[26:27], s[6:7], 0.5 op_sel_hi:[1,0,0]
	s_nop 0
	v_cvt_i32_f32_e32 v26, v26
	v_cvt_i32_f32_e32 v27, v27
	v_lshlrev_b32_e32 v26, 8, v26
	v_lshlrev_b32_e32 v27, 8, v27
	v_or_b32_e32 v28, v27, v28
	v_or_b32_e32 v29, v26, v29
	v_pk_add_f32 v[26:27], v[32:33], 1.0 op_sel_hi:[1,0]
	s_nop 0
	v_rcp_f32_e32 v27, v27
	v_rcp_f32_e32 v26, v26
	s_nop 0
	v_pk_fma_f32 v[26:27], v[26:27], s[6:7], 0.5 op_sel_hi:[1,0,0]
	s_nop 0
	v_cvt_i32_f32_sdwa v26, v26 dst_sel:WORD_1 dst_unused:UNUSED_PAD src0_sel:DWORD
	v_cvt_i32_f32_sdwa v27, v27 dst_sel:WORD_1 dst_unused:UNUSED_PAD src0_sel:DWORD
	v_or_b32_e32 v29, v29, v26
	v_or_b32_e32 v28, v28, v27
	v_pk_add_f32 v[26:27], v[40:41], 1.0 op_sel_hi:[1,0]
	s_nop 0
	v_rcp_f32_e32 v27, v27
	v_rcp_f32_e32 v26, v26
	s_nop 0
	v_pk_fma_f32 v[26:27], v[26:27], s[6:7], 0.5 op_sel_hi:[1,0,0]
	s_nop 0
	v_cvt_i32_f32_sdwa v27, v27 dst_sel:BYTE_3 dst_unused:UNUSED_PAD src0_sel:DWORD
	v_cvt_i32_f32_sdwa v26, v26 dst_sel:BYTE_3 dst_unused:UNUSED_PAD src0_sel:DWORD
	v_or_b32_e32 v27, v28, v27
	v_exp_f32_e32 v28, v23
	v_mul_f32_e32 v23, v24, v36
	v_mul_f32_e32 v23, 0xbfb8aa3b, v23
	v_exp_f32_e32 v24, v23
	v_mul_f32_e32 v23, v25, v37
	v_mul_f32_e32 v23, 0xbfb8aa3b, v23
	v_exp_f32_e32 v30, v23
	v_exp_f32_e32 v23, v18
	v_mul_f32_e32 v18, v19, v35
	v_mul_f32_e32 v18, 0xbfb8aa3b, v18
	v_or_b32_e32 v26, v29, v26
	v_exp_f32_e32 v29, v18
	v_mul_f32_e32 v18, v20, v36
	v_mul_f32_e32 v18, 0xbfb8aa3b, v18
	v_exp_f32_e32 v25, v18
	v_mul_f32_e32 v18, v21, v37
	v_mul_f32_e32 v18, 0xbfb8aa3b, v18
	v_exp_f32_e32 v31, v18
	v_pk_add_f32 v[18:19], v[22:23], 1.0 op_sel_hi:[1,0]
	s_nop 0
	v_rcp_f32_e32 v19, v19
	v_rcp_f32_e32 v18, v18
	s_nop 0
	v_pk_fma_f32 v[18:19], v[18:19], s[6:7], 0.5 op_sel_hi:[1,0,0]
	s_nop 0
	v_cvt_i32_f32_e32 v20, v19
	v_cvt_i32_f32_e32 v21, v18
	v_pk_add_f32 v[18:19], v[28:29], 1.0 op_sel_hi:[1,0]
	s_nop 0
	v_rcp_f32_e32 v19, v19
	v_rcp_f32_e32 v18, v18
	s_nop 0
	v_pk_fma_f32 v[18:19], v[18:19], s[6:7], 0.5 op_sel_hi:[1,0,0]
	s_nop 0
	v_cvt_i32_f32_e32 v18, v18
	v_cvt_i32_f32_e32 v19, v19
	v_lshlrev_b32_e32 v18, 8, v18
	v_lshlrev_b32_e32 v19, 8, v19
	v_or_b32_e32 v20, v19, v20
	v_or_b32_e32 v21, v18, v21
	v_pk_add_f32 v[18:19], v[24:25], 1.0 op_sel_hi:[1,0]
	s_nop 0
	v_rcp_f32_e32 v19, v19
	v_rcp_f32_e32 v18, v18
	s_nop 0
	v_pk_fma_f32 v[18:19], v[18:19], s[6:7], 0.5 op_sel_hi:[1,0,0]
	s_nop 0
	v_cvt_i32_f32_sdwa v18, v18 dst_sel:WORD_1 dst_unused:UNUSED_PAD src0_sel:DWORD
	v_cvt_i32_f32_sdwa v19, v19 dst_sel:WORD_1 dst_unused:UNUSED_PAD src0_sel:DWORD
	v_or_b32_e32 v21, v21, v18
	v_or_b32_e32 v20, v20, v19
	v_pk_add_f32 v[18:19], v[30:31], 1.0 op_sel_hi:[1,0]
	s_nop 0
	v_rcp_f32_e32 v19, v19
	v_rcp_f32_e32 v18, v18
	s_nop 0
	v_pk_fma_f32 v[18:19], v[18:19], s[6:7], 0.5 op_sel_hi:[1,0,0]
	s_nop 0
	v_cvt_i32_f32_sdwa v18, v18 dst_sel:BYTE_3 dst_unused:UNUSED_PAD src0_sel:DWORD
	v_cvt_i32_f32_sdwa v19, v19 dst_sel:BYTE_3 dst_unused:UNUSED_PAD src0_sel:DWORD
	v_or_b32_e32 v28, v21, v18
	v_or_b32_e32 v29, v20, v19
	ds_read_b128 v[18:21], v66 offset:192
	global_store_dwordx4 v0, v[26:29], s[0:1] offset:32
	s_waitcnt lgkmcnt(0)
; DI float sigmoidf_(float v) { return 1.f / (1.f + __expf(-v)); }
; DI void phaseA_tile(const P& p, int layer, int mt, int nt, char* lds) {
;     ...
;     for (int mi = 0; mi < 4; ++mi) {
;       unsigned wv[4];
; #pragma unroll
;       for (int ni = 0; ni < 4; ++ni) {
;         unsigned w_ = 0u;
; #pragma unroll
;         for (int j = 0; j < 4; ++j) {
;           const float r = rr[wm * 64 + mi * 16 + fq * 4 + j];
;           w_ |= ((unsigned)(int)(sigmoidf_(acc[mi][ni][j] * r) * 255.f + 0.5f)) << (8 * j);
;         }
;         wv[ni] = w_;
;       }
;       *(u32x4*)(G + mi * 4) = u32x4{wv[0], wv[1], wv[2], wv[3]};
;     }
	v_mul_f32_e32 v14, v14, v18
	v_mul_f32_e32 v10, v10, v18
	v_mul_f32_e32 v14, 0xbfb8aa3b, v14
	v_mul_f32_e32 v10, 0xbfb8aa3b, v10
	v_exp_f32_e32 v22, v14
	v_mul_f32_e32 v14, v15, v19
	v_exp_f32_e32 v23, v10
	v_mul_f32_e32 v10, v11, v19
	v_mul_f32_e32 v14, 0xbfb8aa3b, v14
	v_mul_f32_e32 v10, 0xbfb8aa3b, v10
	v_exp_f32_e32 v24, v14
	v_mul_f32_e32 v14, v16, v20
	v_exp_f32_e32 v25, v10
	v_mul_f32_e32 v10, v12, v20
	v_mul_f32_e32 v14, 0xbfb8aa3b, v14
	v_mul_f32_e32 v10, 0xbfb8aa3b, v10
	v_exp_f32_e32 v16, v14
	v_mul_f32_e32 v14, v17, v21
	v_exp_f32_e32 v17, v10
	v_mul_f32_e32 v10, v13, v21
	v_mul_f32_e32 v10, 0xbfb8aa3b, v10
	v_exp_f32_e32 v15, v10
	v_pk_add_f32 v[10:11], v[22:23], 1.0 op_sel_hi:[1,0]
	v_mul_f32_e32 v14, 0xbfb8aa3b, v14
	v_exp_f32_e32 v14, v14
	v_mul_f32_e32 v6, v6, v18
	v_mul_f32_e32 v2, v2, v18
	v_rcp_f32_e32 v11, v11
	v_mul_f32_e32 v6, 0xbfb8aa3b, v6
	v_mul_f32_e32 v2, 0xbfb8aa3b, v2
	v_rcp_f32_e32 v10, v10
	s_nop 0
	v_pk_fma_f32 v[10:11], v[10:11], s[6:7], 0.5 op_sel_hi:[1,0,0]
	s_nop 0
	v_cvt_i32_f32_e32 v12, v11
	v_cvt_i32_f32_e32 v13, v10
	v_pk_add_f32 v[10:11], v[24:25], 1.0 op_sel_hi:[1,0]
	s_nop 0
	v_rcp_f32_e32 v11, v11
	v_rcp_f32_e32 v10, v10
	s_nop 0
	v_pk_fma_f32 v[10:11], v[10:11], s[6:7], 0.5 op_sel_hi:[1,0,0]
	s_nop 0
	v_cvt_i32_f32_e32 v10, v10
	v_cvt_i32_f32_e32 v11, v11
	v_lshlrev_b32_e32 v10, 8, v10
	v_lshlrev_b32_e32 v11, 8, v11
	v_or_b32_e32 v12, v11, v12
	v_or_b32_e32 v13, v10, v13
	v_pk_add_f32 v[10:11], v[16:17], 1.0 op_sel_hi:[1,0]
	s_nop 0
	v_rcp_f32_e32 v11, v11
	v_rcp_f32_e32 v10, v10
	s_nop 0
	v_pk_fma_f32 v[10:11], v[10:11], s[6:7], 0.5 op_sel_hi:[1,0,0]
	s_nop 0
	v_cvt_i32_f32_sdwa v10, v10 dst_sel:WORD_1 dst_unused:UNUSED_PAD src0_sel:DWORD
	v_cvt_i32_f32_sdwa v11, v11 dst_sel:WORD_1 dst_unused:UNUSED_PAD src0_sel:DWORD
	v_or_b32_e32 v13, v13, v10
	v_or_b32_e32 v12, v12, v11
	v_pk_add_f32 v[10:11], v[14:15], 1.0 op_sel_hi:[1,0]
	s_nop 0
	v_rcp_f32_e32 v11, v11
	v_rcp_f32_e32 v10, v10
	s_nop 0
	v_pk_fma_f32 v[10:11], v[10:11], s[6:7], 0.5 op_sel_hi:[1,0,0]
	s_nop 0
	v_cvt_i32_f32_sdwa v10, v10 dst_sel:BYTE_3 dst_unused:UNUSED_PAD src0_sel:DWORD
	v_cvt_i32_f32_sdwa v11, v11 dst_sel:BYTE_3 dst_unused:UNUSED_PAD src0_sel:DWORD
	v_or_b32_e32 v10, v13, v10
	v_or_b32_e32 v11, v12, v11
	v_exp_f32_e32 v12, v6
	v_mul_f32_e32 v6, v7, v19
	v_exp_f32_e32 v13, v2
	v_mul_f32_e32 v2, v3, v19
	v_mul_f32_e32 v6, 0xbfb8aa3b, v6
	v_mul_f32_e32 v2, 0xbfb8aa3b, v2
	v_exp_f32_e32 v14, v6
	v_mul_f32_e32 v6, v8, v20
	v_exp_f32_e32 v15, v2
	v_mul_f32_e32 v2, v4, v20
	v_mul_f32_e32 v6, 0xbfb8aa3b, v6
	v_mul_f32_e32 v2, 0xbfb8aa3b, v2
	v_exp_f32_e32 v8, v6
	v_mul_f32_e32 v6, v9, v21
	v_exp_f32_e32 v9, v2
	v_mul_f32_e32 v2, v5, v21
	v_mul_f32_e32 v2, 0xbfb8aa3b, v2
	v_exp_f32_e32 v7, v2
	v_pk_add_f32 v[2:3], v[12:13], 1.0 op_sel_hi:[1,0]
	v_mul_f32_e32 v6, 0xbfb8aa3b, v6
	v_exp_f32_e32 v6, v6
	v_rcp_f32_e32 v3, v3
	v_rcp_f32_e32 v2, v2
	s_nop 0
	v_pk_fma_f32 v[2:3], v[2:3], s[6:7], 0.5 op_sel_hi:[1,0,0]
	s_nop 0
	v_cvt_i32_f32_e32 v4, v3
	v_cvt_i32_f32_e32 v5, v2
	v_pk_add_f32 v[2:3], v[14:15], 1.0 op_sel_hi:[1,0]
	s_nop 0
	v_rcp_f32_e32 v3, v3
	v_rcp_f32_e32 v2, v2
	s_nop 0
	v_pk_fma_f32 v[2:3], v[2:3], s[6:7], 0.5 op_sel_hi:[1,0,0]
	s_nop 0
	v_cvt_i32_f32_e32 v2, v2
	v_cvt_i32_f32_e32 v3, v3
	v_lshlrev_b32_e32 v2, 8, v2
	v_lshlrev_b32_e32 v3, 8, v3
	v_or_b32_e32 v4, v3, v4
	v_or_b32_e32 v5, v2, v5
	v_pk_add_f32 v[2:3], v[8:9], 1.0 op_sel_hi:[1,0]
	s_nop 0
	v_rcp_f32_e32 v3, v3
	v_rcp_f32_e32 v2, v2
	s_nop 0
	v_pk_fma_f32 v[2:3], v[2:3], s[6:7], 0.5 op_sel_hi:[1,0,0]
	s_nop 0
	v_cvt_i32_f32_sdwa v2, v2 dst_sel:WORD_1 dst_unused:UNUSED_PAD src0_sel:DWORD
	v_cvt_i32_f32_sdwa v3, v3 dst_sel:WORD_1 dst_unused:UNUSED_PAD src0_sel:DWORD
	v_or_b32_e32 v5, v5, v2
	v_or_b32_e32 v4, v4, v3
	v_pk_add_f32 v[2:3], v[6:7], 1.0 op_sel_hi:[1,0]
	s_nop 0
	v_rcp_f32_e32 v3, v3
	s_movk_i32 s5, 0x2000
	v_rcp_f32_e32 v2, v2
	s_nop 0
	v_pk_fma_f32 v[2:3], v[2:3], s[6:7], 0.5 op_sel_hi:[1,0,0]
	s_nop 0
	v_cvt_i32_f32_sdwa v2, v2 dst_sel:BYTE_3 dst_unused:UNUSED_PAD src0_sel:DWORD
	v_cvt_i32_f32_sdwa v3, v3 dst_sel:BYTE_3 dst_unused:UNUSED_PAD src0_sel:DWORD
	v_or_b32_e32 v12, v5, v2
	v_or_b32_e32 v13, v4, v3
	global_store_dwordx4 v0, v[10:13], s[0:1] offset:48
	s_branch .LBB0_1588
